# F top-k epilogue: LDS list XOR swizzle + topk stores transposed through LDS so 4 lanes write a token's contiguous 64B
# speedup vs baseline: 1.0270x; 1.0077x over previous
.LBB0_865:
	v_mov_b32_e32 v128, v176
	s_waitcnt vmcnt(0)
	s_barrier
	v_mov_b32_e32 v137, v176
	v_and_b32_e32 v130, 15, v128
	v_lshrrev_b32_e32 v131, 1, v128
	v_and_or_b32 v130, v131, s81, v130
	v_ashrrev_i32_e32 v131, 2, v128
	v_lshrrev_b32_e32 v128, 2, v128
	v_and_b32_e32 v128, 12, v128
	v_and_or_b32 v128, v131, s82, v128
	v_bfe_u32 v131, v60, 16, 1
	v_add3_u32 v60, v60, v131, s83
	v_bfe_u32 v131, v61, 16, 1
	v_lshrrev_b32_e32 v60, 16, v60
	v_add3_u32 v61, v61, v131, s83
	v_and_or_b32 v60, v61, s84, v60
	v_bfe_u32 v61, v62, 16, 1
	v_add3_u32 v61, v62, v61, s83
	v_bfe_u32 v62, v63, 16, 1
	v_add3_u32 v62, v63, v62, s83
	v_bfe_u32 v63, v56, 16, 1
	v_add3_u32 v56, v56, v63, s83
	v_bfe_u32 v63, v57, 16, 1
	v_lshrrev_b32_e32 v56, 16, v56
	v_add3_u32 v57, v57, v63, s83
	v_and_or_b32 v56, v57, s84, v56
	v_bfe_u32 v57, v58, 16, 1
	v_add3_u32 v57, v58, v57, s83
	v_bfe_u32 v58, v59, 16, 1
	v_lshrrev_b32_e32 v57, 16, v57
	v_add3_u32 v58, v59, v58, s83
	v_and_or_b32 v57, v58, s84, v57
	v_bfe_u32 v58, v52, 16, 1
	v_add3_u32 v52, v52, v58, s83
	v_bfe_u32 v58, v53, 16, 1
	v_lshrrev_b32_e32 v52, 16, v52
	v_add3_u32 v53, v53, v58, s83
	v_lshrrev_b32_e32 v61, 16, v61
	v_and_or_b32 v52, v53, s84, v52
	v_bfe_u32 v53, v54, 16, 1
	v_and_or_b32 v61, v62, s84, v61
	v_mul_u32_u24_e32 v62, 0x110, v130
	v_add3_u32 v53, v54, v53, s83
	v_bfe_u32 v54, v55, 16, 1
	v_lshl_add_u32 v62, v128, 1, v62
	v_lshrrev_b32_e32 v53, 16, v53
	v_add3_u32 v54, v55, v54, s83
	v_and_or_b32 v53, v54, s84, v53
	v_add_u32_e32 v54, 0x8000, v62
	ds_write2_b64 v54, v[60:61], v[52:53] offset1:4
	v_bfe_u32 v52, v48, 16, 1
	v_add3_u32 v48, v48, v52, s83
	v_bfe_u32 v52, v49, 16, 1
	v_lshrrev_b32_e32 v48, 16, v48
	v_add3_u32 v49, v49, v52, s83
	v_and_or_b32 v48, v49, s84, v48
	v_bfe_u32 v49, v50, 16, 1
	v_add3_u32 v49, v50, v49, s83
	v_bfe_u32 v50, v51, 16, 1
	v_lshrrev_b32_e32 v49, 16, v49
	v_add3_u32 v50, v51, v50, s83
	v_and_or_b32 v49, v50, s84, v49
	v_add_u32_e32 v50, 0x9000, v62
	ds_write2_b64 v50, v[56:57], v[48:49] offset0:32 offset1:36
	v_bfe_u32 v48, v44, 16, 1
	v_add3_u32 v44, v44, v48, s83
	v_bfe_u32 v48, v45, 16, 1
	v_lshrrev_b32_e32 v44, 16, v44
	v_add3_u32 v45, v45, v48, s83
	v_and_or_b32 v44, v45, s84, v44
	v_bfe_u32 v45, v46, 16, 1
	v_add3_u32 v45, v46, v45, s83
	v_bfe_u32 v46, v47, 16, 1
	v_lshrrev_b32_e32 v45, 16, v45
	v_add3_u32 v46, v47, v46, s83
	v_and_or_b32 v45, v46, s84, v45
	v_bfe_u32 v46, v36, 16, 1
	v_add3_u32 v36, v36, v46, s83
	v_bfe_u32 v46, v37, 16, 1
	v_lshrrev_b32_e32 v36, 16, v36
	v_add3_u32 v37, v37, v46, s83
	v_and_or_b32 v36, v37, s84, v36
	v_bfe_u32 v37, v38, 16, 1
	v_add3_u32 v37, v38, v37, s83
	v_bfe_u32 v38, v39, 16, 1
	v_lshrrev_b32_e32 v37, 16, v37
	v_add3_u32 v38, v39, v38, s83
	v_and_or_b32 v37, v38, s84, v37
	v_bfe_u32 v38, v32, 16, 1
	v_add3_u32 v32, v32, v38, s83
	v_bfe_u32 v38, v33, 16, 1
	v_lshrrev_b32_e32 v32, 16, v32
	v_add3_u32 v33, v33, v38, s83
	v_and_or_b32 v32, v33, s84, v32
	v_bfe_u32 v33, v34, 16, 1
	v_add3_u32 v33, v34, v33, s83
	v_bfe_u32 v34, v35, 16, 1
	v_lshrrev_b32_e32 v33, 16, v33
	v_add3_u32 v34, v35, v34, s83
	v_and_or_b32 v33, v34, s84, v33
	ds_write2_b64 v54, v[44:45], v[32:33] offset0:8 offset1:12
	v_bfe_u32 v32, v24, 16, 1
	v_add3_u32 v24, v24, v32, s83
	v_bfe_u32 v32, v25, 16, 1
	v_lshrrev_b32_e32 v24, 16, v24
	v_add3_u32 v25, v25, v32, s83
	v_and_or_b32 v24, v25, s84, v24
	v_bfe_u32 v25, v26, 16, 1
	v_add3_u32 v25, v26, v25, s83
	v_bfe_u32 v26, v27, 16, 1
	v_lshrrev_b32_e32 v25, 16, v25
	v_add3_u32 v26, v27, v26, s83
	v_and_or_b32 v25, v26, s84, v25
	ds_write2_b64 v50, v[36:37], v[24:25] offset0:40 offset1:44
	v_bfe_u32 v24, v40, 16, 1
	v_add3_u32 v24, v40, v24, s83
	v_bfe_u32 v25, v41, 16, 1
	v_lshrrev_b32_e32 v24, 16, v24
	v_add3_u32 v25, v41, v25, s83
	v_and_or_b32 v24, v25, s84, v24
	v_bfe_u32 v25, v42, 16, 1
	v_add3_u32 v25, v42, v25, s83
	v_bfe_u32 v26, v43, 16, 1
	v_lshrrev_b32_e32 v25, 16, v25
	v_add3_u32 v26, v43, v26, s83
	v_and_or_b32 v25, v26, s84, v25
	v_add_u32_e32 v26, 0x1a000, v62
	ds_write_b64 v26, v[24:25]
	v_bfe_u32 v24, v28, 16, 1
	v_add3_u32 v24, v28, v24, s83
	v_bfe_u32 v25, v29, 16, 1
	v_lshrrev_b32_e32 v24, 16, v24
	v_add3_u32 v25, v29, v25, s83
	v_and_or_b32 v24, v25, s84, v24
	v_bfe_u32 v25, v30, 16, 1
	v_add3_u32 v25, v30, v25, s83
	v_bfe_u32 v27, v31, 16, 1
	v_lshrrev_b32_e32 v25, 16, v25
	v_add3_u32 v27, v31, v27, s83
	v_and_or_b32 v25, v27, s84, v25
	ds_write_b64 v26, v[24:25] offset:4352
	v_bfe_u32 v24, v20, 16, 1
	v_add3_u32 v20, v20, v24, s83
	v_bfe_u32 v24, v21, 16, 1
	v_lshrrev_b32_e32 v20, 16, v20
	v_add3_u32 v21, v21, v24, s83
	v_and_or_b32 v20, v21, s84, v20
	v_bfe_u32 v21, v22, 16, 1
	v_add3_u32 v21, v22, v21, s83
	v_bfe_u32 v22, v23, 16, 1
	v_lshrrev_b32_e32 v21, 16, v21
	v_add3_u32 v22, v23, v22, s83
	v_and_or_b32 v21, v22, s84, v21
	v_add_u32_e32 v22, 0x1a020, v62
	ds_write_b64 v22, v[20:21]
	v_bfe_u32 v20, v16, 16, 1
	v_add3_u32 v16, v16, v20, s83
	v_bfe_u32 v20, v17, 16, 1
	v_lshrrev_b32_e32 v16, 16, v16
	v_add3_u32 v17, v17, v20, s83
	v_and_or_b32 v16, v17, s84, v16
	v_bfe_u32 v17, v18, 16, 1
	v_add3_u32 v17, v18, v17, s83
	v_bfe_u32 v18, v19, 16, 1
	v_lshrrev_b32_e32 v17, 16, v17
	v_add3_u32 v18, v19, v18, s83
	v_and_or_b32 v17, v18, s84, v17
	ds_write_b64 v22, v[16:17] offset:4352
	v_bfe_u32 v16, v12, 16, 1
	v_add3_u32 v12, v12, v16, s83
	v_bfe_u32 v16, v13, 16, 1
	v_lshrrev_b32_e32 v12, 16, v12
	v_add3_u32 v13, v13, v16, s83
	v_and_or_b32 v12, v13, s84, v12
	v_bfe_u32 v13, v14, 16, 1
	v_add3_u32 v13, v14, v13, s83
	v_bfe_u32 v14, v15, 16, 1
	v_lshrrev_b32_e32 v13, 16, v13
	v_add3_u32 v14, v15, v14, s83
	v_and_or_b32 v13, v14, s84, v13
	v_add_u32_e32 v14, 0x1a040, v62
	ds_write_b64 v14, v[12:13]
	v_bfe_u32 v12, v8, 16, 1
	v_add3_u32 v8, v8, v12, s83
	v_bfe_u32 v12, v9, 16, 1
	v_lshrrev_b32_e32 v8, 16, v8
	v_add3_u32 v9, v9, v12, s83
	v_and_or_b32 v8, v9, s84, v8
	v_bfe_u32 v9, v10, 16, 1
	v_add3_u32 v9, v10, v9, s83
	v_bfe_u32 v10, v11, 16, 1
	v_lshrrev_b32_e32 v9, 16, v9
	v_add3_u32 v10, v11, v10, s83
	v_and_or_b32 v9, v10, s84, v9
	ds_write_b64 v14, v[8:9] offset:4352
	v_bfe_u32 v8, v4, 16, 1
	v_add3_u32 v4, v4, v8, s83
	v_bfe_u32 v8, v5, 16, 1
	v_lshrrev_b32_e32 v4, 16, v4
	v_add3_u32 v5, v5, v8, s83
	v_and_or_b32 v4, v5, s84, v4
	v_bfe_u32 v5, v6, 16, 1
	v_add3_u32 v5, v6, v5, s83
	v_bfe_u32 v6, v7, 16, 1
	v_lshrrev_b32_e32 v5, 16, v5
	v_add3_u32 v6, v7, v6, s83
	v_and_or_b32 v5, v6, s84, v5
	v_add_u32_e32 v6, 0x1a060, v62
	ds_write_b64 v6, v[4:5]
	v_bfe_u32 v4, v0, 16, 1
	v_add3_u32 v0, v0, v4, s83
	v_bfe_u32 v4, v1, 16, 1
	v_lshrrev_b32_e32 v0, 16, v0
	v_add3_u32 v1, v1, v4, s83
	v_and_or_b32 v0, v1, s84, v0
	v_bfe_u32 v1, v2, 16, 1
	v_add3_u32 v1, v2, v1, s83
	v_bfe_u32 v2, v3, 16, 1
	v_lshrrev_b32_e32 v1, 16, v1
	v_add3_u32 v2, v3, v2, s83
	v_and_or_b32 v1, v2, s84, v1
	s_lshl_b32 s59, s87, 1
	ds_write_b64 v6, v[0:1] offset:4352
	s_nop 0
	v_ashrrev_i32_e32 v132, 8, v137
	v_add_u32_e32 v130, s59, v132
	v_bfe_u32 v135, v137, 7, 1
	v_ashrrev_i32_e32 v131, 31, v130
	v_and_b32_e32 v2, 31, v137
	v_lshlrev_b64 v[0:1], 7, v[130:131]
	v_lshlrev_b32_e32 v136, 6, v135
	v_or3_b32 v0, v0, v136, v2
	v_bfe_u32 v133, v137, 5, 1
	v_lshlrev_b64 v[0:1], 8, v[0:1]
	v_lshl_add_u64 v[0:1], s[4:5], 0, v[0:1]
	v_lshlrev_b32_e32 v128, 4, v133
	v_lshl_add_u64 v[8:9], v[0:1], 0, v[128:129]
	global_load_dwordx4 v[0:3], v[8:9], off
	v_add_co_u32_e32 v10, vcc, s76, v8
	v_mul_i32_i24_e32 v131, 0x12000, v132
	s_nop 0
	v_addc_co_u32_e32 v11, vcc, 0, v9, vcc
	global_load_dwordx4 v[4:7], v[10:11], off
	global_load_dwordx4 v[138:141], v[8:9], off offset:32
	global_load_dwordx4 v[142:145], v[10:11], off offset:32
	global_load_dwordx4 v[146:149], v[8:9], off offset:64
	global_load_dwordx4 v[150:153], v[8:9], off offset:96
	global_load_dwordx4 v[154:157], v[10:11], off offset:64
	global_load_dwordx4 v[158:161], v[10:11], off offset:96
	global_load_dwordx4 v[162:165], v[8:9], off offset:128
	global_load_dwordx4 v[166:169], v[8:9], off offset:160
	global_load_dwordx4 v[170:173], v[10:11], off offset:128
	global_load_dwordx4 v[178:181], v[10:11], off offset:160
	global_load_dwordx4 v[182:185], v[8:9], off offset:192
	global_load_dwordx4 v[186:189], v[8:9], off offset:224
	global_load_dwordx4 v[190:193], v[10:11], off offset:192
	global_load_dwordx4 v[194:197], v[10:11], off offset:224
	v_and_b32_e32 v8, 0x5f, v137
	v_mul_u32_u24_e32 v8, 0x110, v8
	v_add3_u32 v128, v131, v8, v128
	s_waitcnt lgkmcnt(0)
	s_barrier
	ds_read_b128 v[8:11], v128 offset:32768
	ds_read_b128 v[198:201], v128 offset:32800
	s_waitcnt vmcnt(15) lgkmcnt(1)
	v_mfma_f32_32x32x16_bf16 v[32:47], v[0:3], v[8:11], 0
	ds_read_b128 v[12:15], v128 offset:41472
	ds_read_b128 v[202:205], v128 offset:41504
	v_lshlrev_b32_e32 v135, 1, v135
	s_waitcnt vmcnt(14)
	v_mfma_f32_32x32x16_bf16 v[48:63], v[4:7], v[8:11], 0
	s_waitcnt lgkmcnt(1)
	v_mfma_f32_32x32x16_bf16 v[16:31], v[0:3], v[12:15], 0
	v_mfma_f32_32x32x16_bf16 v[0:15], v[4:7], v[12:15], 0
	s_waitcnt vmcnt(13)
	v_mfma_f32_32x32x16_bf16 v[32:47], v[138:141], v[198:201], v[32:47]
	s_waitcnt vmcnt(12)
	v_mfma_f32_32x32x16_bf16 v[48:63], v[142:145], v[198:201], v[48:63]
	s_waitcnt lgkmcnt(0)
	v_mfma_f32_32x32x16_bf16 v[16:31], v[138:141], v[202:205], v[16:31]
	v_mfma_f32_32x32x16_bf16 v[0:15], v[142:145], v[202:205], v[0:15]
	ds_read_b128 v[138:141], v128 offset:32832
	ds_read_b128 v[142:145], v128 offset:32864
	ds_read_b128 v[198:201], v128 offset:41536
	ds_read_b128 v[202:205], v128 offset:41568
	s_waitcnt vmcnt(11) lgkmcnt(3)
	v_mfma_f32_32x32x16_bf16 v[32:47], v[146:149], v[138:141], v[32:47]
	s_waitcnt vmcnt(9)
	v_mfma_f32_32x32x16_bf16 v[48:63], v[154:157], v[138:141], v[48:63]
	s_waitcnt lgkmcnt(1)
	v_mfma_f32_32x32x16_bf16 v[16:31], v[146:149], v[198:201], v[16:31]
	v_mfma_f32_32x32x16_bf16 v[0:15], v[154:157], v[198:201], v[0:15]
	v_mfma_f32_32x32x16_bf16 v[32:47], v[150:153], v[142:145], v[32:47]
	s_waitcnt vmcnt(8)
	v_mfma_f32_32x32x16_bf16 v[48:63], v[158:161], v[142:145], v[48:63]
	ds_read_b128 v[138:141], v128 offset:32896
	ds_read_b128 v[142:145], v128 offset:32928
	s_waitcnt lgkmcnt(2)
	v_mfma_f32_32x32x16_bf16 v[16:31], v[150:153], v[202:205], v[16:31]
	ds_read_b128 v[146:149], v128 offset:41600
	ds_read_b128 v[150:153], v128 offset:41632
	v_mfma_f32_32x32x16_bf16 v[0:15], v[158:161], v[202:205], v[0:15]
	s_waitcnt vmcnt(7) lgkmcnt(3)
	v_mfma_f32_32x32x16_bf16 v[32:47], v[162:165], v[138:141], v[32:47]
	s_waitcnt vmcnt(5)
	v_mfma_f32_32x32x16_bf16 v[48:63], v[170:173], v[138:141], v[48:63]
	s_waitcnt lgkmcnt(1)
	v_mfma_f32_32x32x16_bf16 v[16:31], v[162:165], v[146:149], v[16:31]
	v_mfma_f32_32x32x16_bf16 v[0:15], v[170:173], v[146:149], v[0:15]
	v_mfma_f32_32x32x16_bf16 v[32:47], v[166:169], v[142:145], v[32:47]
	s_waitcnt vmcnt(4)
	v_mfma_f32_32x32x16_bf16 v[48:63], v[178:181], v[142:145], v[48:63]
	ds_read_b128 v[138:141], v128 offset:32960
	ds_read_b128 v[142:145], v128 offset:32992
	s_waitcnt lgkmcnt(2)
	v_mfma_f32_32x32x16_bf16 v[16:31], v[166:169], v[150:153], v[16:31]
	v_mfma_f32_32x32x16_bf16 v[0:15], v[178:181], v[150:153], v[0:15]
	ds_read_b128 v[146:149], v128 offset:41664
	ds_read_b128 v[150:153], v128 offset:41696
	v_and_b32_e32 v128, 0xff, v137
	v_cmp_gt_u32_e32 vcc, s77, v128
	s_waitcnt vmcnt(3) lgkmcnt(3)
	v_mfma_f32_32x32x16_bf16 v[32:47], v[182:185], v[138:141], v[32:47]
	s_waitcnt vmcnt(1)
	v_mfma_f32_32x32x16_bf16 v[48:63], v[190:193], v[138:141], v[48:63]
	v_lshlrev_b32_e32 v138, 2, v133
	s_waitcnt lgkmcnt(1)
	v_mfma_f32_32x32x16_bf16 v[16:31], v[182:185], v[146:149], v[16:31]
	v_mfma_f32_32x32x16_bf16 v[0:15], v[190:193], v[146:149], v[0:15]
	v_mfma_f32_32x32x16_bf16 v[32:47], v[186:189], v[142:145], v[32:47]
	s_waitcnt vmcnt(0)
	v_mfma_f32_32x32x16_bf16 v[48:63], v[194:197], v[142:145], v[48:63]
	s_nop 9
	v_ashrrev_i32_e32 v139, 31, v32
	v_ashrrev_i32_e32 v140, 31, v33
	v_ashrrev_i32_e32 v141, 31, v34
	v_ashrrev_i32_e32 v142, 31, v35
	v_ashrrev_i32_e32 v143, 31, v36
	v_ashrrev_i32_e32 v144, 31, v37
	v_ashrrev_i32_e32 v145, 31, v38
	s_waitcnt lgkmcnt(0)
	v_mfma_f32_32x32x16_bf16 v[16:31], v[186:189], v[150:153], v[16:31]
	v_ashrrev_i32_e32 v146, 31, v39
	v_ashrrev_i32_e32 v147, 31, v40
	v_ashrrev_i32_e32 v148, 31, v41
	v_ashrrev_i32_e32 v149, 31, v42
	v_ashrrev_i32_e32 v154, 31, v47
	v_or_b32_e32 v139, 0x80000000, v139
	v_or_b32_e32 v140, 0x80000000, v140
	v_mfma_f32_32x32x16_bf16 v[0:15], v[194:197], v[150:153], v[0:15]
	v_ashrrev_i32_e32 v150, 31, v43
	v_ashrrev_i32_e32 v151, 31, v44
	v_ashrrev_i32_e32 v152, 31, v45
	v_ashrrev_i32_e32 v153, 31, v46
	v_or_b32_e32 v141, 0x80000000, v141
	v_or_b32_e32 v142, 0x80000000, v142
	v_or_b32_e32 v143, 0x80000000, v143
	v_or_b32_e32 v144, 0x80000000, v144
	v_or_b32_e32 v145, 0x80000000, v145
	v_or_b32_e32 v146, 0x80000000, v146
	v_or_b32_e32 v147, 0x80000000, v147
	v_or_b32_e32 v148, 0x80000000, v148
	v_or_b32_e32 v149, 0x80000000, v149
	v_or_b32_e32 v150, 0x80000000, v150
	v_or_b32_e32 v151, 0x80000000, v151
	v_or_b32_e32 v152, 0x80000000, v152
	v_or_b32_e32 v153, 0x80000000, v153
	v_or_b32_e32 v154, 0x80000000, v154
	v_bitop3_b32 v32, v139, s86, v32 bitop3:0x48
	v_ashrrev_i32_e32 v139, 31, v48
	v_bitop3_b32 v33, v140, s86, v33 bitop3:0x48
	v_ashrrev_i32_e32 v140, 31, v49
	v_bitop3_b32 v34, v141, s86, v34 bitop3:0x48
	v_ashrrev_i32_e32 v141, 31, v50
	v_bitop3_b32 v35, v142, s86, v35 bitop3:0x48
	v_ashrrev_i32_e32 v142, 31, v51
	v_bitop3_b32 v36, v143, s86, v36 bitop3:0x48
	v_ashrrev_i32_e32 v143, 31, v52
	v_bitop3_b32 v37, v144, s86, v37 bitop3:0x48
	v_ashrrev_i32_e32 v144, 31, v53
	v_bitop3_b32 v38, v145, s86, v38 bitop3:0x48
	v_ashrrev_i32_e32 v145, 31, v54
	v_bitop3_b32 v39, v146, s86, v39 bitop3:0x48
	v_ashrrev_i32_e32 v146, 31, v55
	v_bitop3_b32 v40, v147, s86, v40 bitop3:0x48
	v_ashrrev_i32_e32 v147, 31, v56
	v_bitop3_b32 v41, v148, s86, v41 bitop3:0x48
	v_ashrrev_i32_e32 v148, 31, v57
	v_bitop3_b32 v42, v149, s86, v42 bitop3:0x48
	v_ashrrev_i32_e32 v149, 31, v58
	v_bitop3_b32 v43, v150, s86, v43 bitop3:0x48
	v_ashrrev_i32_e32 v150, 31, v59
	v_bitop3_b32 v44, v151, s86, v44 bitop3:0x48
	v_ashrrev_i32_e32 v151, 31, v60
	v_bitop3_b32 v45, v152, s86, v45 bitop3:0x48
	v_ashrrev_i32_e32 v152, 31, v61
	v_bitop3_b32 v46, v153, s86, v46 bitop3:0x48
	v_ashrrev_i32_e32 v153, 31, v62
	v_bitop3_b32 v47, v154, s86, v47 bitop3:0x48
	v_ashrrev_i32_e32 v154, 31, v63
	v_bitop3_b32 v48, v139, v48, s85 bitop3:0x36
	v_or_b32_e32 v139, 1, v138
	v_bitop3_b32 v49, v140, v49, s85 bitop3:0x36
	v_or_b32_e32 v140, 2, v138
	v_bitop3_b32 v50, v141, v50, s85 bitop3:0x36
	v_or_b32_e32 v141, 3, v138
	v_bitop3_b32 v51, v142, v51, s85 bitop3:0x36
	v_or_b32_e32 v142, 8, v138
	v_bitop3_b32 v52, v143, v52, s85 bitop3:0x36
	v_or_b32_e32 v143, 9, v138
	v_bitop3_b32 v53, v144, v53, s85 bitop3:0x36
	v_or_b32_e32 v144, 10, v138
	v_bitop3_b32 v54, v145, v54, s85 bitop3:0x36
	v_or_b32_e32 v145, 11, v138
	v_bitop3_b32 v55, v146, v55, s85 bitop3:0x36
	v_or_b32_e32 v146, 16, v138
	v_bitop3_b32 v56, v147, v56, s85 bitop3:0x36
	v_or_b32_e32 v147, 17, v138
	v_bitop3_b32 v57, v148, v57, s85 bitop3:0x36
	v_or_b32_e32 v148, 18, v138
	v_bitop3_b32 v58, v149, v58, s85 bitop3:0x36
	v_or_b32_e32 v149, 19, v138
	v_bitop3_b32 v59, v150, v59, s85 bitop3:0x36
	v_or_b32_e32 v150, 24, v138
	v_bitop3_b32 v60, v151, v60, s85 bitop3:0x36
	v_or_b32_e32 v151, 25, v138
	v_bitop3_b32 v61, v152, v61, s85 bitop3:0x36
	v_or_b32_e32 v152, 26, v138
	v_bitop3_b32 v62, v153, v62, s85 bitop3:0x36
	v_or_b32_e32 v153, 27, v138
	v_bitop3_b32 v63, v154, v63, s85 bitop3:0x36
	v_and_or_b32 v48, v48, s86, v138
	v_and_or_b32 v49, v49, s86, v139
	v_and_or_b32 v50, v50, s86, v140
	v_and_or_b32 v51, v51, s86, v141
	v_and_or_b32 v52, v52, s86, v142
	v_and_or_b32 v53, v53, s86, v143
	v_and_or_b32 v54, v54, s86, v144
	v_and_or_b32 v55, v55, s86, v145
	v_and_or_b32 v56, v56, s86, v146
	v_and_or_b32 v57, v57, s86, v147
	v_and_or_b32 v58, v58, s86, v148
	v_and_or_b32 v59, v59, s86, v149
	v_and_or_b32 v60, v60, s86, v150
	v_and_or_b32 v61, v61, s86, v151
	v_and_or_b32 v62, v62, s86, v152
	v_and_or_b32 v63, v63, s86, v153
	v_or3_b32 v32, v136, v32, v138
	v_or3_b32 v48, v48, v136, 32
	v_or3_b32 v33, v136, v33, v139
	v_or3_b32 v49, v49, v136, 32
	v_or3_b32 v34, v136, v34, v140
	v_or3_b32 v50, v50, v136, 32
	v_or3_b32 v35, v136, v35, v141
	v_or3_b32 v51, v51, v136, 32
	v_or3_b32 v36, v136, v36, v142
	v_or3_b32 v52, v52, v136, 32
	v_or3_b32 v37, v136, v37, v143
	v_or3_b32 v53, v53, v136, 32
	v_or3_b32 v38, v136, v38, v144
	v_or3_b32 v54, v54, v136, 32
	v_or3_b32 v39, v136, v39, v145
	v_or3_b32 v55, v55, v136, 32
	v_or3_b32 v40, v136, v40, v146
	v_or3_b32 v56, v56, v136, 32
	v_or3_b32 v41, v136, v41, v147
	v_or3_b32 v57, v57, v136, 32
	v_or3_b32 v42, v136, v42, v148
	v_or3_b32 v58, v58, v136, 32
	v_or3_b32 v43, v136, v43, v149
	v_or3_b32 v59, v59, v136, 32
	v_or3_b32 v44, v136, v44, v150
	v_or3_b32 v60, v60, v136, 32
	v_or3_b32 v45, v136, v45, v151
	v_or3_b32 v61, v61, v136, 32
	v_or3_b32 v46, v136, v46, v152
	v_or3_b32 v62, v62, v136, 32
	v_or3_b32 v47, v136, v47, v153
	v_or3_b32 v63, v63, v136, 32
	v_max_u32_e32 v154, v32, v45
	v_min_u32_e32 v32, v32, v45
	v_max_u32_e32 v45, v33, v44
	v_min_u32_e32 v33, v33, v44
	v_max_u32_e32 v44, v34, v47
	v_min_u32_e32 v34, v34, v47
	v_max_u32_e32 v47, v35, v46
	v_min_u32_e32 v35, v35, v46
	v_max_u32_e32 v46, v36, v40
	v_min_u32_e32 v36, v36, v40
	v_max_u32_e32 v40, v37, v38
	v_min_u32_e32 v37, v37, v38
	v_max_u32_e32 v38, v39, v43
	v_min_u32_e32 v39, v39, v43
	v_max_u32_e32 v43, v41, v42
	v_min_u32_e32 v41, v41, v42
	v_max_u32_e32 v162, v48, v61
	v_min_u32_e32 v48, v48, v61
	v_max_u32_e32 v61, v49, v60
	v_min_u32_e32 v49, v49, v60
	v_max_u32_e32 v60, v50, v63
	v_min_u32_e32 v50, v50, v63
	v_max_u32_e32 v63, v51, v62
	v_min_u32_e32 v51, v51, v62
	v_max_u32_e32 v62, v52, v56
	v_min_u32_e32 v52, v52, v56
	v_max_u32_e32 v56, v53, v54
	v_min_u32_e32 v53, v53, v54
	v_max_u32_e32 v54, v55, v59
	v_min_u32_e32 v55, v55, v59
	v_max_u32_e32 v59, v57, v58
	v_min_u32_e32 v57, v57, v58
	v_max_u32_e32 v42, v154, v40
	v_min_u32_e32 v40, v154, v40
	v_max_u32_e32 v154, v45, v38
	v_min_u32_e32 v38, v45, v38
	v_max_u32_e32 v45, v44, v43
	v_min_u32_e32 v43, v44, v43
	v_max_u32_e32 v44, v47, v46
	v_min_u32_e32 v46, v47, v46
	v_max_u32_e32 v47, v37, v32
	v_min_u32_e32 v32, v37, v32
	v_max_u32_e32 v37, v36, v35
	v_min_u32_e32 v35, v36, v35
	v_max_u32_e32 v36, v41, v34
	v_min_u32_e32 v34, v41, v34
	v_max_u32_e32 v41, v39, v33
	v_min_u32_e32 v33, v39, v33
	v_max_u32_e32 v58, v162, v56
	v_min_u32_e32 v56, v162, v56
	v_max_u32_e32 v162, v61, v54
	v_min_u32_e32 v54, v61, v54
	v_max_u32_e32 v61, v60, v59
	v_min_u32_e32 v59, v60, v59
	v_max_u32_e32 v60, v63, v62
	v_min_u32_e32 v62, v63, v62
	v_max_u32_e32 v63, v53, v48
	v_min_u32_e32 v48, v53, v48
	v_max_u32_e32 v53, v52, v51
	v_min_u32_e32 v51, v52, v51
	v_max_u32_e32 v52, v57, v50
	v_min_u32_e32 v50, v57, v50
	v_max_u32_e32 v57, v55, v49
	v_min_u32_e32 v49, v55, v49
	v_max_u32_e32 v39, v42, v154
	v_min_u32_e32 v42, v42, v154
	v_max_u32_e32 v154, v45, v44
	v_min_u32_e32 v44, v45, v44
	v_max_u32_e32 v45, v46, v40
	v_min_u32_e32 v40, v46, v40
	v_max_u32_e32 v46, v47, v37
	v_min_u32_e32 v37, v47, v37
	v_max_u32_e32 v47, v38, v43
	v_min_u32_e32 v38, v38, v43
	v_max_u32_e32 v43, v36, v41
	v_min_u32_e32 v36, v36, v41
	v_max_u32_e32 v41, v33, v32
	v_min_u32_e32 v32, v33, v32
	v_max_u32_e32 v33, v35, v34
	v_min_u32_e32 v34, v35, v34
	v_max_u32_e32 v55, v58, v162
	v_min_u32_e32 v58, v58, v162
	v_max_u32_e32 v162, v61, v60
	v_min_u32_e32 v60, v61, v60
	v_max_u32_e32 v61, v62, v56
	v_min_u32_e32 v56, v62, v56
	v_max_u32_e32 v62, v63, v53
	v_min_u32_e32 v53, v63, v53
	v_max_u32_e32 v63, v54, v59
	v_min_u32_e32 v54, v54, v59
	v_max_u32_e32 v59, v52, v57
	v_min_u32_e32 v52, v52, v57
	v_max_u32_e32 v57, v49, v48
	v_min_u32_e32 v48, v49, v48
	v_max_u32_e32 v49, v51, v50
	v_min_u32_e32 v50, v51, v50
	v_min_u32_e32 v35, v39, v154
	v_max_u32_e32 v155, v42, v44
	v_min_u32_e32 v42, v42, v44
	v_max_u32_e32 v44, v45, v43
	v_min_u32_e32 v43, v45, v43
	v_max_u32_e32 v45, v40, v36
	v_min_u32_e32 v36, v40, v36
	v_max_u32_e32 v40, v46, v47
	v_min_u32_e32 v46, v46, v47
	v_max_u32_e32 v47, v37, v38
	v_min_u32_e32 v37, v37, v38
	v_max_u32_e32 v38, v41, v33
	v_min_u32_e32 v33, v41, v33
	v_max_u32_e32 v41, v32, v34
	v_min_u32_e32 v51, v55, v162
	v_max_u32_e32 v163, v58, v60
	v_min_u32_e32 v58, v58, v60
	v_max_u32_e32 v60, v61, v59
	v_min_u32_e32 v59, v61, v59
	v_max_u32_e32 v61, v56, v52
	v_min_u32_e32 v52, v56, v52
	v_max_u32_e32 v56, v62, v63
	v_min_u32_e32 v62, v62, v63
	v_max_u32_e32 v63, v53, v54
	v_min_u32_e32 v53, v53, v54
	v_max_u32_e32 v54, v57, v49
	v_min_u32_e32 v49, v57, v49
	v_max_u32_e32 v57, v48, v50
	v_min_u32_e32 v32, v32, v34
	v_max_u32_e32 v34, v155, v35
	v_min_u32_e32 v35, v155, v35
	v_max_u32_e32 v155, v42, v38
	v_min_u32_e32 v38, v42, v38
	v_max_u32_e32 v42, v44, v40
	v_min_u32_e32 v40, v44, v40
	v_max_u32_e32 v44, v45, v46
	v_min_u32_e32 v45, v45, v46
	v_max_u32_e32 v46, v47, v43
	v_min_u32_e32 v43, v47, v43
	v_max_u32_e32 v47, v37, v36
	v_min_u32_e32 v36, v37, v36
	v_max_u32_e32 v37, v41, v33
	v_min_u32_e32 v48, v48, v50
	v_max_u32_e32 v50, v163, v51
	v_min_u32_e32 v51, v163, v51
	v_max_u32_e32 v163, v58, v54
	v_min_u32_e32 v54, v58, v54
	v_max_u32_e32 v58, v60, v56
	v_min_u32_e32 v56, v60, v56
	v_max_u32_e32 v60, v61, v62
	v_min_u32_e32 v61, v61, v62
	v_max_u32_e32 v62, v63, v59
	v_min_u32_e32 v59, v63, v59
	v_max_u32_e32 v63, v53, v52
	v_min_u32_e32 v52, v53, v52
	v_max_u32_e32 v53, v57, v49
	v_min_u32_e32 v33, v41, v33
	v_max_u32_e32 v156, v35, v40
	v_min_u32_e32 v35, v35, v40
	v_max_u32_e32 v40, v44, v46
	v_min_u32_e32 v44, v44, v46
	v_max_u32_e32 v46, v45, v43
	v_min_u32_e32 v43, v45, v43
	v_max_u32_e32 v45, v47, v37
	v_min_u32_e32 v49, v57, v49
	v_max_u32_e32 v164, v51, v56
	v_min_u32_e32 v51, v51, v56
	v_max_u32_e32 v56, v60, v62
	v_min_u32_e32 v60, v60, v62
	v_max_u32_e32 v62, v61, v59
	v_min_u32_e32 v59, v61, v59
	v_max_u32_e32 v61, v63, v53
	v_min_u32_e32 v37, v47, v37
	v_max_u32_e32 v47, v36, v33
	v_max_u32_e32 v157, v155, v35
	v_min_u32_e32 v35, v155, v35
	v_max_u32_e32 v155, v45, v38
	v_min_u32_e32 v38, v45, v38
	v_min_u32_e32 v53, v63, v53
	v_max_u32_e32 v63, v52, v49
	v_max_u32_e32 v165, v163, v51
	v_min_u32_e32 v51, v163, v51
	v_max_u32_e32 v163, v61, v54
	v_min_u32_e32 v54, v61, v54
	v_min_u32_e32 v41, v34, v42
	v_max_u32_e32 v45, v47, v37
	v_min_u32_e32 v37, v47, v37
	v_max_u32_e32 v47, v157, v40
	v_min_u32_e32 v40, v157, v40
	v_max_u32_e32 v157, v35, v44
	v_min_u32_e32 v35, v35, v44
	v_max_u32_e32 v44, v46, v155
	v_min_u32_e32 v46, v46, v155
	v_max_u32_e32 v155, v43, v38
	v_min_u32_e32 v57, v50, v58
	v_max_u32_e32 v61, v63, v53
	v_min_u32_e32 v53, v63, v53
	v_max_u32_e32 v63, v165, v56
	v_min_u32_e32 v56, v165, v56
	v_max_u32_e32 v165, v51, v60
	v_min_u32_e32 v51, v51, v60
	v_max_u32_e32 v60, v62, v163
	v_min_u32_e32 v62, v62, v163
	v_max_u32_e32 v163, v59, v54
	v_min_u32_e32 v33, v36, v33
	v_min_u32_e32 v36, v156, v41
	v_min_u32_e32 v38, v43, v38
	v_min_u32_e32 v158, v40, v157
	v_max_u32_e32 v159, v44, v35
	v_min_u32_e32 v35, v44, v35
	v_max_u32_e32 v44, v46, v155
	v_min_u32_e32 v49, v52, v49
	v_min_u32_e32 v52, v164, v57
	v_min_u32_e32 v54, v59, v54
	v_min_u32_e32 v166, v56, v165
	v_max_u32_e32 v167, v60, v51
	v_min_u32_e32 v51, v60, v51
	v_max_u32_e32 v60, v62, v163
	v_min_u32_e32 v43, v47, v36
	v_min_u32_e32 v46, v46, v155
	v_min_u32_e32 v155, v45, v38
	v_min_u32_e32 v160, v158, v159
	v_min_u32_e32 v161, v35, v44
	v_min_u32_e32 v59, v63, v52
	v_min_u32_e32 v62, v62, v163
	v_min_u32_e32 v163, v61, v54
	v_min_u32_e32 v168, v166, v167
	v_min_u32_e32 v169, v51, v60
	v_max3_u32 v39, v39, v154, v48
	v_max3_u32 v34, v34, v42, v49
	v_max3_u32 v41, v156, v41, v53
	v_max3_u32 v36, v47, v36, v163
	v_max3_u32 v42, v43, v61, v54
	v_max3_u32 v40, v40, v157, v62
	v_max3_u32 v43, v158, v159, v169
	v_max3_u32 v47, v160, v51, v60
	v_max3_u32 v35, v35, v44, v168
	v_max3_u32 v44, v161, v166, v167
	v_max3_u32 v46, v46, v56, v165
	v_max3_u32 v38, v45, v38, v59
	v_max3_u32 v45, v155, v63, v52
	v_max3_u32 v37, v37, v164, v57
	v_max3_u32 v33, v33, v50, v58
	v_max3_u32 v32, v32, v55, v162
	v_max_u32_e32 v48, v39, v35
	v_min_u32_e32 v35, v39, v35
	v_max_u32_e32 v39, v34, v44
	v_min_u32_e32 v34, v34, v44
	v_max_u32_e32 v44, v41, v46
	v_min_u32_e32 v41, v41, v46
	v_max_u32_e32 v46, v36, v38
	v_min_u32_e32 v36, v36, v38
	v_max_u32_e32 v38, v42, v45
	v_min_u32_e32 v42, v42, v45
	v_max_u32_e32 v45, v40, v37
	v_min_u32_e32 v37, v40, v37
	v_max_u32_e32 v40, v43, v33
	v_min_u32_e32 v33, v43, v33
	v_max_u32_e32 v43, v47, v32
	v_min_u32_e32 v32, v47, v32
	v_max_u32_e32 v47, v48, v38
	v_min_u32_e32 v38, v48, v38
	v_max_u32_e32 v48, v39, v45
	v_min_u32_e32 v39, v39, v45
	v_max_u32_e32 v45, v44, v40
	v_min_u32_e32 v40, v44, v40
	v_max_u32_e32 v44, v46, v43
	v_min_u32_e32 v43, v46, v43
	v_max_u32_e32 v46, v35, v42
	v_min_u32_e32 v35, v35, v42
	v_max_u32_e32 v42, v34, v37
	v_min_u32_e32 v34, v34, v37
	v_max_u32_e32 v37, v41, v33
	v_min_u32_e32 v33, v41, v33
	v_max_u32_e32 v41, v36, v32
	v_min_u32_e32 v32, v36, v32
	v_max_u32_e32 v36, v47, v45
	v_min_u32_e32 v45, v47, v45
	v_max_u32_e32 v47, v48, v44
	v_min_u32_e32 v44, v48, v44
	v_max_u32_e32 v48, v38, v40
	v_min_u32_e32 v40, v38, v40
	v_max_u32_e32 v38, v39, v43
	v_min_u32_e32 v39, v39, v43
	v_max_u32_e32 v43, v46, v37
	v_min_u32_e32 v46, v46, v37
	v_max_u32_e32 v51, v35, v33
	v_min_u32_e32 v52, v35, v33
	v_max_u32_e32 v53, v34, v32
	v_min_u32_e32 v54, v34, v32
	v_max_u32_e32 v32, v36, v47
	v_min_u32_e32 v33, v36, v47
	v_max_u32_e32 v36, v48, v38
	v_min_u32_e32 v37, v48, v38
	v_lshlrev_b32_e32 v48, 2, v137
	v_max_u32_e32 v49, v42, v41
	v_and_b32_e32 v48, 0x17c, v48
	v_min_u32_e32 v50, v42, v41
	v_max_u32_e32 v38, v40, v39
	v_min_u32_e32 v39, v40, v39
	v_max_u32_e32 v40, v43, v49
	v_min_u32_e32 v41, v43, v49
	v_or3_b32 v49, v135, v48, v133
	v_lshlrev_b32_e32 v49, 6, v49
	v_max_u32_e32 v34, v45, v44
	v_min_u32_e32 v35, v45, v44
	v_mad_i32_i24 v49, v132, s75, v49
	v_max_u32_e32 v42, v46, v50
	v_min_u32_e32 v43, v46, v50
	v_max_u32_e32 v44, v51, v53
	v_min_u32_e32 v45, v51, v53
	v_max_u32_e32 v46, v52, v54
	v_min_u32_e32 v47, v52, v54
	v_bfe_u32 v240, v49, 8, 4
	v_lshlrev_b32_e32 v240, 4, v240
	v_xor_b32_e32 v240, v49, v240
	ds_write_b128 v240, v[32:35]
	v_xor_b32_e32 v241, 16, v240
	ds_write_b128 v241, v[36:39]
	v_xor_b32_e32 v241, 32, v240
	ds_write_b128 v241, v[40:43]
	v_xor_b32_e32 v241, 48, v240
	ds_write_b128 v241, v[44:47]
	v_ashrrev_i32_e32 v32, 31, v16
	v_or_b32_e32 v32, 0x80000000, v32
	v_bitop3_b32 v16, v32, s86, v16 bitop3:0x48
	v_ashrrev_i32_e32 v32, 31, v0
	v_bitop3_b32 v0, v32, v0, s85 bitop3:0x36
	v_ashrrev_i32_e32 v32, 31, v17
	v_or_b32_e32 v32, 0x80000000, v32
	v_bitop3_b32 v17, v32, s86, v17 bitop3:0x48
	v_ashrrev_i32_e32 v32, 31, v1
	v_bitop3_b32 v1, v32, v1, s85 bitop3:0x36
	v_ashrrev_i32_e32 v32, 31, v18
	v_or_b32_e32 v32, 0x80000000, v32
	v_bitop3_b32 v18, v32, s86, v18 bitop3:0x48
	v_ashrrev_i32_e32 v32, 31, v2
	v_bitop3_b32 v2, v32, v2, s85 bitop3:0x36
	v_ashrrev_i32_e32 v32, 31, v19
	v_or_b32_e32 v32, 0x80000000, v32
	v_bitop3_b32 v19, v32, s86, v19 bitop3:0x48
	v_ashrrev_i32_e32 v32, 31, v3
	v_bitop3_b32 v3, v32, v3, s85 bitop3:0x36
	v_ashrrev_i32_e32 v32, 31, v20
	v_or_b32_e32 v32, 0x80000000, v32
	v_bitop3_b32 v20, v32, s86, v20 bitop3:0x48
	v_ashrrev_i32_e32 v32, 31, v4
	v_bitop3_b32 v4, v32, v4, s85 bitop3:0x36
	v_ashrrev_i32_e32 v32, 31, v21
	v_or_b32_e32 v32, 0x80000000, v32
	v_bitop3_b32 v21, v32, s86, v21 bitop3:0x48
	v_ashrrev_i32_e32 v32, 31, v5
	v_bitop3_b32 v5, v32, v5, s85 bitop3:0x36
	v_ashrrev_i32_e32 v32, 31, v22
	v_or_b32_e32 v32, 0x80000000, v32
	v_bitop3_b32 v22, v32, s86, v22 bitop3:0x48
	v_ashrrev_i32_e32 v32, 31, v6
	v_bitop3_b32 v6, v32, v6, s85 bitop3:0x36
	v_ashrrev_i32_e32 v32, 31, v23
	v_or_b32_e32 v32, 0x80000000, v32
	v_bitop3_b32 v23, v32, s86, v23 bitop3:0x48
	v_ashrrev_i32_e32 v32, 31, v7
	v_bitop3_b32 v7, v32, v7, s85 bitop3:0x36
	v_ashrrev_i32_e32 v32, 31, v24
	v_or_b32_e32 v32, 0x80000000, v32
	v_bitop3_b32 v24, v32, s86, v24 bitop3:0x48
	v_ashrrev_i32_e32 v32, 31, v8
	v_bitop3_b32 v8, v32, v8, s85 bitop3:0x36
	v_ashrrev_i32_e32 v32, 31, v25
	v_or_b32_e32 v32, 0x80000000, v32
	v_bitop3_b32 v25, v32, s86, v25 bitop3:0x48
	v_ashrrev_i32_e32 v32, 31, v9
	v_bitop3_b32 v9, v32, v9, s85 bitop3:0x36
	v_ashrrev_i32_e32 v32, 31, v26
	v_or_b32_e32 v32, 0x80000000, v32
	v_bitop3_b32 v26, v32, s86, v26 bitop3:0x48
	v_ashrrev_i32_e32 v32, 31, v10
	v_bitop3_b32 v10, v32, v10, s85 bitop3:0x36
	v_ashrrev_i32_e32 v32, 31, v27
	v_or_b32_e32 v32, 0x80000000, v32
	v_bitop3_b32 v27, v32, s86, v27 bitop3:0x48
	v_ashrrev_i32_e32 v32, 31, v11
	v_bitop3_b32 v11, v32, v11, s85 bitop3:0x36
	v_ashrrev_i32_e32 v32, 31, v28
	v_or_b32_e32 v32, 0x80000000, v32
	v_bitop3_b32 v28, v32, s86, v28 bitop3:0x48
	v_ashrrev_i32_e32 v32, 31, v12
	v_bitop3_b32 v12, v32, v12, s85 bitop3:0x36
	v_ashrrev_i32_e32 v32, 31, v29
	v_or_b32_e32 v32, 0x80000000, v32
	v_bitop3_b32 v29, v32, s86, v29 bitop3:0x48
	v_ashrrev_i32_e32 v32, 31, v13
	v_bitop3_b32 v13, v32, v13, s85 bitop3:0x36
	v_ashrrev_i32_e32 v32, 31, v30
	v_or_b32_e32 v32, 0x80000000, v32
	v_bitop3_b32 v30, v32, s86, v30 bitop3:0x48
	v_ashrrev_i32_e32 v32, 31, v14
	v_bitop3_b32 v14, v32, v14, s85 bitop3:0x36
	v_ashrrev_i32_e32 v32, 31, v31
	v_or_b32_e32 v32, 0x80000000, v32
	v_bitop3_b32 v31, v32, s86, v31 bitop3:0x48
	v_ashrrev_i32_e32 v32, 31, v15
	v_bitop3_b32 v15, v32, v15, s85 bitop3:0x36
	v_and_or_b32 v0, v0, s86, v138
	v_and_or_b32 v1, v1, s86, v139
	v_and_or_b32 v2, v2, s86, v140
	v_and_or_b32 v3, v3, s86, v141
	v_and_or_b32 v4, v4, s86, v142
	v_and_or_b32 v5, v5, s86, v143
	v_and_or_b32 v6, v6, s86, v144
	v_and_or_b32 v7, v7, s86, v145
	v_and_or_b32 v8, v8, s86, v146
	v_and_or_b32 v9, v9, s86, v147
	v_and_or_b32 v10, v10, s86, v148
	v_and_or_b32 v11, v11, s86, v149
	v_and_or_b32 v12, v12, s86, v150
	v_and_or_b32 v13, v13, s86, v151
	v_and_or_b32 v14, v14, s86, v152
	v_and_or_b32 v15, v15, s86, v153
	v_or3_b32 v16, v136, v16, v138
	v_or3_b32 v0, v0, v136, 32
	v_or3_b32 v17, v136, v17, v139
	v_or3_b32 v1, v1, v136, 32
	v_or3_b32 v18, v136, v18, v140
	v_or3_b32 v2, v2, v136, 32
	v_or3_b32 v19, v136, v19, v141
	v_or3_b32 v3, v3, v136, 32
	v_or3_b32 v20, v136, v20, v142
	v_or3_b32 v4, v4, v136, 32
	v_or3_b32 v21, v136, v21, v143
	v_or3_b32 v5, v5, v136, 32
	v_or3_b32 v22, v136, v22, v144
	v_or3_b32 v6, v6, v136, 32
	v_or3_b32 v23, v136, v23, v145
	v_or3_b32 v7, v7, v136, 32
	v_or3_b32 v24, v136, v24, v146
	v_or3_b32 v8, v8, v136, 32
	v_or3_b32 v25, v136, v25, v147
	v_or3_b32 v9, v9, v136, 32
	v_or3_b32 v26, v136, v26, v148
	v_or3_b32 v10, v10, v136, 32
	v_or3_b32 v27, v136, v27, v149
	v_or3_b32 v11, v11, v136, 32
	v_or3_b32 v28, v136, v28, v150
	v_or3_b32 v12, v12, v136, 32
	v_or3_b32 v29, v136, v29, v151
	v_or3_b32 v13, v13, v136, 32
	v_or3_b32 v30, v136, v30, v152
	v_or3_b32 v14, v14, v136, 32
	v_or3_b32 v31, v136, v31, v153
	v_or3_b32 v15, v15, v136, 32
	v_max_u32_e32 v32, v16, v29
	v_min_u32_e32 v16, v16, v29
	v_max_u32_e32 v29, v17, v28
	v_min_u32_e32 v17, v17, v28
	v_max_u32_e32 v28, v18, v31
	v_min_u32_e32 v18, v18, v31
	v_max_u32_e32 v31, v19, v30
	v_min_u32_e32 v19, v19, v30
	v_max_u32_e32 v30, v20, v24
	v_min_u32_e32 v20, v20, v24
	v_max_u32_e32 v24, v21, v22
	v_min_u32_e32 v21, v21, v22
	v_max_u32_e32 v22, v23, v27
	v_min_u32_e32 v23, v23, v27
	v_max_u32_e32 v27, v25, v26
	v_min_u32_e32 v25, v25, v26
	v_max_u32_e32 v40, v0, v13
	v_min_u32_e32 v0, v0, v13
	v_max_u32_e32 v13, v1, v12
	v_min_u32_e32 v1, v1, v12
	v_max_u32_e32 v12, v2, v15
	v_min_u32_e32 v2, v2, v15
	v_max_u32_e32 v15, v3, v14
	v_min_u32_e32 v3, v3, v14
	v_max_u32_e32 v14, v4, v8
	v_min_u32_e32 v4, v4, v8
	v_max_u32_e32 v8, v5, v6
	v_min_u32_e32 v5, v5, v6
	v_max_u32_e32 v6, v7, v11
	v_min_u32_e32 v7, v7, v11
	v_max_u32_e32 v11, v9, v10
	v_min_u32_e32 v9, v9, v10
	v_max_u32_e32 v26, v32, v24
	v_min_u32_e32 v24, v32, v24
	v_max_u32_e32 v32, v29, v22
	v_min_u32_e32 v22, v29, v22
	v_max_u32_e32 v29, v28, v27
	v_min_u32_e32 v27, v28, v27
	v_max_u32_e32 v28, v31, v30
	v_min_u32_e32 v30, v31, v30
	v_max_u32_e32 v31, v21, v16
	v_min_u32_e32 v16, v21, v16
	v_max_u32_e32 v21, v20, v19
	v_min_u32_e32 v19, v20, v19
	v_max_u32_e32 v20, v25, v18
	v_min_u32_e32 v18, v25, v18
	v_max_u32_e32 v25, v23, v17
	v_min_u32_e32 v17, v23, v17
	v_max_u32_e32 v10, v40, v8
	v_min_u32_e32 v8, v40, v8
	v_max_u32_e32 v40, v13, v6
	v_min_u32_e32 v6, v13, v6
	v_max_u32_e32 v13, v12, v11
	v_min_u32_e32 v11, v12, v11
	v_max_u32_e32 v12, v15, v14
	v_min_u32_e32 v14, v15, v14
	v_max_u32_e32 v15, v5, v0
	v_min_u32_e32 v0, v5, v0
	v_max_u32_e32 v5, v4, v3
	v_min_u32_e32 v3, v4, v3
	v_max_u32_e32 v4, v9, v2
	v_min_u32_e32 v2, v9, v2
	v_max_u32_e32 v9, v7, v1
	v_min_u32_e32 v1, v7, v1
	v_max_u32_e32 v23, v26, v32
	v_min_u32_e32 v26, v26, v32
	v_max_u32_e32 v32, v29, v28
	v_min_u32_e32 v28, v29, v28
	v_max_u32_e32 v29, v30, v24
	v_min_u32_e32 v24, v30, v24
	v_max_u32_e32 v30, v31, v21
	v_min_u32_e32 v21, v31, v21
	v_max_u32_e32 v31, v22, v27
	v_min_u32_e32 v22, v22, v27
	v_max_u32_e32 v27, v20, v25
	v_min_u32_e32 v20, v20, v25
	v_max_u32_e32 v25, v17, v16
	v_min_u32_e32 v16, v17, v16
	v_max_u32_e32 v17, v19, v18
	v_min_u32_e32 v18, v19, v18
	v_max_u32_e32 v7, v10, v40
	v_min_u32_e32 v10, v10, v40
	v_max_u32_e32 v40, v13, v12
	v_min_u32_e32 v12, v13, v12
	v_max_u32_e32 v13, v14, v8
	v_min_u32_e32 v8, v14, v8
	v_max_u32_e32 v14, v15, v5
	v_min_u32_e32 v5, v15, v5
	v_max_u32_e32 v15, v6, v11
	v_min_u32_e32 v6, v6, v11
	v_max_u32_e32 v11, v4, v9
	v_min_u32_e32 v4, v4, v9
	v_max_u32_e32 v9, v1, v0
	v_min_u32_e32 v0, v1, v0
	v_max_u32_e32 v1, v3, v2
	v_min_u32_e32 v2, v3, v2
	v_min_u32_e32 v19, v23, v32
	v_max_u32_e32 v33, v26, v28
	v_min_u32_e32 v26, v26, v28
	v_max_u32_e32 v28, v29, v27
	v_min_u32_e32 v27, v29, v27
	v_max_u32_e32 v29, v24, v20
	v_min_u32_e32 v20, v24, v20
	v_max_u32_e32 v24, v30, v31
	v_min_u32_e32 v30, v30, v31
	v_max_u32_e32 v31, v21, v22
	v_min_u32_e32 v21, v21, v22
	v_max_u32_e32 v22, v25, v17
	v_min_u32_e32 v17, v25, v17
	v_max_u32_e32 v25, v16, v18
	v_min_u32_e32 v3, v7, v40
	v_max_u32_e32 v41, v10, v12
	v_min_u32_e32 v10, v10, v12
	v_max_u32_e32 v12, v13, v11
	v_min_u32_e32 v11, v13, v11
	v_max_u32_e32 v13, v8, v4
	v_min_u32_e32 v4, v8, v4
	v_max_u32_e32 v8, v14, v15
	v_min_u32_e32 v14, v14, v15
	v_max_u32_e32 v15, v5, v6
	v_min_u32_e32 v5, v5, v6
	v_max_u32_e32 v6, v9, v1
	v_min_u32_e32 v1, v9, v1
	v_max_u32_e32 v9, v0, v2
	v_min_u32_e32 v16, v16, v18
	v_max_u32_e32 v18, v33, v19
	v_min_u32_e32 v19, v33, v19
	v_max_u32_e32 v33, v26, v22
	v_min_u32_e32 v22, v26, v22
	v_max_u32_e32 v26, v28, v24
	v_min_u32_e32 v24, v28, v24
	v_max_u32_e32 v28, v29, v30
	v_min_u32_e32 v29, v29, v30
	v_max_u32_e32 v30, v31, v27
	v_min_u32_e32 v27, v31, v27
	v_max_u32_e32 v31, v21, v20
	v_min_u32_e32 v20, v21, v20
	v_max_u32_e32 v21, v25, v17
	v_min_u32_e32 v0, v0, v2
	v_max_u32_e32 v2, v41, v3
	v_min_u32_e32 v3, v41, v3
	v_max_u32_e32 v41, v10, v6
	v_min_u32_e32 v6, v10, v6
	v_max_u32_e32 v10, v12, v8
	v_min_u32_e32 v8, v12, v8
	v_max_u32_e32 v12, v13, v14
	v_min_u32_e32 v13, v13, v14
	v_max_u32_e32 v14, v15, v11
	v_min_u32_e32 v11, v15, v11
	v_max_u32_e32 v15, v5, v4
	v_min_u32_e32 v4, v5, v4
	v_max_u32_e32 v5, v9, v1
	v_min_u32_e32 v17, v25, v17
	v_max_u32_e32 v34, v19, v24
	v_min_u32_e32 v19, v19, v24
	v_max_u32_e32 v24, v28, v30
	v_min_u32_e32 v28, v28, v30
	v_max_u32_e32 v30, v29, v27
	v_min_u32_e32 v27, v29, v27
	v_max_u32_e32 v29, v31, v21
	v_min_u32_e32 v1, v9, v1
	v_max_u32_e32 v42, v3, v8
	v_min_u32_e32 v3, v3, v8
	v_max_u32_e32 v8, v12, v14
	v_min_u32_e32 v12, v12, v14
	v_max_u32_e32 v14, v13, v11
	v_min_u32_e32 v11, v13, v11
	v_max_u32_e32 v13, v15, v5
	v_min_u32_e32 v21, v31, v21
	v_max_u32_e32 v31, v20, v17
	v_max_u32_e32 v35, v33, v19
	v_min_u32_e32 v19, v33, v19
	v_max_u32_e32 v33, v29, v22
	v_min_u32_e32 v22, v29, v22
	v_min_u32_e32 v5, v15, v5
	v_max_u32_e32 v15, v4, v1
	v_max_u32_e32 v43, v41, v3
	v_min_u32_e32 v3, v41, v3
	v_max_u32_e32 v41, v13, v6
	v_min_u32_e32 v6, v13, v6
	v_min_u32_e32 v25, v18, v26
	v_max_u32_e32 v29, v31, v21
	v_min_u32_e32 v21, v31, v21
	v_max_u32_e32 v31, v35, v24
	v_min_u32_e32 v24, v35, v24
	v_max_u32_e32 v35, v19, v28
	v_min_u32_e32 v19, v19, v28
	v_max_u32_e32 v28, v30, v33
	v_min_u32_e32 v30, v30, v33
	v_max_u32_e32 v33, v27, v22
	v_min_u32_e32 v9, v2, v10
	v_max_u32_e32 v13, v15, v5
	v_min_u32_e32 v5, v15, v5
	v_max_u32_e32 v15, v43, v8
	v_min_u32_e32 v8, v43, v8
	v_max_u32_e32 v43, v3, v12
	v_min_u32_e32 v3, v3, v12
	v_max_u32_e32 v12, v14, v41
	v_min_u32_e32 v14, v14, v41
	v_max_u32_e32 v41, v11, v6
	v_min_u32_e32 v17, v20, v17
	v_min_u32_e32 v20, v34, v25
	v_min_u32_e32 v22, v27, v22
	v_min_u32_e32 v36, v24, v35
	v_max_u32_e32 v37, v28, v19
	v_min_u32_e32 v19, v28, v19
	v_max_u32_e32 v28, v30, v33
	v_min_u32_e32 v1, v4, v1
	v_min_u32_e32 v4, v42, v9
	v_min_u32_e32 v6, v11, v6
	v_min_u32_e32 v44, v8, v43
	v_max_u32_e32 v45, v12, v3
	v_min_u32_e32 v3, v12, v3
	v_max_u32_e32 v12, v14, v41
	v_min_u32_e32 v27, v31, v20
	v_min_u32_e32 v30, v30, v33
	v_min_u32_e32 v33, v29, v22
	v_min_u32_e32 v38, v36, v37
	v_min_u32_e32 v39, v19, v28
	v_min_u32_e32 v11, v15, v4
	v_min_u32_e32 v14, v14, v41
	v_min_u32_e32 v41, v13, v6
	v_min_u32_e32 v46, v44, v45
	v_min_u32_e32 v47, v3, v12
	v_max3_u32 v0, v23, v32, v0
	v_max3_u32 v1, v18, v26, v1
	v_max3_u32 v5, v34, v25, v5
	v_max3_u32 v18, v31, v20, v41
	v_max3_u32 v6, v27, v13, v6
	v_max3_u32 v13, v24, v35, v14
	v_max3_u32 v14, v36, v37, v47
	v_max3_u32 v3, v38, v3, v12
	v_max3_u32 v12, v19, v28, v46
	v_max3_u32 v19, v39, v44, v45
	v_max3_u32 v8, v30, v8, v43
	v_max3_u32 v11, v29, v22, v11
	v_max3_u32 v4, v33, v15, v4
	v_max3_u32 v9, v21, v42, v9
	v_max3_u32 v2, v17, v2, v10
	v_max3_u32 v7, v16, v7, v40
	v_max_u32_e32 v10, v0, v12
	v_min_u32_e32 v0, v0, v12
	v_max_u32_e32 v12, v1, v19
	v_max_u32_e32 v15, v5, v8
	v_min_u32_e32 v5, v5, v8
	v_max_u32_e32 v8, v18, v11
	v_max_u32_e32 v16, v6, v4
	v_min_u32_e32 v4, v6, v4
	v_max_u32_e32 v6, v13, v9
	v_min_u32_e32 v9, v13, v9
	v_max_u32_e32 v13, v14, v2
	v_min_u32_e32 v2, v14, v2
	v_max_u32_e32 v14, v3, v7
	v_min_u32_e32 v1, v1, v19
	v_min_u32_e32 v11, v18, v11
	v_min_u32_e32 v3, v3, v7
	v_max_u32_e32 v7, v10, v16
	v_min_u32_e32 v10, v10, v16
	v_max_u32_e32 v16, v12, v6
	v_min_u32_e32 v6, v12, v6
	v_max_u32_e32 v12, v15, v13
	v_min_u32_e32 v13, v15, v13
	v_max_u32_e32 v15, v8, v14
	v_min_u32_e32 v8, v8, v14
	v_max_u32_e32 v14, v0, v4
	v_min_u32_e32 v0, v0, v4
	v_max_u32_e32 v4, v1, v9
	v_min_u32_e32 v1, v1, v9
	v_max_u32_e32 v9, v5, v2
	v_min_u32_e32 v2, v5, v2
	v_max_u32_e32 v5, v11, v3
	v_min_u32_e32 v3, v11, v3
	v_max_u32_e32 v11, v7, v12
	v_min_u32_e32 v7, v7, v12
	v_max_u32_e32 v12, v16, v15
	v_min_u32_e32 v15, v16, v15
	v_max_u32_e32 v16, v10, v13
	v_min_u32_e32 v10, v10, v13
	v_max_u32_e32 v13, v6, v8
	v_max_u32_e32 v17, v14, v9
	v_min_u32_e32 v14, v14, v9
	v_max_u32_e32 v9, v4, v5
	v_min_u32_e32 v18, v4, v5
	v_max_u32_e32 v4, v16, v13
	v_min_u32_e32 v5, v16, v13
	v_or3_b32 v16, v133, v48, v135
	v_lshlrev_b32_e32 v16, 6, v16
	v_min_u32_e32 v8, v6, v8
	v_max_u32_e32 v19, v0, v2
	v_min_u32_e32 v20, v0, v2
	v_max_u32_e32 v21, v1, v3
	v_min_u32_e32 v22, v1, v3
	v_max_u32_e32 v0, v11, v12
	v_min_u32_e32 v1, v11, v12
	v_max_u32_e32 v2, v7, v15
	v_min_u32_e32 v3, v7, v15
	v_mad_i32_i24 v16, v132, s75, v16
	v_max_u32_e32 v6, v10, v8
	v_min_u32_e32 v7, v10, v8
	v_max_u32_e32 v8, v17, v9
	v_min_u32_e32 v9, v17, v9
	v_max_u32_e32 v10, v14, v18
	v_min_u32_e32 v11, v14, v18
	v_max_u32_e32 v12, v19, v21
	v_min_u32_e32 v13, v19, v21
	v_max_u32_e32 v14, v20, v22
	v_min_u32_e32 v15, v20, v22
	v_bfe_u32 v240, v16, 8, 4
	v_lshlrev_b32_e32 v240, 4, v240
	v_xor_b32_e32 v240, v16, v240
	ds_write_b128 v240, v[0:3] offset:8192
	v_xor_b32_e32 v241, 16, v240
	ds_write_b128 v241, v[4:7] offset:8192
	v_xor_b32_e32 v241, 32, v240
	ds_write_b128 v241, v[8:11] offset:8192
	v_xor_b32_e32 v241, 48, v240
	ds_write_b128 v241, v[12:15] offset:8192
	s_waitcnt lgkmcnt(0)
	s_barrier
	s_and_saveexec_b64 s[62:63], vcc
	s_cbranch_execz .LBB0_867
	v_lshl_add_u32 v60, v128, 8, v131
	v_bfe_u32 v240, v60, 8, 4
	v_lshlrev_b32_e32 v240, 4, v240
	v_xor_b32_e32 v240, v60, v240
	ds_read_b128 v[0:3], v240
	v_xor_b32_e32 v241, 16, v240
	ds_read_b128 v[4:7], v241
	v_xor_b32_e32 v241, 32, v240
	ds_read_b128 v[8:11], v241
	v_xor_b32_e32 v241, 48, v240
	ds_read_b128 v[12:15], v241
	v_xor_b32_e32 v241, 64, v240
	ds_read_b128 v[16:19], v241
	v_xor_b32_e32 v241, 0x50, v240
	ds_read_b128 v[20:23], v241
	v_xor_b32_e32 v241, 0x80, v240
	ds_read_b128 v[24:27], v241
	v_xor_b32_e32 v241, 0x90, v240
	ds_read_b128 v[28:31], v241
	v_xor_b32_e32 v241, 0xc0, v240
	ds_read_b128 v[32:35], v241
	v_xor_b32_e32 v241, 0xd0, v240
	ds_read_b128 v[36:39], v241
	v_xor_b32_e32 v241, 0x60, v240
	ds_read_b128 v[40:43], v241
	v_xor_b32_e32 v241, 0x70, v240
	ds_read_b128 v[44:47], v241
	v_xor_b32_e32 v241, 0xa0, v240
	ds_read_b128 v[48:51], v241
	v_xor_b32_e32 v241, 0xb0, v240
	ds_read_b128 v[52:55], v241
	v_xor_b32_e32 v241, 0xe0, v240
	ds_read_b128 v[56:59], v241
	v_xor_b32_e32 v241, 0xf0, v240
	ds_read_b128 v[60:63], v241
	s_waitcnt lgkmcnt(4)
	v_max_u32_e32 v0, v0, v47
	v_max_u32_e32 v1, v1, v46
	v_max_u32_e32 v2, v2, v45
	v_max_u32_e32 v3, v3, v44
	v_max_u32_e32 v4, v4, v43
	v_max_u32_e32 v5, v5, v42
	v_max_u32_e32 v6, v6, v41
	v_max_u32_e32 v7, v7, v40
	v_max_u32_e32 v8, v8, v23
	v_max_u32_e32 v9, v9, v22
	v_max_u32_e32 v10, v10, v21
	v_max_u32_e32 v11, v11, v20
	v_max_u32_e32 v12, v12, v19
	v_max_u32_e32 v13, v13, v18
	v_max_u32_e32 v14, v14, v17
	v_max_u32_e32 v15, v15, v16
	s_waitcnt lgkmcnt(0)
	v_max_u32_e32 v24, v24, v63
	v_max_u32_e32 v25, v25, v62
	v_max_u32_e32 v26, v26, v61
	v_max_u32_e32 v27, v27, v60
	v_max_u32_e32 v28, v28, v59
	v_max_u32_e32 v29, v29, v58
	v_max_u32_e32 v30, v30, v57
	v_max_u32_e32 v31, v31, v56
	v_max_u32_e32 v39, v48, v39
	v_max_u32_e32 v38, v49, v38
	v_max_u32_e32 v37, v50, v37
	v_max_u32_e32 v36, v51, v36
	v_max_u32_e32 v35, v52, v35
	v_max_u32_e32 v34, v53, v34
	v_max_u32_e32 v33, v54, v33
	v_max_u32_e32 v32, v55, v32
	v_max_u32_e32 v16, v0, v8
	v_min_u32_e32 v0, v0, v8
	v_max_u32_e32 v8, v1, v9
	v_min_u32_e32 v1, v1, v9
	v_max_u32_e32 v9, v2, v10
	v_min_u32_e32 v2, v2, v10
	v_max_u32_e32 v10, v3, v11
	v_min_u32_e32 v3, v3, v11
	v_max_u32_e32 v11, v4, v12
	v_min_u32_e32 v4, v4, v12
	v_max_u32_e32 v12, v5, v13
	v_min_u32_e32 v5, v5, v13
	v_max_u32_e32 v13, v6, v14
	v_min_u32_e32 v6, v6, v14
	v_max_u32_e32 v14, v7, v15
	v_min_u32_e32 v7, v7, v15
	v_max_u32_e32 v40, v24, v39
	v_min_u32_e32 v24, v24, v39
	v_max_u32_e32 v39, v25, v38
	v_min_u32_e32 v25, v25, v38
	v_max_u32_e32 v38, v26, v37
	v_min_u32_e32 v26, v26, v37
	v_max_u32_e32 v37, v27, v36
	v_min_u32_e32 v27, v27, v36
	v_max_u32_e32 v36, v28, v35
	v_min_u32_e32 v28, v28, v35
	v_max_u32_e32 v35, v29, v34
	v_min_u32_e32 v29, v29, v34
	v_max_u32_e32 v34, v30, v33
	v_min_u32_e32 v30, v30, v33
	v_max_u32_e32 v33, v31, v32
	v_min_u32_e32 v31, v31, v32
	v_max_u32_e32 v15, v16, v11
	v_min_u32_e32 v11, v16, v11
	v_max_u32_e32 v16, v8, v12
	v_min_u32_e32 v8, v8, v12
	v_max_u32_e32 v12, v9, v13
	v_min_u32_e32 v9, v9, v13
	v_max_u32_e32 v13, v10, v14
	v_min_u32_e32 v10, v10, v14
	v_max_u32_e32 v14, v0, v4
	v_min_u32_e32 v0, v0, v4
	v_max_u32_e32 v4, v1, v5
	v_min_u32_e32 v1, v1, v5
	v_max_u32_e32 v5, v2, v6
	v_min_u32_e32 v2, v2, v6
	v_max_u32_e32 v6, v3, v7
	v_min_u32_e32 v3, v3, v7
	v_max_u32_e32 v32, v40, v36
	v_min_u32_e32 v36, v40, v36
	v_max_u32_e32 v40, v39, v35
	v_min_u32_e32 v35, v39, v35
	v_max_u32_e32 v39, v38, v34
	v_min_u32_e32 v34, v38, v34
	v_max_u32_e32 v38, v37, v33
	v_min_u32_e32 v33, v37, v33
	v_max_u32_e32 v37, v24, v28
	v_min_u32_e32 v24, v24, v28
	v_max_u32_e32 v28, v25, v29
	v_min_u32_e32 v25, v25, v29
	v_max_u32_e32 v29, v26, v30
	v_min_u32_e32 v26, v26, v30
	v_max_u32_e32 v30, v27, v31
	v_min_u32_e32 v27, v27, v31
	v_max_u32_e32 v7, v15, v12
	v_min_u32_e32 v12, v15, v12
	v_max_u32_e32 v15, v16, v13
	v_min_u32_e32 v13, v16, v13
	v_max_u32_e32 v16, v11, v9
	v_min_u32_e32 v9, v11, v9
	v_max_u32_e32 v11, v8, v10
	v_min_u32_e32 v8, v8, v10
	v_max_u32_e32 v10, v14, v5
	v_min_u32_e32 v5, v14, v5
	v_max_u32_e32 v14, v4, v6
	v_min_u32_e32 v4, v4, v6
	v_max_u32_e32 v6, v0, v2
	v_min_u32_e32 v0, v0, v2
	v_max_u32_e32 v2, v1, v3
	v_min_u32_e32 v1, v1, v3
	v_max_u32_e32 v31, v32, v39
	v_min_u32_e32 v32, v32, v39
	v_max_u32_e32 v39, v40, v38
	v_min_u32_e32 v38, v40, v38
	v_max_u32_e32 v40, v36, v34
	v_min_u32_e32 v34, v36, v34
	v_max_u32_e32 v36, v35, v33
	v_min_u32_e32 v33, v35, v33
	v_max_u32_e32 v35, v37, v29
	v_min_u32_e32 v29, v37, v29
	v_max_u32_e32 v37, v28, v30
	v_min_u32_e32 v28, v28, v30
	v_max_u32_e32 v30, v24, v26
	v_min_u32_e32 v24, v24, v26
	v_max_u32_e32 v26, v25, v27
	v_min_u32_e32 v25, v25, v27
	v_min_u32_e32 v3, v7, v15
	v_min_u32_e32 v17, v12, v13
	v_min_u32_e32 v18, v16, v11
	v_min_u32_e32 v19, v9, v8
	v_min_u32_e32 v20, v10, v14
	v_min_u32_e32 v21, v5, v4
	v_min_u32_e32 v22, v6, v2
	v_min_u32_e32 v23, v0, v1
	v_min_u32_e32 v27, v31, v39
	v_min_u32_e32 v41, v32, v38
	v_min_u32_e32 v42, v40, v36
	v_min_u32_e32 v43, v34, v33
	v_min_u32_e32 v44, v35, v37
	v_min_u32_e32 v45, v29, v28
	v_min_u32_e32 v46, v30, v26
	v_min_u32_e32 v47, v24, v25
	v_max3_u32 v7, v7, v15, v47
	v_max3_u32 v3, v3, v24, v25
	v_max3_u32 v12, v12, v13, v46
	v_max3_u32 v13, v17, v30, v26
	v_max3_u32 v11, v16, v11, v45
	v_max3_u32 v15, v18, v29, v28
	v_max3_u32 v8, v9, v8, v44
	v_max3_u32 v9, v19, v35, v37
	v_max3_u32 v10, v10, v14, v43
	v_max3_u32 v14, v20, v34, v33
	v_max3_u32 v4, v5, v4, v42
	v_max3_u32 v5, v21, v40, v36
	v_max3_u32 v2, v6, v2, v41
	v_max3_u32 v6, v22, v32, v38
	v_max3_u32 v0, v0, v1, v27
	v_max3_u32 v1, v23, v31, v39
	v_max_u32_e32 v16, v7, v10
	v_min_u32_e32 v7, v7, v10
	v_max_u32_e32 v10, v3, v14
	v_min_u32_e32 v3, v3, v14
	v_max_u32_e32 v14, v12, v4
	v_min_u32_e32 v4, v12, v4
	v_max_u32_e32 v12, v13, v5
	v_min_u32_e32 v5, v13, v5
	v_max_u32_e32 v13, v11, v2
	v_min_u32_e32 v2, v11, v2
	v_max_u32_e32 v11, v15, v6
	v_min_u32_e32 v6, v15, v6
	v_max_u32_e32 v15, v8, v0
	v_min_u32_e32 v0, v8, v0
	v_max_u32_e32 v8, v9, v1
	v_min_u32_e32 v1, v9, v1
	v_max_u32_e32 v9, v16, v13
	v_min_u32_e32 v13, v16, v13
	v_max_u32_e32 v16, v10, v11
	v_min_u32_e32 v10, v10, v11
	v_max_u32_e32 v11, v14, v15
	v_min_u32_e32 v14, v14, v15
	v_max_u32_e32 v15, v12, v8
	v_min_u32_e32 v8, v12, v8
	v_max_u32_e32 v12, v7, v2
	v_min_u32_e32 v2, v7, v2
	v_max_u32_e32 v7, v3, v6
	v_min_u32_e32 v3, v3, v6
	v_max_u32_e32 v6, v4, v0
	v_min_u32_e32 v0, v4, v0
	v_max_u32_e32 v4, v5, v1
	v_min_u32_e32 v1, v5, v1
	v_max_u32_e32 v5, v9, v11
	v_min_u32_e32 v9, v9, v11
	v_max_u32_e32 v11, v16, v15
	v_min_u32_e32 v15, v16, v15
	v_max_u32_e32 v16, v13, v14
	v_min_u32_e32 v13, v13, v14
	v_max_u32_e32 v14, v10, v8
	v_min_u32_e32 v8, v10, v8
	v_max_u32_e32 v10, v12, v6
	v_max_u32_e32 v17, v7, v4
	v_min_u32_e32 v18, v7, v4
	v_max_u32_e32 v19, v2, v0
	v_min_u32_e32 v20, v2, v0
	v_max_u32_e32 v21, v3, v1
	v_min_u32_e32 v22, v3, v1
	v_max_u32_e32 v0, v5, v11
	v_min_u32_e32 v1, v5, v11
	v_max_u32_e32 v4, v16, v14
	v_min_u32_e32 v5, v16, v14
	v_or_b32_e32 v16, s60, v128
	v_min_u32_e32 v12, v12, v6
	v_max_u32_e32 v2, v9, v15
	v_min_u32_e32 v3, v9, v15
	v_max_u32_e32 v6, v13, v8
	v_min_u32_e32 v7, v13, v8
	v_max_u32_e32 v8, v10, v17
	v_min_u32_e32 v9, v10, v17
	v_ashrrev_i32_e32 v17, 31, v16
	v_max_u32_e32 v10, v12, v18
	v_min_u32_e32 v11, v12, v18
	v_lshlrev_b64 v[16:17], 10, v[16:17]
	v_lshlrev_b32_e32 v18, 4, v130
	v_max_u32_e32 v12, v19, v21
	v_min_u32_e32 v13, v19, v21
	v_lshl_add_u64 v[16:17], s[12:13], 0, v[16:17]
	v_ashrrev_i32_e32 v19, 31, v18
	v_lshl_add_u64 v[16:17], v[18:19], 2, v[16:17]
	v_max_u32_e32 v14, v20, v22
	v_min_u32_e32 v15, v20, v22
	v_and_b32_e32 v238, 3, v128
	v_lshl_add_u32 v239, v128, 8, v131
	v_lshl_add_u32 v239, v238, 6, v239
	ds_write_b128 v239, v[0:3]
	ds_write_b128 v239, v[4:7] offset:16
	ds_write_b128 v239, v[8:11] offset:32
	ds_write_b128 v239, v[12:15] offset:48
	v_bfe_u32 v242, v128, 2, 4
	v_and_or_b32 v242, v128, 64, v242
	v_and_b32_e32 v243, 3, v242
	v_lshlrev_b32_e32 v243, 6, v243
	v_lshl_add_u32 v243, v238, 4, v243
	v_lshl_add_u32 v243, v242, 8, v243
	v_add_u32_e32 v243, v131, v243
	ds_read_b128 v[20:23], v243
	ds_read_b128 v[24:27], v243 offset:4096
	ds_read_b128 v[28:31], v243 offset:8192
	ds_read_b128 v[32:35], v243 offset:12288
	v_or_b32_e32 v244, s60, v242
	v_ashrrev_i32_e32 v245, 31, v244
	v_lshlrev_b64 v[244:245], 10, v[244:245]
	v_lshl_add_u64 v[244:245], s[12:13], 0, v[244:245]
	v_lshl_add_u64 v[244:245], v[18:19], 2, v[244:245]
	v_lshlrev_b32_e32 v246, 4, v238
	v_mov_b32_e32 v247, 0
	v_lshl_add_u64 v[244:245], v[244:245], 0, v[246:247]
	v_mov_b32_e32 v246, 0x4000
	s_waitcnt lgkmcnt(3)
	global_store_dwordx4 v[244:245], v[20:23], off
	v_lshl_add_u64 v[244:245], v[244:245], 0, v[246:247]
	s_waitcnt lgkmcnt(2)
	global_store_dwordx4 v[244:245], v[24:27], off
	v_lshl_add_u64 v[244:245], v[244:245], 0, v[246:247]
	s_waitcnt lgkmcnt(1)
	global_store_dwordx4 v[244:245], v[28:31], off
	v_lshl_add_u64 v[244:245], v[244:245], 0, v[246:247]
	s_waitcnt lgkmcnt(0)
	global_store_dwordx4 v[244:245], v[32:35], off
.LBB0_867:
	s_or_b64 exec, exec, s[62:63]
	v_mov_b32_e32 v0, v176
	s_barrier
	v_bfe_u32 v4, v127, 16, 1
	v_and_b32_e32 v1, 15, v0
	v_lshrrev_b32_e32 v2, 1, v0
	v_and_or_b32 v2, v2, s81, v1
	v_ashrrev_i32_e32 v1, 2, v0
	v_lshrrev_b32_e32 v0, 2, v0
	v_and_b32_e32 v0, 12, v0
	v_and_or_b32 v3, v1, s82, v0
	v_bfe_u32 v0, v124, 16, 1
	v_add3_u32 v0, v124, v0, s83
	v_bfe_u32 v1, v125, 16, 1
	v_mul_u32_u24_e32 v2, 0x110, v2
	v_lshrrev_b32_e32 v0, 16, v0
	v_add3_u32 v1, v125, v1, s83
	v_lshl_add_u32 v6, v3, 1, v2
	v_bfe_u32 v2, v120, 16, 1
	v_and_or_b32 v0, v1, s84, v0
	v_bfe_u32 v1, v126, 16, 1
	v_add3_u32 v2, v120, v2, s83
	v_bfe_u32 v3, v121, 16, 1
	v_add3_u32 v1, v126, v1, s83
	v_lshrrev_b32_e32 v2, 16, v2
	v_add3_u32 v3, v121, v3, s83
	v_lshrrev_b32_e32 v1, 16, v1
	v_add3_u32 v4, v127, v4, s83
	v_and_or_b32 v2, v3, s84, v2
	v_bfe_u32 v3, v122, 16, 1
	v_and_or_b32 v1, v4, s84, v1
	v_add3_u32 v3, v122, v3, s83
	v_bfe_u32 v4, v123, 16, 1
	v_lshrrev_b32_e32 v3, 16, v3
	v_add3_u32 v4, v123, v4, s83
	v_and_or_b32 v3, v4, s84, v3
	v_bfe_u32 v4, v116, 16, 1
	v_add3_u32 v4, v116, v4, s83
	v_bfe_u32 v5, v117, 16, 1
	v_lshrrev_b32_e32 v4, 16, v4
	v_add3_u32 v5, v117, v5, s83
	v_and_or_b32 v4, v5, s84, v4
	v_bfe_u32 v5, v118, 16, 1
	v_add3_u32 v5, v118, v5, s83
	v_bfe_u32 v7, v119, 16, 1
	v_lshrrev_b32_e32 v5, 16, v5
	v_add3_u32 v7, v119, v7, s83
	v_and_or_b32 v5, v7, s84, v5
	v_add_u32_e32 v7, 0x8000, v6
	ds_write2_b64 v7, v[0:1], v[4:5] offset1:4
	v_bfe_u32 v0, v112, 16, 1
	v_add3_u32 v0, v112, v0, s83
	v_bfe_u32 v1, v113, 16, 1
	v_lshrrev_b32_e32 v0, 16, v0
	v_add3_u32 v1, v113, v1, s83
	v_and_or_b32 v0, v1, s84, v0
	v_bfe_u32 v1, v114, 16, 1
	v_add3_u32 v1, v114, v1, s83
	v_bfe_u32 v4, v115, 16, 1
	v_lshrrev_b32_e32 v1, 16, v1
	v_add3_u32 v4, v115, v4, s83
	v_and_or_b32 v1, v4, s84, v1
	v_add_u32_e32 v8, 0x9000, v6
	ds_write2_b64 v8, v[2:3], v[0:1] offset0:32 offset1:36
	v_bfe_u32 v0, v108, 16, 1
	v_add3_u32 v0, v108, v0, s83
	v_bfe_u32 v1, v109, 16, 1
	v_lshrrev_b32_e32 v0, 16, v0
	v_add3_u32 v1, v109, v1, s83
	v_and_or_b32 v0, v1, s84, v0
	v_bfe_u32 v1, v110, 16, 1
	v_add3_u32 v1, v110, v1, s83
	v_bfe_u32 v2, v111, 16, 1
	v_lshrrev_b32_e32 v1, 16, v1
	v_add3_u32 v2, v111, v2, s83
	v_and_or_b32 v1, v2, s84, v1
	v_bfe_u32 v2, v104, 16, 1
	v_add3_u32 v2, v104, v2, s83
	v_bfe_u32 v3, v105, 16, 1
	v_lshrrev_b32_e32 v2, 16, v2
	v_add3_u32 v3, v105, v3, s83
	v_and_or_b32 v2, v3, s84, v2
	v_bfe_u32 v3, v106, 16, 1
	v_add3_u32 v3, v106, v3, s83
	v_bfe_u32 v4, v107, 16, 1
	v_lshrrev_b32_e32 v3, 16, v3
	v_add3_u32 v4, v107, v4, s83
	v_and_or_b32 v3, v4, s84, v3
	v_bfe_u32 v4, v96, 16, 1
	v_add3_u32 v4, v96, v4, s83
	v_bfe_u32 v5, v97, 16, 1
	v_lshrrev_b32_e32 v4, 16, v4
	v_add3_u32 v5, v97, v5, s83
	v_and_or_b32 v4, v5, s84, v4
	v_bfe_u32 v5, v98, 16, 1
	v_add3_u32 v5, v98, v5, s83
	v_bfe_u32 v9, v99, 16, 1
	v_lshrrev_b32_e32 v5, 16, v5
	v_add3_u32 v9, v99, v9, s83
	v_and_or_b32 v5, v9, s84, v5
	ds_write2_b64 v7, v[0:1], v[4:5] offset0:8 offset1:12
	v_bfe_u32 v0, v88, 16, 1
	v_add3_u32 v0, v88, v0, s83
	v_bfe_u32 v1, v89, 16, 1
	v_lshrrev_b32_e32 v0, 16, v0
	v_add3_u32 v1, v89, v1, s83
	v_and_or_b32 v0, v1, s84, v0
	v_bfe_u32 v1, v90, 16, 1
	v_add3_u32 v1, v90, v1, s83
	v_bfe_u32 v4, v91, 16, 1
	v_lshrrev_b32_e32 v1, 16, v1
	v_add3_u32 v4, v91, v4, s83
	v_and_or_b32 v1, v4, s84, v1
	ds_write2_b64 v8, v[2:3], v[0:1] offset0:40 offset1:44
	v_bfe_u32 v0, v100, 16, 1
	v_add3_u32 v0, v100, v0, s83
	v_bfe_u32 v1, v101, 16, 1
	v_lshrrev_b32_e32 v0, 16, v0
	v_add3_u32 v1, v101, v1, s83
	v_and_or_b32 v0, v1, s84, v0
	v_bfe_u32 v1, v102, 16, 1
	v_add3_u32 v1, v102, v1, s83
	v_bfe_u32 v2, v103, 16, 1
	v_lshrrev_b32_e32 v1, 16, v1
	v_add3_u32 v2, v103, v2, s83
	v_and_or_b32 v1, v2, s84, v1
	v_add_u32_e32 v2, 0x1a000, v6
	ds_write_b64 v2, v[0:1]
	v_bfe_u32 v0, v92, 16, 1
	v_add3_u32 v0, v92, v0, s83
	v_bfe_u32 v1, v93, 16, 1
	v_lshrrev_b32_e32 v0, 16, v0
	v_add3_u32 v1, v93, v1, s83
	v_and_or_b32 v0, v1, s84, v0
	v_bfe_u32 v1, v94, 16, 1
	v_add3_u32 v1, v94, v1, s83
	v_bfe_u32 v3, v95, 16, 1
	v_lshrrev_b32_e32 v1, 16, v1
	v_add3_u32 v3, v95, v3, s83
	v_and_or_b32 v1, v3, s84, v1
	ds_write_b64 v2, v[0:1] offset:4352
	v_bfe_u32 v0, v84, 16, 1
	v_add3_u32 v0, v84, v0, s83
	v_bfe_u32 v1, v85, 16, 1
	v_lshrrev_b32_e32 v0, 16, v0
	v_add3_u32 v1, v85, v1, s83
	v_and_or_b32 v0, v1, s84, v0
	v_bfe_u32 v1, v86, 16, 1
	v_add3_u32 v1, v86, v1, s83
	v_bfe_u32 v2, v87, 16, 1
	v_lshrrev_b32_e32 v1, 16, v1
	v_add3_u32 v2, v87, v2, s83
	v_and_or_b32 v1, v2, s84, v1
	v_add_u32_e32 v2, 0x1a020, v6
	ds_write_b64 v2, v[0:1]
	v_bfe_u32 v0, v80, 16, 1
	v_add3_u32 v0, v80, v0, s83
	v_bfe_u32 v1, v81, 16, 1
	v_lshrrev_b32_e32 v0, 16, v0
	v_add3_u32 v1, v81, v1, s83
	v_and_or_b32 v0, v1, s84, v0
	v_bfe_u32 v1, v82, 16, 1
	v_add3_u32 v1, v82, v1, s83
	v_bfe_u32 v3, v83, 16, 1
	v_lshrrev_b32_e32 v1, 16, v1
	v_add3_u32 v3, v83, v3, s83
	v_and_or_b32 v1, v3, s84, v1
	ds_write_b64 v2, v[0:1] offset:4352
	v_bfe_u32 v0, v76, 16, 1
	v_add3_u32 v0, v76, v0, s83
	v_bfe_u32 v1, v77, 16, 1
	v_lshrrev_b32_e32 v0, 16, v0
	v_add3_u32 v1, v77, v1, s83
	v_and_or_b32 v0, v1, s84, v0
	v_bfe_u32 v1, v78, 16, 1
	v_add3_u32 v1, v78, v1, s83
	v_bfe_u32 v2, v79, 16, 1
	v_lshrrev_b32_e32 v1, 16, v1
	v_add3_u32 v2, v79, v2, s83
	v_and_or_b32 v1, v2, s84, v1
	v_add_u32_e32 v2, 0x1a040, v6
	ds_write_b64 v2, v[0:1]
	v_bfe_u32 v0, v72, 16, 1
	v_add3_u32 v0, v72, v0, s83
	v_bfe_u32 v1, v73, 16, 1
	v_lshrrev_b32_e32 v0, 16, v0
	v_add3_u32 v1, v73, v1, s83
	v_and_or_b32 v0, v1, s84, v0
	v_bfe_u32 v1, v74, 16, 1
	v_add3_u32 v1, v74, v1, s83
	v_bfe_u32 v3, v75, 16, 1
	v_lshrrev_b32_e32 v1, 16, v1
	v_add3_u32 v3, v75, v3, s83
	v_and_or_b32 v1, v3, s84, v1
	ds_write_b64 v2, v[0:1] offset:4352
	v_bfe_u32 v0, v68, 16, 1
	v_add3_u32 v0, v68, v0, s83
	v_bfe_u32 v1, v69, 16, 1
	v_lshrrev_b32_e32 v0, 16, v0
	v_add3_u32 v1, v69, v1, s83
	v_and_or_b32 v0, v1, s84, v0
	v_bfe_u32 v1, v70, 16, 1
	v_add3_u32 v1, v70, v1, s83
	v_bfe_u32 v2, v71, 16, 1
	v_lshrrev_b32_e32 v1, 16, v1
	v_add3_u32 v2, v71, v2, s83
	v_and_or_b32 v1, v2, s84, v1
	v_add_u32_e32 v2, 0x1a060, v6
	ds_write_b64 v2, v[0:1]
	v_bfe_u32 v0, v64, 16, 1
	v_add3_u32 v0, v64, v0, s83
	v_bfe_u32 v1, v65, 16, 1
	v_lshrrev_b32_e32 v0, 16, v0
	v_add3_u32 v1, v65, v1, s83
	v_and_or_b32 v0, v1, s84, v0
	v_bfe_u32 v1, v66, 16, 1
	v_add3_u32 v1, v66, v1, s83
	v_bfe_u32 v3, v67, 16, 1
	v_lshrrev_b32_e32 v1, 16, v1
	v_add3_u32 v3, v67, v3, s83
	v_and_or_b32 v1, v3, s84, v1
	v_mov_b32_e32 v71, v176
	ds_write_b64 v2, v[0:1] offset:4352
	s_nop 0
	v_ashrrev_i32_e32 v67, 8, v71
	v_add_u32_e32 v64, s59, v67
	v_bfe_u32 v69, v71, 7, 1
	v_ashrrev_i32_e32 v65, 31, v64
	v_and_b32_e32 v2, 31, v71
	v_lshlrev_b64 v[0:1], 7, v[64:65]
	v_lshlrev_b32_e32 v70, 6, v69
	v_or3_b32 v0, v0, v70, v2
	v_bfe_u32 v68, v71, 5, 1
	v_lshlrev_b64 v[0:1], 8, v[0:1]
	v_lshl_add_u64 v[0:1], s[4:5], 0, v[0:1]
	v_lshlrev_b32_e32 v128, 4, v68
	v_lshl_add_u64 v[8:9], v[0:1], 0, v[128:129]
	global_load_dwordx4 v[0:3], v[8:9], off
	v_add_co_u32_e32 v10, vcc, s76, v8
	v_mul_i32_i24_e32 v66, 0x12000, v67
	s_nop 0
	v_addc_co_u32_e32 v11, vcc, 0, v9, vcc
	global_load_dwordx4 v[4:7], v[10:11], off
	global_load_dwordx4 v[72:75], v[8:9], off offset:32
	global_load_dwordx4 v[76:79], v[10:11], off offset:32
	global_load_dwordx4 v[80:83], v[8:9], off offset:64
	global_load_dwordx4 v[84:87], v[8:9], off offset:96
	global_load_dwordx4 v[88:91], v[10:11], off offset:64
	global_load_dwordx4 v[92:95], v[10:11], off offset:96
	global_load_dwordx4 v[96:99], v[8:9], off offset:128
	global_load_dwordx4 v[100:103], v[8:9], off offset:160
	global_load_dwordx4 v[104:107], v[10:11], off offset:128
	global_load_dwordx4 v[108:111], v[10:11], off offset:160
	global_load_dwordx4 v[112:115], v[8:9], off offset:192
	global_load_dwordx4 v[116:119], v[8:9], off offset:224
	global_load_dwordx4 v[120:123], v[10:11], off offset:192
	global_load_dwordx4 v[124:127], v[10:11], off offset:224
	v_and_b32_e32 v8, 0x5f, v71
	v_mul_u32_u24_e32 v8, 0x110, v8
	v_add3_u32 v65, v66, v8, v128
	s_waitcnt lgkmcnt(0)
	s_barrier
	ds_read_b128 v[8:11], v65 offset:32768
	ds_read_b128 v[130:133], v65 offset:32800
	s_waitcnt vmcnt(15) lgkmcnt(1)
	v_mfma_f32_32x32x16_bf16 v[32:47], v[0:3], v[8:11], 0
	ds_read_b128 v[12:15], v65 offset:41472
	ds_read_b128 v[136:139], v65 offset:41504
	v_lshlrev_b32_e32 v69, 1, v69
	s_waitcnt vmcnt(14)
	v_mfma_f32_32x32x16_bf16 v[48:63], v[4:7], v[8:11], 0
	s_waitcnt lgkmcnt(1)
	v_mfma_f32_32x32x16_bf16 v[16:31], v[0:3], v[12:15], 0
	v_mfma_f32_32x32x16_bf16 v[0:15], v[4:7], v[12:15], 0
	s_waitcnt vmcnt(13)
	v_mfma_f32_32x32x16_bf16 v[32:47], v[72:75], v[130:133], v[32:47]
	s_waitcnt vmcnt(12)
	v_mfma_f32_32x32x16_bf16 v[48:63], v[76:79], v[130:133], v[48:63]
	s_waitcnt lgkmcnt(0)
	v_mfma_f32_32x32x16_bf16 v[16:31], v[72:75], v[136:139], v[16:31]
	v_mfma_f32_32x32x16_bf16 v[0:15], v[76:79], v[136:139], v[0:15]
	ds_read_b128 v[72:75], v65 offset:32832
	ds_read_b128 v[76:79], v65 offset:32864
	ds_read_b128 v[130:133], v65 offset:41536
	ds_read_b128 v[136:139], v65 offset:41568
	s_waitcnt vmcnt(11) lgkmcnt(3)
	v_mfma_f32_32x32x16_bf16 v[32:47], v[80:83], v[72:75], v[32:47]
	s_waitcnt vmcnt(9)
	v_mfma_f32_32x32x16_bf16 v[48:63], v[88:91], v[72:75], v[48:63]
	s_waitcnt lgkmcnt(1)
	v_mfma_f32_32x32x16_bf16 v[16:31], v[80:83], v[130:133], v[16:31]
	v_mfma_f32_32x32x16_bf16 v[0:15], v[88:91], v[130:133], v[0:15]
	v_mfma_f32_32x32x16_bf16 v[32:47], v[84:87], v[76:79], v[32:47]
	s_waitcnt vmcnt(8)
	v_mfma_f32_32x32x16_bf16 v[48:63], v[92:95], v[76:79], v[48:63]
	ds_read_b128 v[72:75], v65 offset:32896
	ds_read_b128 v[76:79], v65 offset:32928
	s_waitcnt lgkmcnt(2)
	v_mfma_f32_32x32x16_bf16 v[16:31], v[84:87], v[136:139], v[16:31]
	ds_read_b128 v[80:83], v65 offset:41600
	ds_read_b128 v[84:87], v65 offset:41632
	v_mfma_f32_32x32x16_bf16 v[0:15], v[92:95], v[136:139], v[0:15]
	s_waitcnt vmcnt(7) lgkmcnt(3)
	v_mfma_f32_32x32x16_bf16 v[32:47], v[96:99], v[72:75], v[32:47]
	s_waitcnt vmcnt(5)
	v_mfma_f32_32x32x16_bf16 v[48:63], v[104:107], v[72:75], v[48:63]
	s_waitcnt lgkmcnt(1)
	v_mfma_f32_32x32x16_bf16 v[16:31], v[96:99], v[80:83], v[16:31]
	v_mfma_f32_32x32x16_bf16 v[0:15], v[104:107], v[80:83], v[0:15]
	v_mfma_f32_32x32x16_bf16 v[32:47], v[100:103], v[76:79], v[32:47]
	s_waitcnt vmcnt(4)
	v_mfma_f32_32x32x16_bf16 v[48:63], v[108:111], v[76:79], v[48:63]
	ds_read_b128 v[72:75], v65 offset:32960
	ds_read_b128 v[76:79], v65 offset:32992
	s_waitcnt lgkmcnt(2)
	v_mfma_f32_32x32x16_bf16 v[16:31], v[100:103], v[84:87], v[16:31]
	v_mfma_f32_32x32x16_bf16 v[0:15], v[108:111], v[84:87], v[0:15]
	ds_read_b128 v[80:83], v65 offset:41664
	ds_read_b128 v[84:87], v65 offset:41696
	v_and_b32_e32 v65, 0xff, v71
	v_cmp_gt_u32_e32 vcc, s77, v65
	s_waitcnt vmcnt(3) lgkmcnt(3)
	v_mfma_f32_32x32x16_bf16 v[32:47], v[112:115], v[72:75], v[32:47]
	s_waitcnt vmcnt(1)
	v_mfma_f32_32x32x16_bf16 v[48:63], v[120:123], v[72:75], v[48:63]
	v_lshlrev_b32_e32 v72, 2, v68
	s_waitcnt lgkmcnt(1)
	v_mfma_f32_32x32x16_bf16 v[16:31], v[112:115], v[80:83], v[16:31]
	v_mfma_f32_32x32x16_bf16 v[0:15], v[120:123], v[80:83], v[0:15]
	v_mfma_f32_32x32x16_bf16 v[32:47], v[116:119], v[76:79], v[32:47]
	s_waitcnt vmcnt(0)
	v_mfma_f32_32x32x16_bf16 v[48:63], v[124:127], v[76:79], v[48:63]
	s_nop 9
	v_ashrrev_i32_e32 v73, 31, v32
	v_ashrrev_i32_e32 v74, 31, v33
	v_ashrrev_i32_e32 v75, 31, v34
	v_ashrrev_i32_e32 v76, 31, v35
	v_ashrrev_i32_e32 v77, 31, v36
	v_ashrrev_i32_e32 v78, 31, v37
	v_ashrrev_i32_e32 v79, 31, v38
	s_waitcnt lgkmcnt(0)
	v_mfma_f32_32x32x16_bf16 v[16:31], v[116:119], v[84:87], v[16:31]
	v_ashrrev_i32_e32 v80, 31, v39
	v_ashrrev_i32_e32 v81, 31, v40
	v_ashrrev_i32_e32 v82, 31, v41
	v_ashrrev_i32_e32 v83, 31, v42
	v_ashrrev_i32_e32 v88, 31, v47
	v_or_b32_e32 v73, 0x80000000, v73
	v_or_b32_e32 v74, 0x80000000, v74
	v_mfma_f32_32x32x16_bf16 v[0:15], v[124:127], v[84:87], v[0:15]
	v_ashrrev_i32_e32 v84, 31, v43
	v_ashrrev_i32_e32 v85, 31, v44
	v_ashrrev_i32_e32 v86, 31, v45
	v_ashrrev_i32_e32 v87, 31, v46
	v_or_b32_e32 v75, 0x80000000, v75
	v_or_b32_e32 v76, 0x80000000, v76
	v_or_b32_e32 v77, 0x80000000, v77
	v_or_b32_e32 v78, 0x80000000, v78
	v_or_b32_e32 v79, 0x80000000, v79
	v_or_b32_e32 v80, 0x80000000, v80
	v_or_b32_e32 v81, 0x80000000, v81
	v_or_b32_e32 v82, 0x80000000, v82
	v_or_b32_e32 v83, 0x80000000, v83
	v_or_b32_e32 v84, 0x80000000, v84
	v_or_b32_e32 v85, 0x80000000, v85
	v_or_b32_e32 v86, 0x80000000, v86
	v_or_b32_e32 v87, 0x80000000, v87
	v_or_b32_e32 v88, 0x80000000, v88
	v_bitop3_b32 v32, v73, s86, v32 bitop3:0x48
	v_ashrrev_i32_e32 v73, 31, v48
	v_bitop3_b32 v33, v74, s86, v33 bitop3:0x48
	v_ashrrev_i32_e32 v74, 31, v49
	v_bitop3_b32 v34, v75, s86, v34 bitop3:0x48
	v_ashrrev_i32_e32 v75, 31, v50
	v_bitop3_b32 v35, v76, s86, v35 bitop3:0x48
	v_ashrrev_i32_e32 v76, 31, v51
	v_bitop3_b32 v36, v77, s86, v36 bitop3:0x48
	v_ashrrev_i32_e32 v77, 31, v52
	v_bitop3_b32 v37, v78, s86, v37 bitop3:0x48
	v_ashrrev_i32_e32 v78, 31, v53
	v_bitop3_b32 v38, v79, s86, v38 bitop3:0x48
	v_ashrrev_i32_e32 v79, 31, v54
	v_bitop3_b32 v39, v80, s86, v39 bitop3:0x48
	v_ashrrev_i32_e32 v80, 31, v55
	v_bitop3_b32 v40, v81, s86, v40 bitop3:0x48
	v_ashrrev_i32_e32 v81, 31, v56
	v_bitop3_b32 v41, v82, s86, v41 bitop3:0x48
	v_ashrrev_i32_e32 v82, 31, v57
	v_bitop3_b32 v42, v83, s86, v42 bitop3:0x48
	v_ashrrev_i32_e32 v83, 31, v58
	v_bitop3_b32 v43, v84, s86, v43 bitop3:0x48
	v_ashrrev_i32_e32 v84, 31, v59
	v_bitop3_b32 v44, v85, s86, v44 bitop3:0x48
	v_ashrrev_i32_e32 v85, 31, v60
	v_bitop3_b32 v45, v86, s86, v45 bitop3:0x48
	v_ashrrev_i32_e32 v86, 31, v61
	v_bitop3_b32 v46, v87, s86, v46 bitop3:0x48
	v_ashrrev_i32_e32 v87, 31, v62
	v_bitop3_b32 v47, v88, s86, v47 bitop3:0x48
	v_ashrrev_i32_e32 v88, 31, v63
	v_bitop3_b32 v48, v73, v48, s85 bitop3:0x36
	v_or_b32_e32 v73, 1, v72
	v_bitop3_b32 v49, v74, v49, s85 bitop3:0x36
	v_or_b32_e32 v74, 2, v72
	v_bitop3_b32 v50, v75, v50, s85 bitop3:0x36
	v_or_b32_e32 v75, 3, v72
	v_bitop3_b32 v51, v76, v51, s85 bitop3:0x36
	v_or_b32_e32 v76, 8, v72
	v_bitop3_b32 v52, v77, v52, s85 bitop3:0x36
	v_or_b32_e32 v77, 9, v72
	v_bitop3_b32 v53, v78, v53, s85 bitop3:0x36
	v_or_b32_e32 v78, 10, v72
	v_bitop3_b32 v54, v79, v54, s85 bitop3:0x36
	v_or_b32_e32 v79, 11, v72
	v_bitop3_b32 v55, v80, v55, s85 bitop3:0x36
	v_or_b32_e32 v80, 16, v72
	v_bitop3_b32 v56, v81, v56, s85 bitop3:0x36
	v_or_b32_e32 v81, 17, v72
	v_bitop3_b32 v57, v82, v57, s85 bitop3:0x36
	v_or_b32_e32 v82, 18, v72
	v_bitop3_b32 v58, v83, v58, s85 bitop3:0x36
	v_or_b32_e32 v83, 19, v72
	v_bitop3_b32 v59, v84, v59, s85 bitop3:0x36
	v_or_b32_e32 v84, 24, v72
	v_bitop3_b32 v60, v85, v60, s85 bitop3:0x36
	v_or_b32_e32 v85, 25, v72
	v_bitop3_b32 v61, v86, v61, s85 bitop3:0x36
	v_or_b32_e32 v86, 26, v72
	v_bitop3_b32 v62, v87, v62, s85 bitop3:0x36
	v_or_b32_e32 v87, 27, v72
	v_bitop3_b32 v63, v88, v63, s85 bitop3:0x36
	v_and_or_b32 v48, v48, s86, v72
	v_and_or_b32 v49, v49, s86, v73
	v_and_or_b32 v50, v50, s86, v74
	v_and_or_b32 v51, v51, s86, v75
	v_and_or_b32 v52, v52, s86, v76
	v_and_or_b32 v53, v53, s86, v77
	v_and_or_b32 v54, v54, s86, v78
	v_and_or_b32 v55, v55, s86, v79
	v_and_or_b32 v56, v56, s86, v80
	v_and_or_b32 v57, v57, s86, v81
	v_and_or_b32 v58, v58, s86, v82
	v_and_or_b32 v59, v59, s86, v83
	v_and_or_b32 v60, v60, s86, v84
	v_and_or_b32 v61, v61, s86, v85
	v_and_or_b32 v62, v62, s86, v86
	v_and_or_b32 v63, v63, s86, v87
	v_or3_b32 v32, v70, v32, v72
	v_or3_b32 v48, v48, v70, 32
	v_or3_b32 v33, v70, v33, v73
	v_or3_b32 v49, v49, v70, 32
	v_or3_b32 v34, v70, v34, v74
	v_or3_b32 v50, v50, v70, 32
	v_or3_b32 v35, v70, v35, v75
	v_or3_b32 v51, v51, v70, 32
	v_or3_b32 v36, v70, v36, v76
	v_or3_b32 v52, v52, v70, 32
	v_or3_b32 v37, v70, v37, v77
	v_or3_b32 v53, v53, v70, 32
	v_or3_b32 v38, v70, v38, v78
	v_or3_b32 v54, v54, v70, 32
	v_or3_b32 v39, v70, v39, v79
	v_or3_b32 v55, v55, v70, 32
	v_or3_b32 v40, v70, v40, v80
	v_or3_b32 v56, v56, v70, 32
	v_or3_b32 v41, v70, v41, v81
	v_or3_b32 v57, v57, v70, 32
	v_or3_b32 v42, v70, v42, v82
	v_or3_b32 v58, v58, v70, 32
	v_or3_b32 v43, v70, v43, v83
	v_or3_b32 v59, v59, v70, 32
	v_or3_b32 v44, v70, v44, v84
	v_or3_b32 v60, v60, v70, 32
	v_or3_b32 v45, v70, v45, v85
	v_or3_b32 v61, v61, v70, 32
	v_or3_b32 v46, v70, v46, v86
	v_or3_b32 v62, v62, v70, 32
	v_or3_b32 v47, v70, v47, v87
	v_or3_b32 v63, v63, v70, 32
	v_max_u32_e32 v88, v32, v45
	v_min_u32_e32 v32, v32, v45
	v_max_u32_e32 v45, v33, v44
	v_min_u32_e32 v33, v33, v44
	v_max_u32_e32 v44, v34, v47
	v_min_u32_e32 v34, v34, v47
	v_max_u32_e32 v47, v35, v46
	v_min_u32_e32 v35, v35, v46
	v_max_u32_e32 v46, v36, v40
	v_min_u32_e32 v36, v36, v40
	v_max_u32_e32 v40, v37, v38
	v_min_u32_e32 v37, v37, v38
	v_max_u32_e32 v38, v39, v43
	v_min_u32_e32 v39, v39, v43
	v_max_u32_e32 v43, v41, v42
	v_min_u32_e32 v41, v41, v42
	v_max_u32_e32 v96, v48, v61
	v_min_u32_e32 v48, v48, v61
	v_max_u32_e32 v61, v49, v60
	v_min_u32_e32 v49, v49, v60
	v_max_u32_e32 v60, v50, v63
	v_min_u32_e32 v50, v50, v63
	v_max_u32_e32 v63, v51, v62
	v_min_u32_e32 v51, v51, v62
	v_max_u32_e32 v62, v52, v56
	v_min_u32_e32 v52, v52, v56
	v_max_u32_e32 v56, v53, v54
	v_min_u32_e32 v53, v53, v54
	v_max_u32_e32 v54, v55, v59
	v_min_u32_e32 v55, v55, v59
	v_max_u32_e32 v59, v57, v58
	v_min_u32_e32 v57, v57, v58
	v_max_u32_e32 v42, v88, v40
	v_min_u32_e32 v40, v88, v40
	v_max_u32_e32 v88, v45, v38
	v_min_u32_e32 v38, v45, v38
	v_max_u32_e32 v45, v44, v43
	v_min_u32_e32 v43, v44, v43
	v_max_u32_e32 v44, v47, v46
	v_min_u32_e32 v46, v47, v46
	v_max_u32_e32 v47, v37, v32
	v_min_u32_e32 v32, v37, v32
	v_max_u32_e32 v37, v36, v35
	v_min_u32_e32 v35, v36, v35
	v_max_u32_e32 v36, v41, v34
	v_min_u32_e32 v34, v41, v34
	v_max_u32_e32 v41, v39, v33
	v_min_u32_e32 v33, v39, v33
	v_max_u32_e32 v58, v96, v56
	v_min_u32_e32 v56, v96, v56
	v_max_u32_e32 v96, v61, v54
	v_min_u32_e32 v54, v61, v54
	v_max_u32_e32 v61, v60, v59
	v_min_u32_e32 v59, v60, v59
	v_max_u32_e32 v60, v63, v62
	v_min_u32_e32 v62, v63, v62
	v_max_u32_e32 v63, v53, v48
	v_min_u32_e32 v48, v53, v48
	v_max_u32_e32 v53, v52, v51
	v_min_u32_e32 v51, v52, v51
	v_max_u32_e32 v52, v57, v50
	v_min_u32_e32 v50, v57, v50
	v_max_u32_e32 v57, v55, v49
	v_min_u32_e32 v49, v55, v49
	v_max_u32_e32 v39, v42, v88
	v_min_u32_e32 v42, v42, v88
	v_max_u32_e32 v88, v45, v44
	v_min_u32_e32 v44, v45, v44
	v_max_u32_e32 v45, v46, v40
	v_min_u32_e32 v40, v46, v40
	v_max_u32_e32 v46, v47, v37
	v_min_u32_e32 v37, v47, v37
	v_max_u32_e32 v47, v38, v43
	v_min_u32_e32 v38, v38, v43
	v_max_u32_e32 v43, v36, v41
	v_min_u32_e32 v36, v36, v41
	v_max_u32_e32 v41, v33, v32
	v_min_u32_e32 v32, v33, v32
	v_max_u32_e32 v33, v35, v34
	v_min_u32_e32 v34, v35, v34
	v_max_u32_e32 v55, v58, v96
	v_min_u32_e32 v58, v58, v96
	v_max_u32_e32 v96, v61, v60
	v_min_u32_e32 v60, v61, v60
	v_max_u32_e32 v61, v62, v56
	v_min_u32_e32 v56, v62, v56
	v_max_u32_e32 v62, v63, v53
	v_min_u32_e32 v53, v63, v53
	v_max_u32_e32 v63, v54, v59
	v_min_u32_e32 v54, v54, v59
	v_max_u32_e32 v59, v52, v57
	v_min_u32_e32 v52, v52, v57
	v_max_u32_e32 v57, v49, v48
	v_min_u32_e32 v48, v49, v48
	v_max_u32_e32 v49, v51, v50
	v_min_u32_e32 v50, v51, v50
	v_min_u32_e32 v35, v39, v88
	v_max_u32_e32 v89, v42, v44
	v_min_u32_e32 v42, v42, v44
	v_max_u32_e32 v44, v45, v43
	v_min_u32_e32 v43, v45, v43
	v_max_u32_e32 v45, v40, v36
	v_min_u32_e32 v36, v40, v36
	v_max_u32_e32 v40, v46, v47
	v_min_u32_e32 v46, v46, v47
	v_max_u32_e32 v47, v37, v38
	v_min_u32_e32 v37, v37, v38
	v_max_u32_e32 v38, v41, v33
	v_min_u32_e32 v33, v41, v33
	v_max_u32_e32 v41, v32, v34
	v_min_u32_e32 v51, v55, v96
	v_max_u32_e32 v97, v58, v60
	v_min_u32_e32 v58, v58, v60
	v_max_u32_e32 v60, v61, v59
	v_min_u32_e32 v59, v61, v59
	v_max_u32_e32 v61, v56, v52
	v_min_u32_e32 v52, v56, v52
	v_max_u32_e32 v56, v62, v63
	v_min_u32_e32 v62, v62, v63
	v_max_u32_e32 v63, v53, v54
	v_min_u32_e32 v53, v53, v54
	v_max_u32_e32 v54, v57, v49
	v_min_u32_e32 v49, v57, v49
	v_max_u32_e32 v57, v48, v50
	v_min_u32_e32 v32, v32, v34
	v_max_u32_e32 v34, v89, v35
	v_min_u32_e32 v35, v89, v35
	v_max_u32_e32 v89, v42, v38
	v_min_u32_e32 v38, v42, v38
	v_max_u32_e32 v42, v44, v40
	v_min_u32_e32 v40, v44, v40
	v_max_u32_e32 v44, v45, v46
	v_min_u32_e32 v45, v45, v46
	v_max_u32_e32 v46, v47, v43
	v_min_u32_e32 v43, v47, v43
	v_max_u32_e32 v47, v37, v36
	v_min_u32_e32 v36, v37, v36
	v_max_u32_e32 v37, v41, v33
	v_min_u32_e32 v48, v48, v50
	v_max_u32_e32 v50, v97, v51
	v_min_u32_e32 v51, v97, v51
	v_max_u32_e32 v97, v58, v54
	v_min_u32_e32 v54, v58, v54
	v_max_u32_e32 v58, v60, v56
	v_min_u32_e32 v56, v60, v56
	v_max_u32_e32 v60, v61, v62
	v_min_u32_e32 v61, v61, v62
	v_max_u32_e32 v62, v63, v59
	v_min_u32_e32 v59, v63, v59
	v_max_u32_e32 v63, v53, v52
	v_min_u32_e32 v52, v53, v52
	v_max_u32_e32 v53, v57, v49
	v_min_u32_e32 v33, v41, v33
	v_max_u32_e32 v90, v35, v40
	v_min_u32_e32 v35, v35, v40
	v_max_u32_e32 v40, v44, v46
	v_min_u32_e32 v44, v44, v46
	v_max_u32_e32 v46, v45, v43
	v_min_u32_e32 v43, v45, v43
	v_max_u32_e32 v45, v47, v37
	v_min_u32_e32 v49, v57, v49
	v_max_u32_e32 v98, v51, v56
	v_min_u32_e32 v51, v51, v56
	v_max_u32_e32 v56, v60, v62
	v_min_u32_e32 v60, v60, v62
	v_max_u32_e32 v62, v61, v59
	v_min_u32_e32 v59, v61, v59
	v_max_u32_e32 v61, v63, v53
	v_min_u32_e32 v37, v47, v37
	v_max_u32_e32 v47, v36, v33
	v_max_u32_e32 v91, v89, v35
	v_min_u32_e32 v35, v89, v35
	v_max_u32_e32 v89, v45, v38
	v_min_u32_e32 v38, v45, v38
	v_min_u32_e32 v53, v63, v53
	v_max_u32_e32 v63, v52, v49
	v_max_u32_e32 v99, v97, v51
	v_min_u32_e32 v51, v97, v51
	v_max_u32_e32 v97, v61, v54
	v_min_u32_e32 v54, v61, v54
	v_min_u32_e32 v41, v34, v42
	v_max_u32_e32 v45, v47, v37
	v_min_u32_e32 v37, v47, v37
	v_max_u32_e32 v47, v91, v40
	v_min_u32_e32 v40, v91, v40
	v_max_u32_e32 v91, v35, v44
	v_min_u32_e32 v35, v35, v44
	v_max_u32_e32 v44, v46, v89
	v_min_u32_e32 v46, v46, v89
	v_max_u32_e32 v89, v43, v38
	v_min_u32_e32 v57, v50, v58
	v_max_u32_e32 v61, v63, v53
	v_min_u32_e32 v53, v63, v53
	v_max_u32_e32 v63, v99, v56
	v_min_u32_e32 v56, v99, v56
	v_max_u32_e32 v99, v51, v60
	v_min_u32_e32 v51, v51, v60
	v_max_u32_e32 v60, v62, v97
	v_min_u32_e32 v62, v62, v97
	v_max_u32_e32 v97, v59, v54
	v_min_u32_e32 v33, v36, v33
	v_min_u32_e32 v36, v90, v41
	v_min_u32_e32 v38, v43, v38
	v_min_u32_e32 v92, v40, v91
	v_max_u32_e32 v93, v44, v35
	v_min_u32_e32 v35, v44, v35
	v_max_u32_e32 v44, v46, v89
	v_min_u32_e32 v49, v52, v49
	v_min_u32_e32 v52, v98, v57
	v_min_u32_e32 v54, v59, v54
	v_min_u32_e32 v100, v56, v99
	v_max_u32_e32 v101, v60, v51
	v_min_u32_e32 v51, v60, v51
	v_max_u32_e32 v60, v62, v97
	v_min_u32_e32 v43, v47, v36
	v_min_u32_e32 v46, v46, v89
	v_min_u32_e32 v89, v45, v38
	v_min_u32_e32 v94, v92, v93
	v_min_u32_e32 v95, v35, v44
	v_min_u32_e32 v59, v63, v52
	v_min_u32_e32 v62, v62, v97
	v_min_u32_e32 v97, v61, v54
	v_min_u32_e32 v102, v100, v101
	v_min_u32_e32 v103, v51, v60
	v_max3_u32 v39, v39, v88, v48
	v_max3_u32 v34, v34, v42, v49
	v_max3_u32 v41, v90, v41, v53
	v_max3_u32 v36, v47, v36, v97
	v_max3_u32 v42, v43, v61, v54
	v_max3_u32 v40, v40, v91, v62
	v_max3_u32 v43, v92, v93, v103
	v_max3_u32 v47, v94, v51, v60
	v_max3_u32 v35, v35, v44, v102
	v_max3_u32 v44, v95, v100, v101
	v_max3_u32 v46, v46, v56, v99
	v_max3_u32 v38, v45, v38, v59
	v_max3_u32 v45, v89, v63, v52
	v_max3_u32 v37, v37, v98, v57
	v_max3_u32 v33, v33, v50, v58
	v_max3_u32 v32, v32, v55, v96
	v_max_u32_e32 v48, v39, v35
	v_min_u32_e32 v35, v39, v35
	v_max_u32_e32 v39, v34, v44
	v_min_u32_e32 v34, v34, v44
	v_max_u32_e32 v44, v41, v46
	v_min_u32_e32 v41, v41, v46
	v_max_u32_e32 v46, v36, v38
	v_min_u32_e32 v36, v36, v38
	v_max_u32_e32 v38, v42, v45
	v_min_u32_e32 v42, v42, v45
	v_max_u32_e32 v45, v40, v37
	v_min_u32_e32 v37, v40, v37
	v_max_u32_e32 v40, v43, v33
	v_min_u32_e32 v33, v43, v33
	v_max_u32_e32 v43, v47, v32
	v_min_u32_e32 v32, v47, v32
	v_max_u32_e32 v47, v48, v38
	v_min_u32_e32 v38, v48, v38
	v_max_u32_e32 v48, v39, v45
	v_min_u32_e32 v39, v39, v45
	v_max_u32_e32 v45, v44, v40
	v_min_u32_e32 v40, v44, v40
	v_max_u32_e32 v44, v46, v43
	v_min_u32_e32 v43, v46, v43
	v_max_u32_e32 v46, v35, v42
	v_min_u32_e32 v35, v35, v42
	v_max_u32_e32 v42, v34, v37
	v_min_u32_e32 v34, v34, v37
	v_max_u32_e32 v37, v41, v33
	v_min_u32_e32 v33, v41, v33
	v_max_u32_e32 v41, v36, v32
	v_min_u32_e32 v32, v36, v32
	v_max_u32_e32 v36, v47, v45
	v_min_u32_e32 v45, v47, v45
	v_max_u32_e32 v47, v48, v44
	v_min_u32_e32 v44, v48, v44
	v_max_u32_e32 v48, v38, v40
	v_min_u32_e32 v40, v38, v40
	v_max_u32_e32 v38, v39, v43
	v_min_u32_e32 v39, v39, v43
	v_max_u32_e32 v43, v46, v37
	v_min_u32_e32 v46, v46, v37
	v_max_u32_e32 v51, v35, v33
	v_min_u32_e32 v52, v35, v33
	v_max_u32_e32 v53, v34, v32
	v_min_u32_e32 v54, v34, v32
	v_max_u32_e32 v32, v36, v47
	v_min_u32_e32 v33, v36, v47
	v_max_u32_e32 v36, v48, v38
	v_min_u32_e32 v37, v48, v38
	v_lshlrev_b32_e32 v48, 2, v71
	v_max_u32_e32 v49, v42, v41
	v_and_b32_e32 v48, 0x17c, v48
	v_min_u32_e32 v50, v42, v41
	v_max_u32_e32 v38, v40, v39
	v_min_u32_e32 v39, v40, v39
	v_max_u32_e32 v40, v43, v49
	v_min_u32_e32 v41, v43, v49
	v_or3_b32 v49, v69, v48, v68
	v_lshlrev_b32_e32 v49, 6, v49
	v_max_u32_e32 v34, v45, v44
	v_min_u32_e32 v35, v45, v44
	v_mad_i32_i24 v49, v67, s75, v49
	v_max_u32_e32 v42, v46, v50
	v_min_u32_e32 v43, v46, v50
	v_max_u32_e32 v44, v51, v53
	v_min_u32_e32 v45, v51, v53
	v_max_u32_e32 v46, v52, v54
	v_min_u32_e32 v47, v52, v54
	v_bfe_u32 v240, v49, 8, 4
	v_lshlrev_b32_e32 v240, 4, v240
	v_xor_b32_e32 v240, v49, v240
	ds_write_b128 v240, v[32:35]
	v_xor_b32_e32 v241, 16, v240
	ds_write_b128 v241, v[36:39]
	v_xor_b32_e32 v241, 32, v240
	ds_write_b128 v241, v[40:43]
	v_xor_b32_e32 v241, 48, v240
	ds_write_b128 v241, v[44:47]
	v_ashrrev_i32_e32 v32, 31, v16
	v_or_b32_e32 v32, 0x80000000, v32
	v_bitop3_b32 v16, v32, s86, v16 bitop3:0x48
	v_ashrrev_i32_e32 v32, 31, v0
	v_bitop3_b32 v0, v32, v0, s85 bitop3:0x36
	v_ashrrev_i32_e32 v32, 31, v17
	v_or_b32_e32 v32, 0x80000000, v32
	v_bitop3_b32 v17, v32, s86, v17 bitop3:0x48
	v_ashrrev_i32_e32 v32, 31, v1
	v_bitop3_b32 v1, v32, v1, s85 bitop3:0x36
	v_ashrrev_i32_e32 v32, 31, v18
	v_or_b32_e32 v32, 0x80000000, v32
	v_bitop3_b32 v18, v32, s86, v18 bitop3:0x48
	v_ashrrev_i32_e32 v32, 31, v2
	v_bitop3_b32 v2, v32, v2, s85 bitop3:0x36
	v_ashrrev_i32_e32 v32, 31, v19
	v_or_b32_e32 v32, 0x80000000, v32
	v_bitop3_b32 v19, v32, s86, v19 bitop3:0x48
	v_ashrrev_i32_e32 v32, 31, v3
	v_bitop3_b32 v3, v32, v3, s85 bitop3:0x36
	v_ashrrev_i32_e32 v32, 31, v20
	v_or_b32_e32 v32, 0x80000000, v32
	v_bitop3_b32 v20, v32, s86, v20 bitop3:0x48
	v_ashrrev_i32_e32 v32, 31, v4
	v_bitop3_b32 v4, v32, v4, s85 bitop3:0x36
	v_ashrrev_i32_e32 v32, 31, v21
	v_or_b32_e32 v32, 0x80000000, v32
	v_bitop3_b32 v21, v32, s86, v21 bitop3:0x48
	v_ashrrev_i32_e32 v32, 31, v5
	v_bitop3_b32 v5, v32, v5, s85 bitop3:0x36
	v_ashrrev_i32_e32 v32, 31, v22
	v_or_b32_e32 v32, 0x80000000, v32
	v_bitop3_b32 v22, v32, s86, v22 bitop3:0x48
	v_ashrrev_i32_e32 v32, 31, v6
	v_bitop3_b32 v6, v32, v6, s85 bitop3:0x36
	v_ashrrev_i32_e32 v32, 31, v23
	v_or_b32_e32 v32, 0x80000000, v32
	v_bitop3_b32 v23, v32, s86, v23 bitop3:0x48
	v_ashrrev_i32_e32 v32, 31, v7
	v_bitop3_b32 v7, v32, v7, s85 bitop3:0x36
	v_ashrrev_i32_e32 v32, 31, v24
	v_or_b32_e32 v32, 0x80000000, v32
	v_bitop3_b32 v24, v32, s86, v24 bitop3:0x48
	v_ashrrev_i32_e32 v32, 31, v8
	v_bitop3_b32 v8, v32, v8, s85 bitop3:0x36
	v_ashrrev_i32_e32 v32, 31, v25
	v_or_b32_e32 v32, 0x80000000, v32
	v_bitop3_b32 v25, v32, s86, v25 bitop3:0x48
	v_ashrrev_i32_e32 v32, 31, v9
	v_bitop3_b32 v9, v32, v9, s85 bitop3:0x36
	v_ashrrev_i32_e32 v32, 31, v26
	v_or_b32_e32 v32, 0x80000000, v32
	v_bitop3_b32 v26, v32, s86, v26 bitop3:0x48
	v_ashrrev_i32_e32 v32, 31, v10
	v_bitop3_b32 v10, v32, v10, s85 bitop3:0x36
	v_ashrrev_i32_e32 v32, 31, v27
	v_or_b32_e32 v32, 0x80000000, v32
	v_bitop3_b32 v27, v32, s86, v27 bitop3:0x48
	v_ashrrev_i32_e32 v32, 31, v11
	v_bitop3_b32 v11, v32, v11, s85 bitop3:0x36
	v_ashrrev_i32_e32 v32, 31, v28
	v_or_b32_e32 v32, 0x80000000, v32
	v_bitop3_b32 v28, v32, s86, v28 bitop3:0x48
	v_ashrrev_i32_e32 v32, 31, v12
	v_bitop3_b32 v12, v32, v12, s85 bitop3:0x36
	v_ashrrev_i32_e32 v32, 31, v29
	v_or_b32_e32 v32, 0x80000000, v32
	v_bitop3_b32 v29, v32, s86, v29 bitop3:0x48
	v_ashrrev_i32_e32 v32, 31, v13
	v_bitop3_b32 v13, v32, v13, s85 bitop3:0x36
	v_ashrrev_i32_e32 v32, 31, v30
	v_or_b32_e32 v32, 0x80000000, v32
	v_bitop3_b32 v30, v32, s86, v30 bitop3:0x48
	v_ashrrev_i32_e32 v32, 31, v14
	v_bitop3_b32 v14, v32, v14, s85 bitop3:0x36
	v_ashrrev_i32_e32 v32, 31, v31
	v_or_b32_e32 v32, 0x80000000, v32
	v_bitop3_b32 v31, v32, s86, v31 bitop3:0x48
	v_ashrrev_i32_e32 v32, 31, v15
	v_bitop3_b32 v15, v32, v15, s85 bitop3:0x36
	v_and_or_b32 v0, v0, s86, v72
	v_and_or_b32 v1, v1, s86, v73
	v_and_or_b32 v2, v2, s86, v74
	v_and_or_b32 v3, v3, s86, v75
	v_and_or_b32 v4, v4, s86, v76
	v_and_or_b32 v5, v5, s86, v77
	v_and_or_b32 v6, v6, s86, v78
	v_and_or_b32 v7, v7, s86, v79
	v_and_or_b32 v8, v8, s86, v80
	v_and_or_b32 v9, v9, s86, v81
	v_and_or_b32 v10, v10, s86, v82
	v_and_or_b32 v11, v11, s86, v83
	v_and_or_b32 v12, v12, s86, v84
	v_and_or_b32 v13, v13, s86, v85
	v_and_or_b32 v14, v14, s86, v86
	v_and_or_b32 v15, v15, s86, v87
	v_or3_b32 v16, v70, v16, v72
	v_or3_b32 v0, v0, v70, 32
	v_or3_b32 v17, v70, v17, v73
	v_or3_b32 v1, v1, v70, 32
	v_or3_b32 v18, v70, v18, v74
	v_or3_b32 v2, v2, v70, 32
	v_or3_b32 v19, v70, v19, v75
	v_or3_b32 v3, v3, v70, 32
	v_or3_b32 v20, v70, v20, v76
	v_or3_b32 v4, v4, v70, 32
	v_or3_b32 v21, v70, v21, v77
	v_or3_b32 v5, v5, v70, 32
	v_or3_b32 v22, v70, v22, v78
	v_or3_b32 v6, v6, v70, 32
	v_or3_b32 v23, v70, v23, v79
	v_or3_b32 v7, v7, v70, 32
	v_or3_b32 v24, v70, v24, v80
	v_or3_b32 v8, v8, v70, 32
	v_or3_b32 v25, v70, v25, v81
	v_or3_b32 v9, v9, v70, 32
	v_or3_b32 v26, v70, v26, v82
	v_or3_b32 v10, v10, v70, 32
	v_or3_b32 v27, v70, v27, v83
	v_or3_b32 v11, v11, v70, 32
	v_or3_b32 v28, v70, v28, v84
	v_or3_b32 v12, v12, v70, 32
	v_or3_b32 v29, v70, v29, v85
	v_or3_b32 v13, v13, v70, 32
	v_or3_b32 v30, v70, v30, v86
	v_or3_b32 v14, v14, v70, 32
	v_or3_b32 v31, v70, v31, v87
	v_or3_b32 v15, v15, v70, 32
	v_max_u32_e32 v32, v16, v29
	v_min_u32_e32 v16, v16, v29
	v_max_u32_e32 v29, v17, v28
	v_min_u32_e32 v17, v17, v28
	v_max_u32_e32 v28, v18, v31
	v_min_u32_e32 v18, v18, v31
	v_max_u32_e32 v31, v19, v30
	v_min_u32_e32 v19, v19, v30
	v_max_u32_e32 v30, v20, v24
	v_min_u32_e32 v20, v20, v24
	v_max_u32_e32 v24, v21, v22
	v_min_u32_e32 v21, v21, v22
	v_max_u32_e32 v22, v23, v27
	v_min_u32_e32 v23, v23, v27
	v_max_u32_e32 v27, v25, v26
	v_min_u32_e32 v25, v25, v26
	v_max_u32_e32 v40, v0, v13
	v_min_u32_e32 v0, v0, v13
	v_max_u32_e32 v13, v1, v12
	v_min_u32_e32 v1, v1, v12
	v_max_u32_e32 v12, v2, v15
	v_min_u32_e32 v2, v2, v15
	v_max_u32_e32 v15, v3, v14
	v_min_u32_e32 v3, v3, v14
	v_max_u32_e32 v14, v4, v8
	v_min_u32_e32 v4, v4, v8
	v_max_u32_e32 v8, v5, v6
	v_min_u32_e32 v5, v5, v6
	v_max_u32_e32 v6, v7, v11
	v_min_u32_e32 v7, v7, v11
	v_max_u32_e32 v11, v9, v10
	v_min_u32_e32 v9, v9, v10
	v_max_u32_e32 v26, v32, v24
	v_min_u32_e32 v24, v32, v24
	v_max_u32_e32 v32, v29, v22
	v_min_u32_e32 v22, v29, v22
	v_max_u32_e32 v29, v28, v27
	v_min_u32_e32 v27, v28, v27
	v_max_u32_e32 v28, v31, v30
	v_min_u32_e32 v30, v31, v30
	v_max_u32_e32 v31, v21, v16
	v_min_u32_e32 v16, v21, v16
	v_max_u32_e32 v21, v20, v19
	v_min_u32_e32 v19, v20, v19
	v_max_u32_e32 v20, v25, v18
	v_min_u32_e32 v18, v25, v18
	v_max_u32_e32 v25, v23, v17
	v_min_u32_e32 v17, v23, v17
	v_max_u32_e32 v10, v40, v8
	v_min_u32_e32 v8, v40, v8
	v_max_u32_e32 v40, v13, v6
	v_min_u32_e32 v6, v13, v6
	v_max_u32_e32 v13, v12, v11
	v_min_u32_e32 v11, v12, v11
	v_max_u32_e32 v12, v15, v14
	v_min_u32_e32 v14, v15, v14
	v_max_u32_e32 v15, v5, v0
	v_min_u32_e32 v0, v5, v0
	v_max_u32_e32 v5, v4, v3
	v_min_u32_e32 v3, v4, v3
	v_max_u32_e32 v4, v9, v2
	v_min_u32_e32 v2, v9, v2
	v_max_u32_e32 v9, v7, v1
	v_min_u32_e32 v1, v7, v1
	v_max_u32_e32 v23, v26, v32
	v_min_u32_e32 v26, v26, v32
	v_max_u32_e32 v32, v29, v28
	v_min_u32_e32 v28, v29, v28
	v_max_u32_e32 v29, v30, v24
	v_min_u32_e32 v24, v30, v24
	v_max_u32_e32 v30, v31, v21
	v_min_u32_e32 v21, v31, v21
	v_max_u32_e32 v31, v22, v27
	v_min_u32_e32 v22, v22, v27
	v_max_u32_e32 v27, v20, v25
	v_min_u32_e32 v20, v20, v25
	v_max_u32_e32 v25, v17, v16
	v_min_u32_e32 v16, v17, v16
	v_max_u32_e32 v17, v19, v18
	v_min_u32_e32 v18, v19, v18
	v_max_u32_e32 v7, v10, v40
	v_min_u32_e32 v10, v10, v40
	v_max_u32_e32 v40, v13, v12
	v_min_u32_e32 v12, v13, v12
	v_max_u32_e32 v13, v14, v8
	v_min_u32_e32 v8, v14, v8
	v_max_u32_e32 v14, v15, v5
	v_min_u32_e32 v5, v15, v5
	v_max_u32_e32 v15, v6, v11
	v_min_u32_e32 v6, v6, v11
	v_max_u32_e32 v11, v4, v9
	v_min_u32_e32 v4, v4, v9
	v_max_u32_e32 v9, v1, v0
	v_min_u32_e32 v0, v1, v0
	v_max_u32_e32 v1, v3, v2
	v_min_u32_e32 v2, v3, v2
	v_min_u32_e32 v19, v23, v32
	v_max_u32_e32 v33, v26, v28
	v_min_u32_e32 v26, v26, v28
	v_max_u32_e32 v28, v29, v27
	v_min_u32_e32 v27, v29, v27
	v_max_u32_e32 v29, v24, v20
	v_min_u32_e32 v20, v24, v20
	v_max_u32_e32 v24, v30, v31
	v_min_u32_e32 v30, v30, v31
	v_max_u32_e32 v31, v21, v22
	v_min_u32_e32 v21, v21, v22
	v_max_u32_e32 v22, v25, v17
	v_min_u32_e32 v17, v25, v17
	v_max_u32_e32 v25, v16, v18
	v_min_u32_e32 v3, v7, v40
	v_max_u32_e32 v41, v10, v12
	v_min_u32_e32 v10, v10, v12
	v_max_u32_e32 v12, v13, v11
	v_min_u32_e32 v11, v13, v11
	v_max_u32_e32 v13, v8, v4
	v_min_u32_e32 v4, v8, v4
	v_max_u32_e32 v8, v14, v15
	v_min_u32_e32 v14, v14, v15
	v_max_u32_e32 v15, v5, v6
	v_min_u32_e32 v5, v5, v6
	v_max_u32_e32 v6, v9, v1
	v_min_u32_e32 v1, v9, v1
	v_max_u32_e32 v9, v0, v2
	v_min_u32_e32 v16, v16, v18
	v_max_u32_e32 v18, v33, v19
	v_min_u32_e32 v19, v33, v19
	v_max_u32_e32 v33, v26, v22
	v_min_u32_e32 v22, v26, v22
	v_max_u32_e32 v26, v28, v24
	v_min_u32_e32 v24, v28, v24
	v_max_u32_e32 v28, v29, v30
	v_min_u32_e32 v29, v29, v30
	v_max_u32_e32 v30, v31, v27
	v_min_u32_e32 v27, v31, v27
	v_max_u32_e32 v31, v21, v20
	v_min_u32_e32 v20, v21, v20
	v_max_u32_e32 v21, v25, v17
	v_min_u32_e32 v0, v0, v2
	v_max_u32_e32 v2, v41, v3
	v_min_u32_e32 v3, v41, v3
	v_max_u32_e32 v41, v10, v6
	v_min_u32_e32 v6, v10, v6
	v_max_u32_e32 v10, v12, v8
	v_min_u32_e32 v8, v12, v8
	v_max_u32_e32 v12, v13, v14
	v_min_u32_e32 v13, v13, v14
	v_max_u32_e32 v14, v15, v11
	v_min_u32_e32 v11, v15, v11
	v_max_u32_e32 v15, v5, v4
	v_min_u32_e32 v4, v5, v4
	v_max_u32_e32 v5, v9, v1
	v_min_u32_e32 v17, v25, v17
	v_max_u32_e32 v34, v19, v24
	v_min_u32_e32 v19, v19, v24
	v_max_u32_e32 v24, v28, v30
	v_min_u32_e32 v28, v28, v30
	v_max_u32_e32 v30, v29, v27
	v_min_u32_e32 v27, v29, v27
	v_max_u32_e32 v29, v31, v21
	v_min_u32_e32 v1, v9, v1
	v_max_u32_e32 v42, v3, v8
	v_min_u32_e32 v3, v3, v8
	v_max_u32_e32 v8, v12, v14
	v_min_u32_e32 v12, v12, v14
	v_max_u32_e32 v14, v13, v11
	v_min_u32_e32 v11, v13, v11
	v_max_u32_e32 v13, v15, v5
	v_min_u32_e32 v21, v31, v21
	v_max_u32_e32 v31, v20, v17
	v_max_u32_e32 v35, v33, v19
	v_min_u32_e32 v19, v33, v19
	v_max_u32_e32 v33, v29, v22
	v_min_u32_e32 v22, v29, v22
	v_min_u32_e32 v5, v15, v5
	v_max_u32_e32 v15, v4, v1
	v_max_u32_e32 v43, v41, v3
	v_min_u32_e32 v3, v41, v3
	v_max_u32_e32 v41, v13, v6
	v_min_u32_e32 v6, v13, v6
	v_min_u32_e32 v25, v18, v26
	v_max_u32_e32 v29, v31, v21
	v_min_u32_e32 v21, v31, v21
	v_max_u32_e32 v31, v35, v24
	v_min_u32_e32 v24, v35, v24
	v_max_u32_e32 v35, v19, v28
	v_min_u32_e32 v19, v19, v28
	v_max_u32_e32 v28, v30, v33
	v_min_u32_e32 v30, v30, v33
	v_max_u32_e32 v33, v27, v22
	v_min_u32_e32 v9, v2, v10
	v_max_u32_e32 v13, v15, v5
	v_min_u32_e32 v5, v15, v5
	v_max_u32_e32 v15, v43, v8
	v_min_u32_e32 v8, v43, v8
	v_max_u32_e32 v43, v3, v12
	v_min_u32_e32 v3, v3, v12
	v_max_u32_e32 v12, v14, v41
	v_min_u32_e32 v14, v14, v41
	v_max_u32_e32 v41, v11, v6
	v_min_u32_e32 v17, v20, v17
	v_min_u32_e32 v20, v34, v25
	v_min_u32_e32 v22, v27, v22
	v_min_u32_e32 v36, v24, v35
	v_max_u32_e32 v37, v28, v19
	v_min_u32_e32 v19, v28, v19
	v_max_u32_e32 v28, v30, v33
	v_min_u32_e32 v1, v4, v1
	v_min_u32_e32 v4, v42, v9
	v_min_u32_e32 v6, v11, v6
	v_min_u32_e32 v44, v8, v43
	v_max_u32_e32 v45, v12, v3
	v_min_u32_e32 v3, v12, v3
	v_max_u32_e32 v12, v14, v41
	v_min_u32_e32 v27, v31, v20
	v_min_u32_e32 v30, v30, v33
	v_min_u32_e32 v33, v29, v22
	v_min_u32_e32 v38, v36, v37
	v_min_u32_e32 v39, v19, v28
	v_min_u32_e32 v11, v15, v4
	v_min_u32_e32 v14, v14, v41
	v_min_u32_e32 v41, v13, v6
	v_min_u32_e32 v46, v44, v45
	v_min_u32_e32 v47, v3, v12
	v_max3_u32 v0, v23, v32, v0
	v_max3_u32 v1, v18, v26, v1
	v_max3_u32 v5, v34, v25, v5
	v_max3_u32 v18, v31, v20, v41
	v_max3_u32 v6, v27, v13, v6
	v_max3_u32 v13, v24, v35, v14
	v_max3_u32 v14, v36, v37, v47
	v_max3_u32 v3, v38, v3, v12
	v_max3_u32 v12, v19, v28, v46
	v_max3_u32 v19, v39, v44, v45
	v_max3_u32 v8, v30, v8, v43
	v_max3_u32 v11, v29, v22, v11
	v_max3_u32 v4, v33, v15, v4
	v_max3_u32 v9, v21, v42, v9
	v_max3_u32 v2, v17, v2, v10
	v_max3_u32 v7, v16, v7, v40
	v_max_u32_e32 v10, v0, v12
	v_min_u32_e32 v0, v0, v12
	v_max_u32_e32 v12, v1, v19
	v_max_u32_e32 v15, v5, v8
	v_min_u32_e32 v5, v5, v8
	v_max_u32_e32 v8, v18, v11
	v_max_u32_e32 v16, v6, v4
	v_min_u32_e32 v4, v6, v4
	v_max_u32_e32 v6, v13, v9
	v_min_u32_e32 v9, v13, v9
	v_max_u32_e32 v13, v14, v2
	v_min_u32_e32 v2, v14, v2
	v_max_u32_e32 v14, v3, v7
	v_min_u32_e32 v1, v1, v19
	v_min_u32_e32 v11, v18, v11
	v_min_u32_e32 v3, v3, v7
	v_max_u32_e32 v7, v10, v16
	v_min_u32_e32 v10, v10, v16
	v_max_u32_e32 v16, v12, v6
	v_min_u32_e32 v6, v12, v6
	v_max_u32_e32 v12, v15, v13
	v_min_u32_e32 v13, v15, v13
	v_max_u32_e32 v15, v8, v14
	v_min_u32_e32 v8, v8, v14
	v_max_u32_e32 v14, v0, v4
	v_min_u32_e32 v0, v0, v4
	v_max_u32_e32 v4, v1, v9
	v_min_u32_e32 v1, v1, v9
	v_max_u32_e32 v9, v5, v2
	v_min_u32_e32 v2, v5, v2
	v_max_u32_e32 v5, v11, v3
	v_min_u32_e32 v3, v11, v3
	v_max_u32_e32 v11, v7, v12
	v_min_u32_e32 v7, v7, v12
	v_max_u32_e32 v12, v16, v15
	v_min_u32_e32 v15, v16, v15
	v_max_u32_e32 v16, v10, v13
	v_min_u32_e32 v10, v10, v13
	v_max_u32_e32 v13, v6, v8
	v_max_u32_e32 v17, v14, v9
	v_min_u32_e32 v14, v14, v9
	v_max_u32_e32 v9, v4, v5
	v_min_u32_e32 v18, v4, v5
	v_max_u32_e32 v4, v16, v13
	v_min_u32_e32 v5, v16, v13
	v_or3_b32 v16, v68, v48, v69
	v_lshlrev_b32_e32 v16, 6, v16
	v_min_u32_e32 v8, v6, v8
	v_max_u32_e32 v19, v0, v2
	v_min_u32_e32 v20, v0, v2
	v_max_u32_e32 v21, v1, v3
	v_min_u32_e32 v22, v1, v3
	v_max_u32_e32 v0, v11, v12
	v_min_u32_e32 v1, v11, v12
	v_max_u32_e32 v2, v7, v15
	v_min_u32_e32 v3, v7, v15
	v_mad_i32_i24 v16, v67, s75, v16
	v_max_u32_e32 v6, v10, v8
	v_min_u32_e32 v7, v10, v8
	v_max_u32_e32 v8, v17, v9
	v_min_u32_e32 v9, v17, v9
	v_max_u32_e32 v10, v14, v18
	v_min_u32_e32 v11, v14, v18
	v_max_u32_e32 v12, v19, v21
	v_min_u32_e32 v13, v19, v21
	v_max_u32_e32 v14, v20, v22
	v_min_u32_e32 v15, v20, v22
	v_bfe_u32 v240, v16, 8, 4
	v_lshlrev_b32_e32 v240, 4, v240
	v_xor_b32_e32 v240, v16, v240
	ds_write_b128 v240, v[0:3] offset:8192
	v_xor_b32_e32 v241, 16, v240
	ds_write_b128 v241, v[4:7] offset:8192
	v_xor_b32_e32 v241, 32, v240
	ds_write_b128 v241, v[8:11] offset:8192
	v_xor_b32_e32 v241, 48, v240
	ds_write_b128 v241, v[12:15] offset:8192
	s_waitcnt lgkmcnt(0)
	s_barrier
	s_and_saveexec_b64 s[60:61], vcc
	s_cbranch_execz .LBB0_856
	v_lshl_add_u32 v60, v65, 8, v66
	v_bfe_u32 v240, v60, 8, 4
	v_lshlrev_b32_e32 v240, 4, v240
	v_xor_b32_e32 v240, v60, v240
	ds_read_b128 v[0:3], v240
	v_xor_b32_e32 v241, 16, v240
	ds_read_b128 v[4:7], v241
	v_xor_b32_e32 v241, 32, v240
	ds_read_b128 v[8:11], v241
	v_xor_b32_e32 v241, 48, v240
	ds_read_b128 v[12:15], v241
	v_xor_b32_e32 v241, 64, v240
	ds_read_b128 v[16:19], v241
	v_xor_b32_e32 v241, 0x50, v240
	ds_read_b128 v[20:23], v241
	v_xor_b32_e32 v241, 0x80, v240
	ds_read_b128 v[24:27], v241
	v_xor_b32_e32 v241, 0x90, v240
	ds_read_b128 v[28:31], v241
	v_xor_b32_e32 v241, 0xc0, v240
	ds_read_b128 v[32:35], v241
	v_xor_b32_e32 v241, 0xd0, v240
	ds_read_b128 v[36:39], v241
	v_xor_b32_e32 v241, 0x60, v240
	ds_read_b128 v[40:43], v241
	v_xor_b32_e32 v241, 0x70, v240
	ds_read_b128 v[44:47], v241
	v_xor_b32_e32 v241, 0xa0, v240
	ds_read_b128 v[48:51], v241
	v_xor_b32_e32 v241, 0xb0, v240
	ds_read_b128 v[52:55], v241
	v_xor_b32_e32 v241, 0xe0, v240
	ds_read_b128 v[56:59], v241
	v_xor_b32_e32 v241, 0xf0, v240
	ds_read_b128 v[60:63], v241
	s_waitcnt lgkmcnt(4)
	v_max_u32_e32 v0, v0, v47
	v_max_u32_e32 v1, v1, v46
	v_max_u32_e32 v2, v2, v45
	v_max_u32_e32 v3, v3, v44
	v_max_u32_e32 v4, v4, v43
	v_max_u32_e32 v5, v5, v42
	v_max_u32_e32 v6, v6, v41
	v_max_u32_e32 v7, v7, v40
	v_max_u32_e32 v8, v8, v23
	v_max_u32_e32 v9, v9, v22
	v_max_u32_e32 v10, v10, v21
	v_max_u32_e32 v11, v11, v20
	v_max_u32_e32 v12, v12, v19
	v_max_u32_e32 v13, v13, v18
	v_max_u32_e32 v14, v14, v17
	v_max_u32_e32 v15, v15, v16
	s_waitcnt lgkmcnt(0)
	v_max_u32_e32 v24, v24, v63
	v_max_u32_e32 v25, v25, v62
	v_max_u32_e32 v26, v26, v61
	v_max_u32_e32 v27, v27, v60
	v_max_u32_e32 v28, v28, v59
	v_max_u32_e32 v29, v29, v58
	v_max_u32_e32 v30, v30, v57
	v_max_u32_e32 v31, v31, v56
	v_max_u32_e32 v39, v48, v39
	v_max_u32_e32 v38, v49, v38
	v_max_u32_e32 v37, v50, v37
	v_max_u32_e32 v36, v51, v36
	v_max_u32_e32 v35, v52, v35
	v_max_u32_e32 v34, v53, v34
	v_max_u32_e32 v33, v54, v33
	v_max_u32_e32 v32, v55, v32
	v_max_u32_e32 v16, v0, v8
	v_min_u32_e32 v0, v0, v8
	v_max_u32_e32 v8, v1, v9
	v_min_u32_e32 v1, v1, v9
	v_max_u32_e32 v9, v2, v10
	v_min_u32_e32 v2, v2, v10
	v_max_u32_e32 v10, v3, v11
	v_min_u32_e32 v3, v3, v11
	v_max_u32_e32 v11, v4, v12
	v_min_u32_e32 v4, v4, v12
	v_max_u32_e32 v12, v5, v13
	v_min_u32_e32 v5, v5, v13
	v_max_u32_e32 v13, v6, v14
	v_min_u32_e32 v6, v6, v14
	v_max_u32_e32 v14, v7, v15
	v_min_u32_e32 v7, v7, v15
	v_max_u32_e32 v40, v24, v39
	v_min_u32_e32 v24, v24, v39
	v_max_u32_e32 v39, v25, v38
	v_min_u32_e32 v25, v25, v38
	v_max_u32_e32 v38, v26, v37
	v_min_u32_e32 v26, v26, v37
	v_max_u32_e32 v37, v27, v36
	v_min_u32_e32 v27, v27, v36
	v_max_u32_e32 v36, v28, v35
	v_min_u32_e32 v28, v28, v35
	v_max_u32_e32 v35, v29, v34
	v_min_u32_e32 v29, v29, v34
	v_max_u32_e32 v34, v30, v33
	v_min_u32_e32 v30, v30, v33
	v_max_u32_e32 v33, v31, v32
	v_min_u32_e32 v31, v31, v32
	v_max_u32_e32 v15, v16, v11
	v_min_u32_e32 v11, v16, v11
	v_max_u32_e32 v16, v8, v12
	v_min_u32_e32 v8, v8, v12
	v_max_u32_e32 v12, v9, v13
	v_min_u32_e32 v9, v9, v13
	v_max_u32_e32 v13, v10, v14
	v_min_u32_e32 v10, v10, v14
	v_max_u32_e32 v14, v0, v4
	v_min_u32_e32 v0, v0, v4
	v_max_u32_e32 v4, v1, v5
	v_min_u32_e32 v1, v1, v5
	v_max_u32_e32 v5, v2, v6
	v_min_u32_e32 v2, v2, v6
	v_max_u32_e32 v6, v3, v7
	v_min_u32_e32 v3, v3, v7
	v_max_u32_e32 v32, v40, v36
	v_min_u32_e32 v36, v40, v36
	v_max_u32_e32 v40, v39, v35
	v_min_u32_e32 v35, v39, v35
	v_max_u32_e32 v39, v38, v34
	v_min_u32_e32 v34, v38, v34
	v_max_u32_e32 v38, v37, v33
	v_min_u32_e32 v33, v37, v33
	v_max_u32_e32 v37, v24, v28
	v_min_u32_e32 v24, v24, v28
	v_max_u32_e32 v28, v25, v29
	v_min_u32_e32 v25, v25, v29
	v_max_u32_e32 v29, v26, v30
	v_min_u32_e32 v26, v26, v30
	v_max_u32_e32 v30, v27, v31
	v_min_u32_e32 v27, v27, v31
	v_max_u32_e32 v7, v15, v12
	v_min_u32_e32 v12, v15, v12
	v_max_u32_e32 v15, v16, v13
	v_min_u32_e32 v13, v16, v13
	v_max_u32_e32 v16, v11, v9
	v_min_u32_e32 v9, v11, v9
	v_max_u32_e32 v11, v8, v10
	v_min_u32_e32 v8, v8, v10
	v_max_u32_e32 v10, v14, v5
	v_min_u32_e32 v5, v14, v5
	v_max_u32_e32 v14, v4, v6
	v_min_u32_e32 v4, v4, v6
	v_max_u32_e32 v6, v0, v2
	v_min_u32_e32 v0, v0, v2
	v_max_u32_e32 v2, v1, v3
	v_min_u32_e32 v1, v1, v3
	v_max_u32_e32 v31, v32, v39
	v_min_u32_e32 v32, v32, v39
	v_max_u32_e32 v39, v40, v38
	v_min_u32_e32 v38, v40, v38
	v_max_u32_e32 v40, v36, v34
	v_min_u32_e32 v34, v36, v34
	v_max_u32_e32 v36, v35, v33
	v_min_u32_e32 v33, v35, v33
	v_max_u32_e32 v35, v37, v29
	v_min_u32_e32 v29, v37, v29
	v_max_u32_e32 v37, v28, v30
	v_min_u32_e32 v28, v28, v30
	v_max_u32_e32 v30, v24, v26
	v_min_u32_e32 v24, v24, v26
	v_max_u32_e32 v26, v25, v27
	v_min_u32_e32 v25, v25, v27
	v_min_u32_e32 v3, v7, v15
	v_min_u32_e32 v17, v12, v13
	v_min_u32_e32 v18, v16, v11
	v_min_u32_e32 v19, v9, v8
	v_min_u32_e32 v20, v10, v14
	v_min_u32_e32 v21, v5, v4
	v_min_u32_e32 v22, v6, v2
	v_min_u32_e32 v23, v0, v1
	v_min_u32_e32 v27, v31, v39
	v_min_u32_e32 v41, v32, v38
	v_min_u32_e32 v42, v40, v36
	v_min_u32_e32 v43, v34, v33
	v_min_u32_e32 v44, v35, v37
	v_min_u32_e32 v45, v29, v28
	v_min_u32_e32 v46, v30, v26
	v_min_u32_e32 v47, v24, v25
	v_max3_u32 v7, v7, v15, v47
	v_max3_u32 v3, v3, v24, v25
	v_max3_u32 v12, v12, v13, v46
	v_max3_u32 v13, v17, v30, v26
	v_max3_u32 v11, v16, v11, v45
	v_max3_u32 v15, v18, v29, v28
	v_max3_u32 v8, v9, v8, v44
	v_max3_u32 v9, v19, v35, v37
	v_max3_u32 v10, v10, v14, v43
	v_max3_u32 v14, v20, v34, v33
	v_max3_u32 v4, v5, v4, v42
	v_max3_u32 v5, v21, v40, v36
	v_max3_u32 v2, v6, v2, v41
	v_max3_u32 v6, v22, v32, v38
	v_max3_u32 v0, v0, v1, v27
	v_max3_u32 v1, v23, v31, v39
	v_max_u32_e32 v16, v7, v10
	v_min_u32_e32 v7, v7, v10
	v_max_u32_e32 v10, v3, v14
	v_min_u32_e32 v3, v3, v14
	v_max_u32_e32 v14, v12, v4
	v_min_u32_e32 v4, v12, v4
	v_max_u32_e32 v12, v13, v5
	v_min_u32_e32 v5, v13, v5
	v_max_u32_e32 v13, v11, v2
	v_min_u32_e32 v2, v11, v2
	v_max_u32_e32 v11, v15, v6
	v_min_u32_e32 v6, v15, v6
	v_max_u32_e32 v15, v8, v0
	v_min_u32_e32 v0, v8, v0
	v_max_u32_e32 v8, v9, v1
	v_min_u32_e32 v1, v9, v1
	v_max_u32_e32 v9, v16, v13
	v_min_u32_e32 v13, v16, v13
	v_max_u32_e32 v16, v10, v11
	v_min_u32_e32 v10, v10, v11
	v_max_u32_e32 v11, v14, v15
	v_min_u32_e32 v14, v14, v15
	v_max_u32_e32 v15, v12, v8
	v_min_u32_e32 v8, v12, v8
	v_max_u32_e32 v12, v7, v2
	v_min_u32_e32 v2, v7, v2
	v_max_u32_e32 v7, v3, v6
	v_min_u32_e32 v3, v3, v6
	v_max_u32_e32 v6, v4, v0
	v_min_u32_e32 v0, v4, v0
	v_max_u32_e32 v4, v5, v1
	v_min_u32_e32 v1, v5, v1
	v_max_u32_e32 v5, v9, v11
	v_min_u32_e32 v9, v9, v11
	v_max_u32_e32 v11, v16, v15
	v_min_u32_e32 v15, v16, v15
	v_max_u32_e32 v16, v13, v14
	v_min_u32_e32 v13, v13, v14
	v_max_u32_e32 v14, v10, v8
	v_min_u32_e32 v8, v10, v8
	v_max_u32_e32 v10, v12, v6
	v_max_u32_e32 v17, v7, v4
	v_min_u32_e32 v18, v7, v4
	v_max_u32_e32 v19, v2, v0
	v_min_u32_e32 v20, v2, v0
	v_max_u32_e32 v21, v3, v1
	v_min_u32_e32 v22, v3, v1
	v_max_u32_e32 v0, v5, v11
	v_min_u32_e32 v1, v5, v11
	v_max_u32_e32 v4, v16, v14
	v_min_u32_e32 v5, v16, v14
	v_or_b32_e32 v16, s58, v65
	v_min_u32_e32 v12, v12, v6
	v_max_u32_e32 v2, v9, v15
	v_min_u32_e32 v3, v9, v15
	v_max_u32_e32 v6, v13, v8
	v_min_u32_e32 v7, v13, v8
	v_max_u32_e32 v8, v10, v17
	v_min_u32_e32 v9, v10, v17
	v_ashrrev_i32_e32 v17, 31, v16
	v_max_u32_e32 v10, v12, v18
	v_min_u32_e32 v11, v12, v18
	v_lshlrev_b64 v[16:17], 10, v[16:17]
	v_lshlrev_b32_e32 v18, 4, v64
	v_max_u32_e32 v12, v19, v21
	v_min_u32_e32 v13, v19, v21
	v_lshl_add_u64 v[16:17], s[12:13], 0, v[16:17]
	v_ashrrev_i32_e32 v19, 31, v18
	v_lshl_add_u64 v[16:17], v[18:19], 2, v[16:17]
	v_max_u32_e32 v14, v20, v22
	v_min_u32_e32 v15, v20, v22
	v_and_b32_e32 v238, 3, v65
	v_lshl_add_u32 v239, v65, 8, v66
	v_lshl_add_u32 v239, v238, 6, v239
	ds_write_b128 v239, v[0:3]
	ds_write_b128 v239, v[4:7] offset:16
	ds_write_b128 v239, v[8:11] offset:32
	ds_write_b128 v239, v[12:15] offset:48
	v_bfe_u32 v242, v65, 2, 4
	v_and_or_b32 v242, v65, 64, v242
	v_and_b32_e32 v243, 3, v242
	v_lshlrev_b32_e32 v243, 6, v243
	v_lshl_add_u32 v243, v238, 4, v243
	v_lshl_add_u32 v243, v242, 8, v243
	v_add_u32_e32 v243, v66, v243
	ds_read_b128 v[20:23], v243
	ds_read_b128 v[24:27], v243 offset:4096
	ds_read_b128 v[28:31], v243 offset:8192
	ds_read_b128 v[32:35], v243 offset:12288
	v_or_b32_e32 v244, s58, v242
	v_ashrrev_i32_e32 v245, 31, v244
	v_lshlrev_b64 v[244:245], 10, v[244:245]
	v_lshl_add_u64 v[244:245], s[12:13], 0, v[244:245]
	v_lshl_add_u64 v[244:245], v[18:19], 2, v[244:245]
	v_lshlrev_b32_e32 v246, 4, v238
	v_mov_b32_e32 v247, 0
	v_lshl_add_u64 v[244:245], v[244:245], 0, v[246:247]
	v_mov_b32_e32 v246, 0x4000
	s_waitcnt lgkmcnt(3)
	global_store_dwordx4 v[244:245], v[20:23], off
	v_lshl_add_u64 v[244:245], v[244:245], 0, v[246:247]
	s_waitcnt lgkmcnt(2)
	global_store_dwordx4 v[244:245], v[24:27], off
	v_lshl_add_u64 v[244:245], v[244:245], 0, v[246:247]
	s_waitcnt lgkmcnt(1)
	global_store_dwordx4 v[244:245], v[28:31], off
	v_lshl_add_u64 v[244:245], v[244:245], 0, v[246:247]
	s_waitcnt lgkmcnt(0)
	global_store_dwordx4 v[244:245], v[32:35], off
	s_branch .LBB0_856

.LBB0_906:
	s_andn2_saveexec_b64 s[4:5], s[4:5]
	s_cbranch_execz .LBB0_887
	s_lshl_b32 s22, s42, 1
	s_add_i32 s22, s45, s22
	v_lshrrev_b32_e32 v130, 7, v142
	s_ashr_i32 s23, s22, 31
	v_and_b32_e32 v0, 31, v142
	s_lshl_b64 s[24:25], s[22:23], 7
	v_lshlrev_b32_e32 v117, 6, v130
	v_or3_b32 v0, s24, v117, v0
	v_mov_b32_e32 v1, s25
	v_bfe_u32 v118, v142, 5, 1
	v_lshlrev_b64 v[0:1], 8, v[0:1]
	v_lshl_add_u64 v[0:1], s[16:17], 0, v[0:1]
	v_lshlrev_b32_e32 v128, 4, v118
	v_lshl_add_u64 v[8:9], v[0:1], 0, v[128:129]
	global_load_dwordx4 v[0:3], v[8:9], off
	v_add_co_u32_e32 v10, vcc, s37, v8
	v_and_b32_e32 v12, 0x5f, v142
	s_nop 0
	v_addc_co_u32_e32 v11, vcc, 0, v9, vcc
	global_load_dwordx4 v[4:7], v[10:11], off
	global_load_dwordx4 v[120:123], v[8:9], off offset:32
	global_load_dwordx4 v[112:115], v[10:11], off offset:32
	global_load_dwordx4 v[96:99], v[8:9], off offset:64
	global_load_dwordx4 v[108:111], v[10:11], off offset:64
	global_load_dwordx4 v[104:107], v[8:9], off offset:96
	global_load_dwordx4 v[92:95], v[8:9], off offset:128
	global_load_dwordx4 v[84:87], v[8:9], off offset:160
	global_load_dwordx4 v[76:79], v[8:9], off offset:192
	global_load_dwordx4 v[68:71], v[8:9], off offset:224
	global_load_dwordx4 v[100:103], v[10:11], off offset:96
	global_load_dwordx4 v[88:91], v[10:11], off offset:128
	global_load_dwordx4 v[80:83], v[10:11], off offset:160
	global_load_dwordx4 v[72:75], v[10:11], off offset:192
	global_load_dwordx4 v[64:67], v[10:11], off offset:224
	v_mul_u32_u24_e32 v12, 0x110, v12
	v_add3_u32 v131, v143, v12, v128
	s_waitcnt lgkmcnt(0)
	s_barrier
	ds_read_b128 v[8:11], v131 offset:32768
	s_waitcnt vmcnt(16)
	ds_read_b128 v[124:127], v131 offset:32800
	ds_read_b128 v[12:15], v131 offset:41472
	ds_read_b128 v[132:135], v131 offset:41504
	v_lshlrev_b32_e32 v119, 2, v118
	v_or_b32_e32 v128, 17, v119
	v_lshlrev_b32_e32 v130, 1, v130
	v_cmp_gt_u32_e32 vcc, s40, v116
	s_waitcnt vmcnt(14) lgkmcnt(3)
	v_mfma_f32_32x32x16_bf16 v[48:63], v[4:7], v[8:11], 0
	v_mfma_f32_32x32x16_bf16 v[32:47], v[0:3], v[8:11], 0
	s_waitcnt lgkmcnt(1)
	v_mfma_f32_32x32x16_bf16 v[16:31], v[0:3], v[12:15], 0
	s_waitcnt vmcnt(13)
	v_mfma_f32_32x32x16_bf16 v[32:47], v[120:123], v[124:127], v[32:47]
	s_waitcnt vmcnt(12)
	v_mfma_f32_32x32x16_bf16 v[48:63], v[112:115], v[124:127], v[48:63]
	s_waitcnt lgkmcnt(0)
	v_mfma_f32_32x32x16_bf16 v[16:31], v[120:123], v[132:135], v[16:31]
	ds_read_b128 v[120:123], v131 offset:32832
	ds_read_b128 v[124:127], v131 offset:32864
	s_waitcnt vmcnt(11) lgkmcnt(1)
	v_mfma_f32_32x32x16_bf16 v[32:47], v[96:99], v[120:123], v[32:47]
	s_waitcnt vmcnt(10)
	v_mfma_f32_32x32x16_bf16 v[48:63], v[108:111], v[120:123], v[48:63]
	s_waitcnt vmcnt(9) lgkmcnt(0)
	v_mfma_f32_32x32x16_bf16 v[32:47], v[104:107], v[124:127], v[32:47]
	s_waitcnt vmcnt(4)
	v_mfma_f32_32x32x16_bf16 v[48:63], v[100:103], v[124:127], v[48:63]
	ds_read_b128 v[120:123], v131 offset:32896
	ds_read_b128 v[124:127], v131 offset:32928
	v_mfma_f32_32x32x16_bf16 v[0:15], v[4:7], v[12:15], 0
	s_waitcnt lgkmcnt(1)
	v_mfma_f32_32x32x16_bf16 v[32:47], v[92:95], v[120:123], v[32:47]
	s_waitcnt vmcnt(3)
	v_mfma_f32_32x32x16_bf16 v[48:63], v[88:91], v[120:123], v[48:63]
	v_or_b32_e32 v120, 1, v119
	v_or_b32_e32 v121, 2, v119
	v_mfma_f32_32x32x16_bf16 v[0:15], v[112:115], v[132:135], v[0:15]
	s_waitcnt lgkmcnt(0)
	v_mfma_f32_32x32x16_bf16 v[32:47], v[84:87], v[124:127], v[32:47]
	s_waitcnt vmcnt(2)
	v_mfma_f32_32x32x16_bf16 v[48:63], v[80:83], v[124:127], v[48:63]
	ds_read_b128 v[122:125], v131 offset:32960
	ds_read_b128 v[136:139], v131 offset:32992
	ds_read_b128 v[144:147], v131 offset:41536
	ds_read_b128 v[148:151], v131 offset:41568
	ds_read_b128 v[152:155], v131 offset:41600
	ds_read_b128 v[156:159], v131 offset:41632
	ds_read_b128 v[160:163], v131 offset:41664
	ds_read_b128 v[164:167], v131 offset:41696
	v_or_b32_e32 v126, 11, v119
	v_or_b32_e32 v127, 16, v119
	s_waitcnt lgkmcnt(5)
	v_mfma_f32_32x32x16_bf16 v[16:31], v[96:99], v[144:147], v[16:31]
	v_or_b32_e32 v96, 18, v119
	v_mfma_f32_32x32x16_bf16 v[0:15], v[108:111], v[144:147], v[0:15]
	s_waitcnt lgkmcnt(4)
	v_mfma_f32_32x32x16_bf16 v[16:31], v[104:107], v[148:151], v[16:31]
	v_mfma_f32_32x32x16_bf16 v[0:15], v[100:103], v[148:151], v[0:15]
	s_waitcnt lgkmcnt(3)
	v_mfma_f32_32x32x16_bf16 v[16:31], v[92:95], v[152:155], v[16:31]
	v_or_b32_e32 v92, 25, v119
	v_mfma_f32_32x32x16_bf16 v[32:47], v[76:79], v[122:125], v[32:47]
	v_mfma_f32_32x32x16_bf16 v[0:15], v[88:91], v[152:155], v[0:15]
	v_or_b32_e32 v88, 26, v119
	s_waitcnt vmcnt(1)
	v_mfma_f32_32x32x16_bf16 v[48:63], v[72:75], v[122:125], v[48:63]
	v_or_b32_e32 v122, 3, v119
	v_or_b32_e32 v123, 8, v119
	v_or_b32_e32 v124, 9, v119
	v_or_b32_e32 v125, 10, v119
	s_waitcnt lgkmcnt(2)
	v_mfma_f32_32x32x16_bf16 v[16:31], v[84:87], v[156:159], v[16:31]
	v_mfma_f32_32x32x16_bf16 v[32:47], v[68:71], v[136:139], v[32:47]
	v_mfma_f32_32x32x16_bf16 v[0:15], v[80:83], v[156:159], v[0:15]
	s_nop 10
	v_ashrrev_i32_e32 v97, 31, v42
	v_ashrrev_i32_e32 v98, 31, v43
	v_ashrrev_i32_e32 v99, 31, v44
	v_ashrrev_i32_e32 v93, 31, v45
	v_or_b32_e32 v97, 0x80000000, v97
	v_or_b32_e32 v98, 0x80000000, v98
	v_or_b32_e32 v99, 0x80000000, v99
	s_waitcnt vmcnt(0)
	v_mfma_f32_32x32x16_bf16 v[48:63], v[64:67], v[136:139], v[48:63]
	v_or_b32_e32 v93, 0x80000000, v93
	v_ashrrev_i32_e32 v131, 31, v32
	v_ashrrev_i32_e32 v136, 31, v33
	v_ashrrev_i32_e32 v137, 31, v34
	v_ashrrev_i32_e32 v138, 31, v35
	v_ashrrev_i32_e32 v139, 31, v36
	v_ashrrev_i32_e32 v168, 31, v37
	s_waitcnt lgkmcnt(1)
	v_mfma_f32_32x32x16_bf16 v[16:31], v[76:79], v[160:163], v[16:31]
	v_ashrrev_i32_e32 v169, 31, v38
	v_ashrrev_i32_e32 v170, 31, v39
	v_ashrrev_i32_e32 v171, 31, v40
	v_ashrrev_i32_e32 v172, 31, v41
	v_ashrrev_i32_e32 v173, 31, v48
	v_ashrrev_i32_e32 v174, 31, v49
	v_ashrrev_i32_e32 v175, 31, v50
	v_mfma_f32_32x32x16_bf16 v[0:15], v[72:75], v[160:163], v[0:15]
	v_ashrrev_i32_e32 v177, 31, v51
	v_ashrrev_i32_e32 v178, 31, v52
	v_ashrrev_i32_e32 v179, 31, v53
	v_ashrrev_i32_e32 v180, 31, v54
	v_ashrrev_i32_e32 v181, 31, v55
	v_ashrrev_i32_e32 v182, 31, v56
	v_ashrrev_i32_e32 v112, 31, v57
	v_bitop3_b32 v42, v97, s39, v42 bitop3:0x48
	v_ashrrev_i32_e32 v97, 31, v58
	v_bitop3_b32 v43, v98, s39, v43 bitop3:0x48
	v_ashrrev_i32_e32 v98, 31, v59
	v_bitop3_b32 v44, v99, s39, v44 bitop3:0x48
	v_ashrrev_i32_e32 v99, 31, v60
	v_bitop3_b32 v45, v93, s39, v45 bitop3:0x48
	v_ashrrev_i32_e32 v93, 31, v61
	v_ashrrev_i32_e32 v89, 31, v46
	v_ashrrev_i32_e32 v84, 31, v62
	v_ashrrev_i32_e32 v85, 31, v47
	v_ashrrev_i32_e32 v80, 31, v63
	v_or_b32_e32 v131, 0x80000000, v131
	v_or_b32_e32 v136, 0x80000000, v136
	v_or_b32_e32 v137, 0x80000000, v137
	v_or_b32_e32 v138, 0x80000000, v138
	v_or_b32_e32 v139, 0x80000000, v139
	v_or_b32_e32 v168, 0x80000000, v168
	v_or_b32_e32 v169, 0x80000000, v169
	v_or_b32_e32 v170, 0x80000000, v170
	v_or_b32_e32 v171, 0x80000000, v171
	v_or_b32_e32 v172, 0x80000000, v172
	v_bitop3_b32 v48, v173, v48, s38 bitop3:0x36
	v_bitop3_b32 v49, v174, v49, s38 bitop3:0x36
	v_bitop3_b32 v50, v175, v50, s38 bitop3:0x36
	v_bitop3_b32 v51, v177, v51, s38 bitop3:0x36
	v_bitop3_b32 v52, v178, v52, s38 bitop3:0x36
	v_bitop3_b32 v53, v179, v53, s38 bitop3:0x36
	v_bitop3_b32 v54, v180, v54, s38 bitop3:0x36
	v_bitop3_b32 v55, v181, v55, s38 bitop3:0x36
	v_bitop3_b32 v56, v182, v56, s38 bitop3:0x36
	v_bitop3_b32 v57, v112, v57, s38 bitop3:0x36
	v_bitop3_b32 v58, v97, v58, s38 bitop3:0x36
	v_or_b32_e32 v97, 19, v119
	v_bitop3_b32 v59, v98, v59, s38 bitop3:0x36
	v_or_b32_e32 v98, 24, v119
	v_bitop3_b32 v60, v99, v60, s38 bitop3:0x36
	v_bitop3_b32 v61, v93, v61, s38 bitop3:0x36
	v_or_b32_e32 v89, 0x80000000, v89
	v_bitop3_b32 v62, v84, v62, s38 bitop3:0x36
	v_or_b32_e32 v84, 27, v119
	v_or_b32_e32 v85, 0x80000000, v85
	v_bitop3_b32 v63, v80, v63, s38 bitop3:0x36
	v_bitop3_b32 v32, v131, s39, v32 bitop3:0x48
	v_bitop3_b32 v33, v136, s39, v33 bitop3:0x48
	v_bitop3_b32 v34, v137, s39, v34 bitop3:0x48
	v_bitop3_b32 v35, v138, s39, v35 bitop3:0x48
	v_bitop3_b32 v36, v139, s39, v36 bitop3:0x48
	v_bitop3_b32 v37, v168, s39, v37 bitop3:0x48
	v_bitop3_b32 v38, v169, s39, v38 bitop3:0x48
	v_bitop3_b32 v39, v170, s39, v39 bitop3:0x48
	v_bitop3_b32 v40, v171, s39, v40 bitop3:0x48
	v_and_or_b32 v48, v48, s39, v119
	v_and_or_b32 v49, v49, s39, v120
	v_and_or_b32 v50, v50, s39, v121
	v_and_or_b32 v51, v51, s39, v122
	v_and_or_b32 v52, v52, s39, v123
	v_and_or_b32 v53, v53, s39, v124
	v_and_or_b32 v54, v54, s39, v125
	v_and_or_b32 v55, v55, s39, v126
	v_and_or_b32 v56, v56, s39, v127
	v_bitop3_b32 v41, v172, s39, v41 bitop3:0x48
	v_and_or_b32 v57, v57, s39, v128
	v_and_or_b32 v58, v58, s39, v96
	v_and_or_b32 v59, v59, s39, v97
	v_and_or_b32 v60, v60, s39, v98
	v_and_or_b32 v61, v61, s39, v92
	v_bitop3_b32 v46, v89, s39, v46 bitop3:0x48
	v_and_or_b32 v62, v62, s39, v88
	v_bitop3_b32 v47, v85, s39, v47 bitop3:0x48
	v_and_or_b32 v63, v63, s39, v84
	v_or3_b32 v32, v117, v32, v119
	v_or3_b32 v33, v117, v33, v120
	v_or3_b32 v34, v117, v34, v121
	v_or3_b32 v35, v117, v35, v122
	v_or3_b32 v36, v117, v36, v123
	v_or3_b32 v37, v117, v37, v124
	v_or3_b32 v38, v117, v38, v125
	v_or3_b32 v39, v117, v39, v126
	v_or3_b32 v40, v117, v40, v127
	v_or3_b32 v48, v48, v117, 32
	v_or3_b32 v49, v49, v117, 32
	v_or3_b32 v50, v50, v117, 32
	v_or3_b32 v51, v51, v117, 32
	v_or3_b32 v52, v52, v117, 32
	v_or3_b32 v53, v53, v117, 32
	v_or3_b32 v54, v54, v117, 32
	v_or3_b32 v55, v55, v117, 32
	v_or3_b32 v56, v56, v117, 32
	v_or3_b32 v41, v117, v41, v128
	v_or3_b32 v57, v57, v117, 32
	v_or3_b32 v42, v117, v42, v96
	v_or3_b32 v58, v58, v117, 32
	v_or3_b32 v43, v117, v43, v97
	v_or3_b32 v59, v59, v117, 32
	v_or3_b32 v44, v117, v44, v98
	v_or3_b32 v60, v60, v117, 32
	v_or3_b32 v45, v117, v45, v92
	v_or3_b32 v61, v61, v117, 32
	v_or3_b32 v46, v117, v46, v88
	v_or3_b32 v62, v62, v117, 32
	v_or3_b32 v47, v117, v47, v84
	v_or3_b32 v63, v63, v117, 32
	v_max_u32_e32 v80, v32, v45
	v_min_u32_e32 v32, v32, v45
	v_max_u32_e32 v45, v33, v44
	v_min_u32_e32 v33, v33, v44
	v_max_u32_e32 v44, v34, v47
	v_min_u32_e32 v34, v34, v47
	v_max_u32_e32 v47, v35, v46
	v_min_u32_e32 v35, v35, v46
	v_max_u32_e32 v46, v36, v40
	v_min_u32_e32 v36, v36, v40
	v_max_u32_e32 v40, v37, v38
	v_min_u32_e32 v37, v37, v38
	v_max_u32_e32 v38, v39, v43
	v_min_u32_e32 v39, v39, v43
	v_max_u32_e32 v43, v41, v42
	v_min_u32_e32 v41, v41, v42
	v_max_u32_e32 v72, v48, v61
	v_min_u32_e32 v48, v48, v61
	v_max_u32_e32 v61, v49, v60
	v_min_u32_e32 v49, v49, v60
	v_max_u32_e32 v60, v50, v63
	v_min_u32_e32 v50, v50, v63
	v_max_u32_e32 v63, v51, v62
	v_min_u32_e32 v51, v51, v62
	v_max_u32_e32 v62, v52, v56
	v_min_u32_e32 v52, v52, v56
	v_max_u32_e32 v56, v53, v54
	v_min_u32_e32 v53, v53, v54
	v_max_u32_e32 v54, v55, v59
	v_min_u32_e32 v55, v55, v59
	v_max_u32_e32 v59, v57, v58
	v_min_u32_e32 v57, v57, v58
	s_waitcnt lgkmcnt(0)
	v_mfma_f32_32x32x16_bf16 v[16:31], v[68:71], v[164:167], v[16:31]
	v_max_u32_e32 v42, v80, v40
	v_min_u32_e32 v40, v80, v40
	v_max_u32_e32 v68, v45, v38
	v_min_u32_e32 v38, v45, v38
	v_max_u32_e32 v45, v44, v43
	v_min_u32_e32 v43, v44, v43
	v_max_u32_e32 v44, v47, v46
	v_min_u32_e32 v46, v47, v46
	v_max_u32_e32 v47, v37, v32
	v_min_u32_e32 v32, v37, v32
	v_max_u32_e32 v37, v36, v35
	v_min_u32_e32 v35, v36, v35
	v_max_u32_e32 v36, v41, v34
	v_min_u32_e32 v34, v41, v34
	v_max_u32_e32 v41, v39, v33
	v_min_u32_e32 v33, v39, v33
	v_max_u32_e32 v58, v72, v56
	v_min_u32_e32 v56, v72, v56
	v_max_u32_e32 v72, v61, v54
	v_min_u32_e32 v54, v61, v54
	v_max_u32_e32 v61, v60, v59
	v_min_u32_e32 v59, v60, v59
	v_max_u32_e32 v60, v63, v62
	v_min_u32_e32 v62, v63, v62
	v_max_u32_e32 v63, v53, v48
	v_min_u32_e32 v48, v53, v48
	v_max_u32_e32 v53, v52, v51
	v_min_u32_e32 v51, v52, v51
	v_max_u32_e32 v52, v57, v50
	v_min_u32_e32 v50, v57, v50
	v_max_u32_e32 v57, v55, v49
	v_min_u32_e32 v49, v55, v49
	v_mfma_f32_32x32x16_bf16 v[0:15], v[64:67], v[164:167], v[0:15]
	v_max_u32_e32 v39, v42, v68
	v_min_u32_e32 v42, v42, v68
	v_max_u32_e32 v64, v45, v44
	v_min_u32_e32 v44, v45, v44
	v_max_u32_e32 v45, v46, v40
	v_min_u32_e32 v40, v46, v40
	v_max_u32_e32 v46, v47, v37
	v_min_u32_e32 v37, v47, v37
	v_max_u32_e32 v47, v38, v43
	v_min_u32_e32 v38, v38, v43
	v_max_u32_e32 v43, v36, v41
	v_min_u32_e32 v36, v36, v41
	v_max_u32_e32 v41, v33, v32
	v_min_u32_e32 v32, v33, v32
	v_max_u32_e32 v33, v35, v34
	v_min_u32_e32 v34, v35, v34
	v_max_u32_e32 v55, v58, v72
	v_min_u32_e32 v58, v58, v72
	v_max_u32_e32 v72, v61, v60
	v_min_u32_e32 v60, v61, v60
	v_max_u32_e32 v61, v62, v56
	v_min_u32_e32 v56, v62, v56
	v_max_u32_e32 v62, v63, v53
	v_min_u32_e32 v53, v63, v53
	v_max_u32_e32 v63, v54, v59
	v_min_u32_e32 v54, v54, v59
	v_max_u32_e32 v59, v52, v57
	v_min_u32_e32 v52, v52, v57
	v_max_u32_e32 v57, v49, v48
	v_min_u32_e32 v48, v49, v48
	v_max_u32_e32 v49, v51, v50
	v_min_u32_e32 v50, v51, v50
	v_min_u32_e32 v35, v39, v64
	v_max_u32_e32 v65, v42, v44
	v_min_u32_e32 v42, v42, v44
	v_max_u32_e32 v44, v45, v43
	v_min_u32_e32 v43, v45, v43
	v_max_u32_e32 v45, v40, v36
	v_min_u32_e32 v36, v40, v36
	v_max_u32_e32 v40, v46, v47
	v_min_u32_e32 v46, v46, v47
	v_max_u32_e32 v47, v37, v38
	v_min_u32_e32 v37, v37, v38
	v_max_u32_e32 v38, v41, v33
	v_min_u32_e32 v33, v41, v33
	v_max_u32_e32 v41, v32, v34
	v_min_u32_e32 v51, v55, v72
	v_max_u32_e32 v73, v58, v60
	v_min_u32_e32 v58, v58, v60
	v_max_u32_e32 v60, v61, v59
	v_min_u32_e32 v59, v61, v59
	v_max_u32_e32 v61, v56, v52
	v_min_u32_e32 v52, v56, v52
	v_max_u32_e32 v56, v62, v63
	v_min_u32_e32 v62, v62, v63
	v_max_u32_e32 v63, v53, v54
	v_min_u32_e32 v53, v53, v54
	v_max_u32_e32 v54, v57, v49
	v_min_u32_e32 v49, v57, v49
	v_max_u32_e32 v57, v48, v50
	v_min_u32_e32 v32, v32, v34
	v_max_u32_e32 v34, v65, v35
	v_min_u32_e32 v35, v65, v35
	v_max_u32_e32 v65, v42, v38
	v_min_u32_e32 v38, v42, v38
	v_max_u32_e32 v42, v44, v40
	v_min_u32_e32 v40, v44, v40
	v_max_u32_e32 v44, v45, v46
	v_min_u32_e32 v45, v45, v46
	v_max_u32_e32 v46, v47, v43
	v_min_u32_e32 v43, v47, v43
	v_max_u32_e32 v47, v37, v36
	v_min_u32_e32 v36, v37, v36
	v_max_u32_e32 v37, v41, v33
	v_min_u32_e32 v48, v48, v50
	v_max_u32_e32 v50, v73, v51
	v_min_u32_e32 v51, v73, v51
	v_max_u32_e32 v73, v58, v54
	v_min_u32_e32 v54, v58, v54
	v_max_u32_e32 v58, v60, v56
	v_min_u32_e32 v56, v60, v56
	v_max_u32_e32 v60, v61, v62
	v_min_u32_e32 v61, v61, v62
	v_max_u32_e32 v62, v63, v59
	v_min_u32_e32 v59, v63, v59
	v_max_u32_e32 v63, v53, v52
	v_min_u32_e32 v52, v53, v52
	v_max_u32_e32 v53, v57, v49
	v_min_u32_e32 v33, v41, v33
	v_max_u32_e32 v66, v35, v40
	v_min_u32_e32 v35, v35, v40
	v_max_u32_e32 v40, v44, v46
	v_min_u32_e32 v44, v44, v46
	v_max_u32_e32 v46, v45, v43
	v_min_u32_e32 v43, v45, v43
	v_max_u32_e32 v45, v47, v37
	v_min_u32_e32 v49, v57, v49
	v_max_u32_e32 v74, v51, v56
	v_min_u32_e32 v51, v51, v56
	v_max_u32_e32 v56, v60, v62
	v_min_u32_e32 v60, v60, v62
	v_max_u32_e32 v62, v61, v59
	v_min_u32_e32 v59, v61, v59
	v_max_u32_e32 v61, v63, v53
	v_min_u32_e32 v37, v47, v37
	v_max_u32_e32 v47, v36, v33
	v_max_u32_e32 v67, v65, v35
	v_min_u32_e32 v35, v65, v35
	v_max_u32_e32 v65, v45, v38
	v_min_u32_e32 v38, v45, v38
	v_min_u32_e32 v53, v63, v53
	v_max_u32_e32 v63, v52, v49
	v_max_u32_e32 v75, v73, v51
	v_min_u32_e32 v51, v73, v51
	v_max_u32_e32 v73, v61, v54
	v_min_u32_e32 v54, v61, v54
	v_min_u32_e32 v41, v34, v42
	v_max_u32_e32 v45, v47, v37
	v_min_u32_e32 v37, v47, v37
	v_max_u32_e32 v47, v67, v40
	v_min_u32_e32 v40, v67, v40
	v_max_u32_e32 v67, v35, v44
	v_min_u32_e32 v35, v35, v44
	v_max_u32_e32 v44, v46, v65
	v_min_u32_e32 v46, v46, v65
	v_max_u32_e32 v65, v43, v38
	v_min_u32_e32 v57, v50, v58
	v_max_u32_e32 v61, v63, v53
	v_min_u32_e32 v53, v63, v53
	v_max_u32_e32 v63, v75, v56
	v_min_u32_e32 v56, v75, v56
	v_max_u32_e32 v75, v51, v60
	v_min_u32_e32 v51, v51, v60
	v_max_u32_e32 v60, v62, v73
	v_min_u32_e32 v62, v62, v73
	v_max_u32_e32 v73, v59, v54
	v_min_u32_e32 v33, v36, v33
	v_min_u32_e32 v36, v66, v41
	v_min_u32_e32 v38, v43, v38
	v_min_u32_e32 v68, v40, v67
	v_max_u32_e32 v69, v44, v35
	v_min_u32_e32 v35, v44, v35
	v_max_u32_e32 v44, v46, v65
	v_min_u32_e32 v49, v52, v49
	v_min_u32_e32 v52, v74, v57
	v_min_u32_e32 v54, v59, v54
	v_min_u32_e32 v76, v56, v75
	v_max_u32_e32 v77, v60, v51
	v_min_u32_e32 v51, v60, v51
	v_max_u32_e32 v60, v62, v73
	v_min_u32_e32 v43, v47, v36
	v_min_u32_e32 v46, v46, v65
	v_min_u32_e32 v65, v45, v38
	v_min_u32_e32 v70, v68, v69
	v_min_u32_e32 v71, v35, v44
	v_min_u32_e32 v59, v63, v52
	v_min_u32_e32 v62, v62, v73
	v_min_u32_e32 v73, v61, v54
	v_min_u32_e32 v78, v76, v77
	v_min_u32_e32 v79, v51, v60
	v_max3_u32 v39, v39, v64, v48
	v_max3_u32 v34, v34, v42, v49
	v_max3_u32 v41, v66, v41, v53
	v_max3_u32 v36, v47, v36, v73
	v_max3_u32 v42, v43, v61, v54
	v_max3_u32 v40, v40, v67, v62
	v_max3_u32 v43, v68, v69, v79
	v_max3_u32 v47, v70, v51, v60
	v_max3_u32 v35, v35, v44, v78
	v_max3_u32 v44, v71, v76, v77
	v_max3_u32 v46, v46, v56, v75
	v_max3_u32 v38, v45, v38, v59
	v_max3_u32 v45, v65, v63, v52
	v_max3_u32 v37, v37, v74, v57
	v_max3_u32 v33, v33, v50, v58
	v_max3_u32 v32, v32, v55, v72
	v_max_u32_e32 v48, v39, v35
	v_min_u32_e32 v35, v39, v35
	v_max_u32_e32 v39, v34, v44
	v_min_u32_e32 v34, v34, v44
	v_max_u32_e32 v44, v41, v46
	v_min_u32_e32 v41, v41, v46
	v_max_u32_e32 v46, v36, v38
	v_min_u32_e32 v36, v36, v38
	v_max_u32_e32 v38, v42, v45
	v_min_u32_e32 v42, v42, v45
	v_max_u32_e32 v45, v40, v37
	v_min_u32_e32 v37, v40, v37
	v_max_u32_e32 v40, v43, v33
	v_min_u32_e32 v33, v43, v33
	v_max_u32_e32 v43, v47, v32
	v_min_u32_e32 v32, v47, v32
	v_max_u32_e32 v47, v48, v38
	v_min_u32_e32 v38, v48, v38
	v_max_u32_e32 v48, v39, v45
	v_min_u32_e32 v39, v39, v45
	v_max_u32_e32 v45, v44, v40
	v_min_u32_e32 v40, v44, v40
	v_max_u32_e32 v44, v46, v43
	v_min_u32_e32 v43, v46, v43
	v_max_u32_e32 v46, v35, v42
	v_min_u32_e32 v35, v35, v42
	v_max_u32_e32 v42, v34, v37
	v_min_u32_e32 v34, v34, v37
	v_max_u32_e32 v37, v41, v33
	v_min_u32_e32 v33, v41, v33
	v_max_u32_e32 v41, v36, v32
	v_min_u32_e32 v32, v36, v32
	v_max_u32_e32 v36, v47, v45
	v_min_u32_e32 v45, v47, v45
	v_max_u32_e32 v47, v48, v44
	v_min_u32_e32 v44, v48, v44
	v_max_u32_e32 v48, v38, v40
	v_min_u32_e32 v40, v38, v40
	v_max_u32_e32 v38, v39, v43
	v_min_u32_e32 v39, v39, v43
	v_max_u32_e32 v43, v46, v37
	v_min_u32_e32 v46, v46, v37
	v_max_u32_e32 v51, v35, v33
	v_min_u32_e32 v52, v35, v33
	v_max_u32_e32 v53, v34, v32
	v_min_u32_e32 v54, v34, v32
	v_max_u32_e32 v32, v36, v47
	v_min_u32_e32 v33, v36, v47
	v_max_u32_e32 v36, v48, v38
	v_min_u32_e32 v37, v48, v38
	v_lshlrev_b32_e32 v48, 2, v142
	v_and_b32_e32 v48, 0x17c, v48
	v_or3_b32 v48, v130, v48, v118
	v_max_u32_e32 v49, v42, v41
	v_lshlrev_b32_e32 v48, 6, v48
	v_min_u32_e32 v50, v42, v41
	v_max_u32_e32 v34, v45, v44
	v_min_u32_e32 v35, v45, v44
	v_max_u32_e32 v38, v40, v39
	v_min_u32_e32 v39, v40, v39
	v_max_u32_e32 v40, v43, v49
	v_min_u32_e32 v41, v43, v49
	v_add_u32_e32 v49, v143, v48
	v_max_u32_e32 v42, v46, v50
	v_min_u32_e32 v43, v46, v50
	v_max_u32_e32 v44, v51, v53
	v_min_u32_e32 v45, v51, v53
	v_max_u32_e32 v46, v52, v54
	v_min_u32_e32 v47, v52, v54
	v_bfe_u32 v240, v49, 8, 4
	v_lshlrev_b32_e32 v240, 4, v240
	v_xor_b32_e32 v240, v49, v240
	ds_write_b128 v240, v[32:35]
	v_xor_b32_e32 v241, 16, v240
	ds_write_b128 v241, v[36:39]
	v_xor_b32_e32 v241, 32, v240
	ds_write_b128 v241, v[40:43]
	v_xor_b32_e32 v241, 48, v240
	ds_write_b128 v241, v[44:47]
	v_ashrrev_i32_e32 v32, 31, v16
	v_or_b32_e32 v32, 0x80000000, v32
	v_bitop3_b32 v16, v32, s39, v16 bitop3:0x48
	v_ashrrev_i32_e32 v32, 31, v0
	v_bitop3_b32 v0, v32, v0, s38 bitop3:0x36
	v_ashrrev_i32_e32 v32, 31, v17
	v_or_b32_e32 v32, 0x80000000, v32
	v_bitop3_b32 v17, v32, s39, v17 bitop3:0x48
	v_ashrrev_i32_e32 v32, 31, v1
	v_bitop3_b32 v1, v32, v1, s38 bitop3:0x36
	v_ashrrev_i32_e32 v32, 31, v18
	v_or_b32_e32 v32, 0x80000000, v32
	v_bitop3_b32 v18, v32, s39, v18 bitop3:0x48
	v_ashrrev_i32_e32 v32, 31, v2
	v_bitop3_b32 v2, v32, v2, s38 bitop3:0x36
	v_ashrrev_i32_e32 v32, 31, v19
	v_or_b32_e32 v32, 0x80000000, v32
	v_bitop3_b32 v19, v32, s39, v19 bitop3:0x48
	v_ashrrev_i32_e32 v32, 31, v3
	v_bitop3_b32 v3, v32, v3, s38 bitop3:0x36
	v_ashrrev_i32_e32 v32, 31, v20
	v_or_b32_e32 v32, 0x80000000, v32
	v_bitop3_b32 v20, v32, s39, v20 bitop3:0x48
	v_ashrrev_i32_e32 v32, 31, v4
	v_bitop3_b32 v4, v32, v4, s38 bitop3:0x36
	v_ashrrev_i32_e32 v32, 31, v21
	v_or_b32_e32 v32, 0x80000000, v32
	v_bitop3_b32 v21, v32, s39, v21 bitop3:0x48
	v_ashrrev_i32_e32 v32, 31, v5
	v_bitop3_b32 v5, v32, v5, s38 bitop3:0x36
	v_ashrrev_i32_e32 v32, 31, v22
	v_or_b32_e32 v32, 0x80000000, v32
	v_bitop3_b32 v22, v32, s39, v22 bitop3:0x48
	v_ashrrev_i32_e32 v32, 31, v6
	v_bitop3_b32 v6, v32, v6, s38 bitop3:0x36
	v_ashrrev_i32_e32 v32, 31, v23
	v_or_b32_e32 v32, 0x80000000, v32
	v_bitop3_b32 v23, v32, s39, v23 bitop3:0x48
	v_ashrrev_i32_e32 v32, 31, v7
	v_bitop3_b32 v7, v32, v7, s38 bitop3:0x36
	v_ashrrev_i32_e32 v32, 31, v24
	v_or_b32_e32 v32, 0x80000000, v32
	v_bitop3_b32 v24, v32, s39, v24 bitop3:0x48
	v_ashrrev_i32_e32 v32, 31, v8
	v_bitop3_b32 v8, v32, v8, s38 bitop3:0x36
	v_ashrrev_i32_e32 v32, 31, v25
	v_or_b32_e32 v32, 0x80000000, v32
	v_bitop3_b32 v25, v32, s39, v25 bitop3:0x48
	v_ashrrev_i32_e32 v32, 31, v9
	v_bitop3_b32 v9, v32, v9, s38 bitop3:0x36
	v_ashrrev_i32_e32 v32, 31, v26
	v_or_b32_e32 v32, 0x80000000, v32
	v_bitop3_b32 v26, v32, s39, v26 bitop3:0x48
	v_ashrrev_i32_e32 v32, 31, v10
	v_bitop3_b32 v10, v32, v10, s38 bitop3:0x36
	v_ashrrev_i32_e32 v32, 31, v27
	v_or_b32_e32 v32, 0x80000000, v32
	v_bitop3_b32 v27, v32, s39, v27 bitop3:0x48
	v_ashrrev_i32_e32 v32, 31, v11
	v_bitop3_b32 v11, v32, v11, s38 bitop3:0x36
	v_ashrrev_i32_e32 v32, 31, v28
	v_or_b32_e32 v32, 0x80000000, v32
	v_bitop3_b32 v28, v32, s39, v28 bitop3:0x48
	v_ashrrev_i32_e32 v32, 31, v12
	v_bitop3_b32 v12, v32, v12, s38 bitop3:0x36
	v_ashrrev_i32_e32 v32, 31, v29
	v_or_b32_e32 v32, 0x80000000, v32
	v_bitop3_b32 v29, v32, s39, v29 bitop3:0x48
	v_ashrrev_i32_e32 v32, 31, v13
	v_bitop3_b32 v13, v32, v13, s38 bitop3:0x36
	v_ashrrev_i32_e32 v32, 31, v30
	v_or_b32_e32 v32, 0x80000000, v32
	v_bitop3_b32 v30, v32, s39, v30 bitop3:0x48
	v_ashrrev_i32_e32 v32, 31, v14
	v_bitop3_b32 v14, v32, v14, s38 bitop3:0x36
	v_ashrrev_i32_e32 v32, 31, v31
	v_or_b32_e32 v32, 0x80000000, v32
	v_bitop3_b32 v31, v32, s39, v31 bitop3:0x48
	v_ashrrev_i32_e32 v32, 31, v15
	v_bitop3_b32 v15, v32, v15, s38 bitop3:0x36
	v_and_or_b32 v0, v0, s39, v119
	v_and_or_b32 v1, v1, s39, v120
	v_and_or_b32 v2, v2, s39, v121
	v_and_or_b32 v3, v3, s39, v122
	v_and_or_b32 v4, v4, s39, v123
	v_and_or_b32 v5, v5, s39, v124
	v_and_or_b32 v6, v6, s39, v125
	v_and_or_b32 v7, v7, s39, v126
	v_and_or_b32 v8, v8, s39, v127
	v_and_or_b32 v9, v9, s39, v128
	v_and_or_b32 v10, v10, s39, v96
	v_and_or_b32 v11, v11, s39, v97
	v_and_or_b32 v12, v12, s39, v98
	v_and_or_b32 v13, v13, s39, v92
	v_and_or_b32 v14, v14, s39, v88
	v_and_or_b32 v15, v15, s39, v84
	v_or3_b32 v16, v117, v16, v119
	v_or3_b32 v0, v0, v117, 32
	v_or3_b32 v17, v117, v17, v120
	v_or3_b32 v1, v1, v117, 32
	v_or3_b32 v18, v117, v18, v121
	v_or3_b32 v2, v2, v117, 32
	v_or3_b32 v19, v117, v19, v122
	v_or3_b32 v3, v3, v117, 32
	v_or3_b32 v20, v117, v20, v123
	v_or3_b32 v4, v4, v117, 32
	v_or3_b32 v21, v117, v21, v124
	v_or3_b32 v5, v5, v117, 32
	v_or3_b32 v22, v117, v22, v125
	v_or3_b32 v6, v6, v117, 32
	v_or3_b32 v23, v117, v23, v126
	v_or3_b32 v7, v7, v117, 32
	v_or3_b32 v24, v117, v24, v127
	v_or3_b32 v8, v8, v117, 32
	v_or3_b32 v25, v117, v25, v128
	v_or3_b32 v9, v9, v117, 32
	v_or3_b32 v26, v117, v26, v96
	v_or3_b32 v10, v10, v117, 32
	v_or3_b32 v27, v117, v27, v97
	v_or3_b32 v11, v11, v117, 32
	v_or3_b32 v28, v117, v28, v98
	v_or3_b32 v12, v12, v117, 32
	v_or3_b32 v29, v117, v29, v92
	v_or3_b32 v13, v13, v117, 32
	v_or3_b32 v30, v117, v30, v88
	v_or3_b32 v14, v14, v117, 32
	v_or3_b32 v31, v117, v31, v84
	v_or3_b32 v15, v15, v117, 32
	v_max_u32_e32 v32, v16, v29
	v_min_u32_e32 v16, v16, v29
	v_max_u32_e32 v29, v17, v28
	v_min_u32_e32 v17, v17, v28
	v_max_u32_e32 v28, v18, v31
	v_min_u32_e32 v18, v18, v31
	v_max_u32_e32 v31, v19, v30
	v_min_u32_e32 v19, v19, v30
	v_max_u32_e32 v30, v20, v24
	v_min_u32_e32 v20, v20, v24
	v_max_u32_e32 v24, v21, v22
	v_min_u32_e32 v21, v21, v22
	v_max_u32_e32 v22, v23, v27
	v_min_u32_e32 v23, v23, v27
	v_max_u32_e32 v27, v25, v26
	v_min_u32_e32 v25, v25, v26
	v_max_u32_e32 v40, v0, v13
	v_min_u32_e32 v0, v0, v13
	v_max_u32_e32 v13, v1, v12
	v_min_u32_e32 v1, v1, v12
	v_max_u32_e32 v12, v2, v15
	v_min_u32_e32 v2, v2, v15
	v_max_u32_e32 v15, v3, v14
	v_min_u32_e32 v3, v3, v14
	v_max_u32_e32 v14, v4, v8
	v_min_u32_e32 v4, v4, v8
	v_max_u32_e32 v8, v5, v6
	v_min_u32_e32 v5, v5, v6
	v_max_u32_e32 v6, v7, v11
	v_min_u32_e32 v7, v7, v11
	v_max_u32_e32 v11, v9, v10
	v_min_u32_e32 v9, v9, v10
	v_max_u32_e32 v26, v32, v24
	v_min_u32_e32 v24, v32, v24
	v_max_u32_e32 v32, v29, v22
	v_min_u32_e32 v22, v29, v22
	v_max_u32_e32 v29, v28, v27
	v_min_u32_e32 v27, v28, v27
	v_max_u32_e32 v28, v31, v30
	v_min_u32_e32 v30, v31, v30
	v_max_u32_e32 v31, v21, v16
	v_min_u32_e32 v16, v21, v16
	v_max_u32_e32 v21, v20, v19
	v_min_u32_e32 v19, v20, v19
	v_max_u32_e32 v20, v25, v18
	v_min_u32_e32 v18, v25, v18
	v_max_u32_e32 v25, v23, v17
	v_min_u32_e32 v17, v23, v17
	v_max_u32_e32 v10, v40, v8
	v_min_u32_e32 v8, v40, v8
	v_max_u32_e32 v40, v13, v6
	v_min_u32_e32 v6, v13, v6
	v_max_u32_e32 v13, v12, v11
	v_min_u32_e32 v11, v12, v11
	v_max_u32_e32 v12, v15, v14
	v_min_u32_e32 v14, v15, v14
	v_max_u32_e32 v15, v5, v0
	v_min_u32_e32 v0, v5, v0
	v_max_u32_e32 v5, v4, v3
	v_min_u32_e32 v3, v4, v3
	v_max_u32_e32 v4, v9, v2
	v_min_u32_e32 v2, v9, v2
	v_max_u32_e32 v9, v7, v1
	v_min_u32_e32 v1, v7, v1
	v_max_u32_e32 v23, v26, v32
	v_min_u32_e32 v26, v26, v32
	v_max_u32_e32 v32, v29, v28
	v_min_u32_e32 v28, v29, v28
	v_max_u32_e32 v29, v30, v24
	v_min_u32_e32 v24, v30, v24
	v_max_u32_e32 v30, v31, v21
	v_min_u32_e32 v21, v31, v21
	v_max_u32_e32 v31, v22, v27
	v_min_u32_e32 v22, v22, v27
	v_max_u32_e32 v27, v20, v25
	v_min_u32_e32 v20, v20, v25
	v_max_u32_e32 v25, v17, v16
	v_min_u32_e32 v16, v17, v16
	v_max_u32_e32 v17, v19, v18
	v_min_u32_e32 v18, v19, v18
	v_max_u32_e32 v7, v10, v40
	v_min_u32_e32 v10, v10, v40
	v_max_u32_e32 v40, v13, v12
	v_min_u32_e32 v12, v13, v12
	v_max_u32_e32 v13, v14, v8
	v_min_u32_e32 v8, v14, v8
	v_max_u32_e32 v14, v15, v5
	v_min_u32_e32 v5, v15, v5
	v_max_u32_e32 v15, v6, v11
	v_min_u32_e32 v6, v6, v11
	v_max_u32_e32 v11, v4, v9
	v_min_u32_e32 v4, v4, v9
	v_max_u32_e32 v9, v1, v0
	v_min_u32_e32 v0, v1, v0
	v_max_u32_e32 v1, v3, v2
	v_min_u32_e32 v2, v3, v2
	v_min_u32_e32 v19, v23, v32
	v_max_u32_e32 v33, v26, v28
	v_min_u32_e32 v26, v26, v28
	v_max_u32_e32 v28, v29, v27
	v_min_u32_e32 v27, v29, v27
	v_max_u32_e32 v29, v24, v20
	v_min_u32_e32 v20, v24, v20
	v_max_u32_e32 v24, v30, v31
	v_min_u32_e32 v30, v30, v31
	v_max_u32_e32 v31, v21, v22
	v_min_u32_e32 v21, v21, v22
	v_max_u32_e32 v22, v25, v17
	v_min_u32_e32 v17, v25, v17
	v_max_u32_e32 v25, v16, v18
	v_min_u32_e32 v3, v7, v40
	v_max_u32_e32 v41, v10, v12
	v_min_u32_e32 v10, v10, v12
	v_max_u32_e32 v12, v13, v11
	v_min_u32_e32 v11, v13, v11
	v_max_u32_e32 v13, v8, v4
	v_min_u32_e32 v4, v8, v4
	v_max_u32_e32 v8, v14, v15
	v_min_u32_e32 v14, v14, v15
	v_max_u32_e32 v15, v5, v6
	v_min_u32_e32 v5, v5, v6
	v_max_u32_e32 v6, v9, v1
	v_min_u32_e32 v1, v9, v1
	v_max_u32_e32 v9, v0, v2
	v_min_u32_e32 v16, v16, v18
	v_max_u32_e32 v18, v33, v19
	v_min_u32_e32 v19, v33, v19
	v_max_u32_e32 v33, v26, v22
	v_min_u32_e32 v22, v26, v22
	v_max_u32_e32 v26, v28, v24
	v_min_u32_e32 v24, v28, v24
	v_max_u32_e32 v28, v29, v30
	v_min_u32_e32 v29, v29, v30
	v_max_u32_e32 v30, v31, v27
	v_min_u32_e32 v27, v31, v27
	v_max_u32_e32 v31, v21, v20
	v_min_u32_e32 v20, v21, v20
	v_max_u32_e32 v21, v25, v17
	v_min_u32_e32 v0, v0, v2
	v_max_u32_e32 v2, v41, v3
	v_min_u32_e32 v3, v41, v3
	v_max_u32_e32 v41, v10, v6
	v_min_u32_e32 v6, v10, v6
	v_max_u32_e32 v10, v12, v8
	v_min_u32_e32 v8, v12, v8
	v_max_u32_e32 v12, v13, v14
	v_min_u32_e32 v13, v13, v14
	v_max_u32_e32 v14, v15, v11
	v_min_u32_e32 v11, v15, v11
	v_max_u32_e32 v15, v5, v4
	v_min_u32_e32 v4, v5, v4
	v_max_u32_e32 v5, v9, v1
	v_min_u32_e32 v17, v25, v17
	v_max_u32_e32 v34, v19, v24
	v_min_u32_e32 v19, v19, v24
	v_max_u32_e32 v24, v28, v30
	v_min_u32_e32 v28, v28, v30
	v_max_u32_e32 v30, v29, v27
	v_min_u32_e32 v27, v29, v27
	v_max_u32_e32 v29, v31, v21
	v_min_u32_e32 v1, v9, v1
	v_max_u32_e32 v42, v3, v8
	v_min_u32_e32 v3, v3, v8
	v_max_u32_e32 v8, v12, v14
	v_min_u32_e32 v12, v12, v14
	v_max_u32_e32 v14, v13, v11
	v_min_u32_e32 v11, v13, v11
	v_max_u32_e32 v13, v15, v5
	v_min_u32_e32 v21, v31, v21
	v_max_u32_e32 v31, v20, v17
	v_max_u32_e32 v35, v33, v19
	v_min_u32_e32 v19, v33, v19
	v_max_u32_e32 v33, v29, v22
	v_min_u32_e32 v22, v29, v22
	v_min_u32_e32 v5, v15, v5
	v_max_u32_e32 v15, v4, v1
	v_max_u32_e32 v43, v41, v3
	v_min_u32_e32 v3, v41, v3
	v_max_u32_e32 v41, v13, v6
	v_min_u32_e32 v6, v13, v6
	v_min_u32_e32 v25, v18, v26
	v_max_u32_e32 v29, v31, v21
	v_min_u32_e32 v21, v31, v21
	v_max_u32_e32 v31, v35, v24
	v_min_u32_e32 v24, v35, v24
	v_max_u32_e32 v35, v19, v28
	v_min_u32_e32 v19, v19, v28
	v_max_u32_e32 v28, v30, v33
	v_min_u32_e32 v30, v30, v33
	v_max_u32_e32 v33, v27, v22
	v_min_u32_e32 v9, v2, v10
	v_max_u32_e32 v13, v15, v5
	v_min_u32_e32 v5, v15, v5
	v_max_u32_e32 v15, v43, v8
	v_min_u32_e32 v8, v43, v8
	v_max_u32_e32 v43, v3, v12
	v_min_u32_e32 v3, v3, v12
	v_max_u32_e32 v12, v14, v41
	v_min_u32_e32 v14, v14, v41
	v_max_u32_e32 v41, v11, v6
	v_min_u32_e32 v17, v20, v17
	v_min_u32_e32 v20, v34, v25
	v_min_u32_e32 v22, v27, v22
	v_min_u32_e32 v36, v24, v35
	v_max_u32_e32 v37, v28, v19
	v_min_u32_e32 v19, v28, v19
	v_max_u32_e32 v28, v30, v33
	v_min_u32_e32 v1, v4, v1
	v_min_u32_e32 v4, v42, v9
	v_min_u32_e32 v6, v11, v6
	v_min_u32_e32 v44, v8, v43
	v_max_u32_e32 v45, v12, v3
	v_min_u32_e32 v3, v12, v3
	v_max_u32_e32 v12, v14, v41
	v_min_u32_e32 v27, v31, v20
	v_min_u32_e32 v30, v30, v33
	v_min_u32_e32 v33, v29, v22
	v_min_u32_e32 v38, v36, v37
	v_min_u32_e32 v39, v19, v28
	v_min_u32_e32 v11, v15, v4
	v_min_u32_e32 v14, v14, v41
	v_min_u32_e32 v41, v13, v6
	v_min_u32_e32 v46, v44, v45
	v_min_u32_e32 v47, v3, v12
	v_max3_u32 v0, v23, v32, v0
	v_max3_u32 v1, v18, v26, v1
	v_max3_u32 v5, v34, v25, v5
	v_max3_u32 v18, v31, v20, v41
	v_max3_u32 v6, v27, v13, v6
	v_max3_u32 v13, v24, v35, v14
	v_max3_u32 v14, v36, v37, v47
	v_max3_u32 v3, v38, v3, v12
	v_max3_u32 v12, v19, v28, v46
	v_max3_u32 v19, v39, v44, v45
	v_max3_u32 v8, v30, v8, v43
	v_max3_u32 v11, v29, v22, v11
	v_max3_u32 v4, v33, v15, v4
	v_max3_u32 v9, v21, v42, v9
	v_max3_u32 v2, v17, v2, v10
	v_max3_u32 v7, v16, v7, v40
	v_max_u32_e32 v10, v0, v12
	v_min_u32_e32 v0, v0, v12
	v_max_u32_e32 v12, v1, v19
	v_max_u32_e32 v15, v5, v8
	v_min_u32_e32 v5, v5, v8
	v_max_u32_e32 v8, v18, v11
	v_max_u32_e32 v16, v6, v4
	v_min_u32_e32 v4, v6, v4
	v_max_u32_e32 v6, v13, v9
	v_min_u32_e32 v9, v13, v9
	v_max_u32_e32 v13, v14, v2
	v_min_u32_e32 v2, v14, v2
	v_max_u32_e32 v14, v3, v7
	v_min_u32_e32 v1, v1, v19
	v_min_u32_e32 v11, v18, v11
	v_min_u32_e32 v3, v3, v7
	v_max_u32_e32 v7, v10, v16
	v_min_u32_e32 v10, v10, v16
	v_max_u32_e32 v16, v12, v6
	v_min_u32_e32 v6, v12, v6
	v_max_u32_e32 v12, v15, v13
	v_min_u32_e32 v13, v15, v13
	v_max_u32_e32 v15, v8, v14
	v_min_u32_e32 v8, v8, v14
	v_max_u32_e32 v14, v0, v4
	v_min_u32_e32 v0, v0, v4
	v_max_u32_e32 v4, v1, v9
	v_min_u32_e32 v1, v1, v9
	v_max_u32_e32 v9, v5, v2
	v_min_u32_e32 v2, v5, v2
	v_max_u32_e32 v5, v11, v3
	v_min_u32_e32 v3, v11, v3
	v_max_u32_e32 v11, v7, v12
	v_min_u32_e32 v7, v7, v12
	v_max_u32_e32 v12, v16, v15
	v_min_u32_e32 v15, v16, v15
	v_max_u32_e32 v16, v10, v13
	v_min_u32_e32 v10, v10, v13
	v_max_u32_e32 v13, v6, v8
	v_max_u32_e32 v17, v14, v9
	v_min_u32_e32 v14, v14, v9
	v_max_u32_e32 v9, v4, v5
	v_min_u32_e32 v18, v4, v5
	v_max_u32_e32 v4, v16, v13
	v_min_u32_e32 v5, v16, v13
	v_or_b32_e32 v16, 0x2000, v48
	v_min_u32_e32 v8, v6, v8
	v_max_u32_e32 v19, v0, v2
	v_min_u32_e32 v20, v0, v2
	v_max_u32_e32 v21, v1, v3
	v_min_u32_e32 v22, v1, v3
	v_max_u32_e32 v0, v11, v12
	v_min_u32_e32 v1, v11, v12
	v_max_u32_e32 v2, v7, v15
	v_min_u32_e32 v3, v7, v15
	v_add_u32_e32 v16, v143, v16
	v_max_u32_e32 v6, v10, v8
	v_min_u32_e32 v7, v10, v8
	v_max_u32_e32 v8, v17, v9
	v_min_u32_e32 v9, v17, v9
	v_max_u32_e32 v10, v14, v18
	v_min_u32_e32 v11, v14, v18
	v_max_u32_e32 v12, v19, v21
	v_min_u32_e32 v13, v19, v21
	v_max_u32_e32 v14, v20, v22
	v_min_u32_e32 v15, v20, v22
	v_bfe_u32 v240, v16, 8, 4
	v_lshlrev_b32_e32 v240, 4, v240
	v_xor_b32_e32 v240, v16, v240
	ds_write_b128 v240, v[0:3]
	v_xor_b32_e32 v241, 16, v240
	ds_write_b128 v241, v[4:7]
	v_xor_b32_e32 v241, 32, v240
	ds_write_b128 v241, v[8:11]
	v_xor_b32_e32 v241, 48, v240
	ds_write_b128 v241, v[12:15]
	s_waitcnt lgkmcnt(0)
	s_barrier
	s_and_saveexec_b64 s[24:25], vcc
	s_cbranch_execz .LBB0_886
	v_lshl_add_u32 v60, v142, 8, v143
	v_bfe_u32 v240, v60, 8, 4
	v_lshlrev_b32_e32 v240, 4, v240
	v_xor_b32_e32 v240, v60, v240
	ds_read_b128 v[0:3], v240
	v_xor_b32_e32 v241, 16, v240
	ds_read_b128 v[4:7], v241
	v_xor_b32_e32 v241, 32, v240
	ds_read_b128 v[8:11], v241
	v_xor_b32_e32 v241, 48, v240
	ds_read_b128 v[12:15], v241
	v_xor_b32_e32 v241, 64, v240
	ds_read_b128 v[16:19], v241
	v_xor_b32_e32 v241, 0x50, v240
	ds_read_b128 v[20:23], v241
	v_xor_b32_e32 v241, 0x80, v240
	ds_read_b128 v[24:27], v241
	v_xor_b32_e32 v241, 0x90, v240
	ds_read_b128 v[28:31], v241
	v_xor_b32_e32 v241, 0xc0, v240
	ds_read_b128 v[32:35], v241
	v_xor_b32_e32 v241, 0xd0, v240
	ds_read_b128 v[36:39], v241
	v_xor_b32_e32 v241, 0x60, v240
	ds_read_b128 v[40:43], v241
	v_xor_b32_e32 v241, 0x70, v240
	ds_read_b128 v[44:47], v241
	v_xor_b32_e32 v241, 0xa0, v240
	ds_read_b128 v[48:51], v241
	v_xor_b32_e32 v241, 0xb0, v240
	ds_read_b128 v[52:55], v241
	v_xor_b32_e32 v241, 0xe0, v240
	ds_read_b128 v[56:59], v241
	v_xor_b32_e32 v241, 0xf0, v240
	ds_read_b128 v[60:63], v241
	s_waitcnt lgkmcnt(4)
	v_max_u32_e32 v0, v0, v47
	v_max_u32_e32 v1, v1, v46
	v_max_u32_e32 v2, v2, v45
	v_max_u32_e32 v3, v3, v44
	v_max_u32_e32 v4, v4, v43
	v_max_u32_e32 v5, v5, v42
	v_max_u32_e32 v6, v6, v41
	v_max_u32_e32 v7, v7, v40
	v_max_u32_e32 v8, v8, v23
	v_max_u32_e32 v9, v9, v22
	v_max_u32_e32 v10, v10, v21
	v_max_u32_e32 v11, v11, v20
	v_max_u32_e32 v12, v12, v19
	v_max_u32_e32 v13, v13, v18
	v_max_u32_e32 v14, v14, v17
	v_max_u32_e32 v15, v15, v16
	s_waitcnt lgkmcnt(0)
	v_max_u32_e32 v24, v24, v63
	v_max_u32_e32 v25, v25, v62
	v_max_u32_e32 v26, v26, v61
	v_max_u32_e32 v27, v27, v60
	v_max_u32_e32 v28, v28, v59
	v_max_u32_e32 v29, v29, v58
	v_max_u32_e32 v30, v30, v57
	v_max_u32_e32 v31, v31, v56
	v_max_u32_e32 v39, v48, v39
	v_max_u32_e32 v38, v49, v38
	v_max_u32_e32 v37, v50, v37
	v_max_u32_e32 v36, v51, v36
	v_max_u32_e32 v35, v52, v35
	v_max_u32_e32 v34, v53, v34
	v_max_u32_e32 v33, v54, v33
	v_max_u32_e32 v32, v55, v32
	v_max_u32_e32 v16, v0, v8
	v_min_u32_e32 v0, v0, v8
	v_max_u32_e32 v8, v1, v9
	v_min_u32_e32 v1, v1, v9
	v_max_u32_e32 v9, v2, v10
	v_min_u32_e32 v2, v2, v10
	v_max_u32_e32 v10, v3, v11
	v_min_u32_e32 v3, v3, v11
	v_max_u32_e32 v11, v4, v12
	v_min_u32_e32 v4, v4, v12
	v_max_u32_e32 v12, v5, v13
	v_min_u32_e32 v5, v5, v13
	v_max_u32_e32 v13, v6, v14
	v_min_u32_e32 v6, v6, v14
	v_max_u32_e32 v14, v7, v15
	v_min_u32_e32 v7, v7, v15
	v_max_u32_e32 v40, v24, v39
	v_min_u32_e32 v24, v24, v39
	v_max_u32_e32 v39, v25, v38
	v_min_u32_e32 v25, v25, v38
	v_max_u32_e32 v38, v26, v37
	v_min_u32_e32 v26, v26, v37
	v_max_u32_e32 v37, v27, v36
	v_min_u32_e32 v27, v27, v36
	v_max_u32_e32 v36, v28, v35
	v_min_u32_e32 v28, v28, v35
	v_max_u32_e32 v35, v29, v34
	v_min_u32_e32 v29, v29, v34
	v_max_u32_e32 v34, v30, v33
	v_min_u32_e32 v30, v30, v33
	v_max_u32_e32 v33, v31, v32
	v_min_u32_e32 v31, v31, v32
	v_max_u32_e32 v15, v16, v11
	v_min_u32_e32 v11, v16, v11
	v_max_u32_e32 v16, v8, v12
	v_min_u32_e32 v8, v8, v12
	v_max_u32_e32 v12, v9, v13
	v_min_u32_e32 v9, v9, v13
	v_max_u32_e32 v13, v10, v14
	v_min_u32_e32 v10, v10, v14
	v_max_u32_e32 v14, v0, v4
	v_min_u32_e32 v0, v0, v4
	v_max_u32_e32 v4, v1, v5
	v_min_u32_e32 v1, v1, v5
	v_max_u32_e32 v5, v2, v6
	v_min_u32_e32 v2, v2, v6
	v_max_u32_e32 v6, v3, v7
	v_min_u32_e32 v3, v3, v7
	v_max_u32_e32 v32, v40, v36
	v_min_u32_e32 v36, v40, v36
	v_max_u32_e32 v40, v39, v35
	v_min_u32_e32 v35, v39, v35
	v_max_u32_e32 v39, v38, v34
	v_min_u32_e32 v34, v38, v34
	v_max_u32_e32 v38, v37, v33
	v_min_u32_e32 v33, v37, v33
	v_max_u32_e32 v37, v24, v28
	v_min_u32_e32 v24, v24, v28
	v_max_u32_e32 v28, v25, v29
	v_min_u32_e32 v25, v25, v29
	v_max_u32_e32 v29, v26, v30
	v_min_u32_e32 v26, v26, v30
	v_max_u32_e32 v30, v27, v31
	v_min_u32_e32 v27, v27, v31
	v_max_u32_e32 v7, v15, v12
	v_min_u32_e32 v12, v15, v12
	v_max_u32_e32 v15, v16, v13
	v_min_u32_e32 v13, v16, v13
	v_max_u32_e32 v16, v11, v9
	v_min_u32_e32 v9, v11, v9
	v_max_u32_e32 v11, v8, v10
	v_min_u32_e32 v8, v8, v10
	v_max_u32_e32 v10, v14, v5
	v_min_u32_e32 v5, v14, v5
	v_max_u32_e32 v14, v4, v6
	v_min_u32_e32 v4, v4, v6
	v_max_u32_e32 v6, v0, v2
	v_min_u32_e32 v0, v0, v2
	v_max_u32_e32 v2, v1, v3
	v_min_u32_e32 v1, v1, v3
	v_max_u32_e32 v31, v32, v39
	v_min_u32_e32 v32, v32, v39
	v_max_u32_e32 v39, v40, v38
	v_min_u32_e32 v38, v40, v38
	v_max_u32_e32 v40, v36, v34
	v_min_u32_e32 v34, v36, v34
	v_max_u32_e32 v36, v35, v33
	v_min_u32_e32 v33, v35, v33
	v_max_u32_e32 v35, v37, v29
	v_min_u32_e32 v29, v37, v29
	v_max_u32_e32 v37, v28, v30
	v_min_u32_e32 v28, v28, v30
	v_max_u32_e32 v30, v24, v26
	v_min_u32_e32 v24, v24, v26
	v_max_u32_e32 v26, v25, v27
	v_min_u32_e32 v25, v25, v27
	v_min_u32_e32 v3, v7, v15
	v_min_u32_e32 v17, v12, v13
	v_min_u32_e32 v18, v16, v11
	v_min_u32_e32 v19, v9, v8
	v_min_u32_e32 v20, v10, v14
	v_min_u32_e32 v21, v5, v4
	v_min_u32_e32 v22, v6, v2
	v_min_u32_e32 v23, v0, v1
	v_min_u32_e32 v27, v31, v39
	v_min_u32_e32 v41, v32, v38
	v_min_u32_e32 v42, v40, v36
	v_min_u32_e32 v43, v34, v33
	v_min_u32_e32 v44, v35, v37
	v_min_u32_e32 v45, v29, v28
	v_min_u32_e32 v46, v30, v26
	v_min_u32_e32 v47, v24, v25
	v_max3_u32 v7, v7, v15, v47
	v_max3_u32 v3, v3, v24, v25
	v_max3_u32 v12, v12, v13, v46
	v_max3_u32 v13, v17, v30, v26
	v_max3_u32 v11, v16, v11, v45
	v_max3_u32 v15, v18, v29, v28
	v_max3_u32 v8, v9, v8, v44
	v_max3_u32 v9, v19, v35, v37
	v_max3_u32 v10, v10, v14, v43
	v_max3_u32 v14, v20, v34, v33
	v_max3_u32 v4, v5, v4, v42
	v_max3_u32 v5, v21, v40, v36
	v_max3_u32 v2, v6, v2, v41
	v_max3_u32 v6, v22, v32, v38
	v_max3_u32 v0, v0, v1, v27
	v_max3_u32 v1, v23, v31, v39
	v_max_u32_e32 v16, v7, v10
	v_min_u32_e32 v7, v7, v10
	v_max_u32_e32 v10, v3, v14
	v_min_u32_e32 v3, v3, v14
	v_max_u32_e32 v14, v12, v4
	v_min_u32_e32 v4, v12, v4
	v_max_u32_e32 v12, v13, v5
	v_min_u32_e32 v5, v13, v5
	v_max_u32_e32 v13, v11, v2
	v_min_u32_e32 v2, v11, v2
	v_max_u32_e32 v11, v15, v6
	v_min_u32_e32 v6, v15, v6
	v_max_u32_e32 v15, v8, v0
	v_min_u32_e32 v0, v8, v0
	v_max_u32_e32 v8, v9, v1
	v_min_u32_e32 v1, v9, v1
	v_max_u32_e32 v9, v16, v13
	v_min_u32_e32 v13, v16, v13
	v_max_u32_e32 v16, v10, v11
	v_min_u32_e32 v10, v10, v11
	v_max_u32_e32 v11, v14, v15
	v_min_u32_e32 v14, v14, v15
	v_max_u32_e32 v15, v12, v8
	v_min_u32_e32 v8, v12, v8
	v_max_u32_e32 v12, v7, v2
	v_min_u32_e32 v2, v7, v2
	v_max_u32_e32 v7, v3, v6
	v_min_u32_e32 v3, v3, v6
	v_max_u32_e32 v6, v4, v0
	v_min_u32_e32 v0, v4, v0
	v_max_u32_e32 v4, v5, v1
	v_min_u32_e32 v1, v5, v1
	v_max_u32_e32 v5, v9, v11
	v_min_u32_e32 v9, v9, v11
	v_max_u32_e32 v11, v16, v15
	v_min_u32_e32 v15, v16, v15
	v_max_u32_e32 v16, v13, v14
	v_min_u32_e32 v13, v13, v14
	v_max_u32_e32 v14, v10, v8
	v_min_u32_e32 v8, v10, v8
	v_max_u32_e32 v10, v12, v6
	v_max_u32_e32 v17, v7, v4
	v_min_u32_e32 v18, v7, v4
	v_max_u32_e32 v19, v2, v0
	v_min_u32_e32 v20, v2, v0
	v_max_u32_e32 v21, v3, v1
	v_min_u32_e32 v22, v3, v1
	v_max_u32_e32 v0, v5, v11
	v_min_u32_e32 v1, v5, v11
	v_max_u32_e32 v4, v16, v14
	v_min_u32_e32 v5, v16, v14
	v_or_b32_e32 v16, s46, v142
	v_min_u32_e32 v12, v12, v6
	v_max_u32_e32 v2, v9, v15
	v_min_u32_e32 v3, v9, v15
	v_max_u32_e32 v6, v13, v8
	v_min_u32_e32 v7, v13, v8
	v_max_u32_e32 v8, v10, v17
	v_min_u32_e32 v9, v10, v17
	v_ashrrev_i32_e32 v17, 31, v16
	v_lshlrev_b64 v[16:17], 10, v[16:17]
	s_lshl_b32 s22, s22, 4
	v_lshl_add_u64 v[16:17], s[18:19], 0, v[16:17]
	s_ashr_i32 s23, s22, 31
	v_lshl_add_u64 v[16:17], s[22:23], 2, v[16:17]
	v_max_u32_e32 v10, v12, v18
	v_min_u32_e32 v11, v12, v18
	v_max_u32_e32 v12, v19, v21
	v_min_u32_e32 v13, v19, v21
	v_max_u32_e32 v14, v20, v22
	v_min_u32_e32 v15, v20, v22
	global_store_dwordx4 v[16:17], v[0:3], off
	global_store_dwordx4 v[16:17], v[4:7], off offset:16
	global_store_dwordx4 v[16:17], v[8:11], off offset:32
	global_store_dwordx4 v[16:17], v[12:15], off offset:48
	s_branch .LBB0_886

.LBB0_995:
	v_add_u32_e32 v68, s28, v132
	ds_read_b128 v[40:43], v68
	ds_read_b128 v[44:47], v68 offset:256
	ds_read_b128 v[48:51], v68 offset:512
	ds_read_b128 v[52:55], v68 offset:768
	ds_read_b128 v[56:59], v68 offset:1024
	ds_read_b128 v[60:63], v68 offset:1280
	ds_read_b128 v[64:67], v68 offset:1536
	ds_read_b128 v[68:71], v68 offset:1792
	s_waitcnt lgkmcnt(7)
	v_cmp_gt_u32_e32 vcc, v40, v29
	s_waitcnt lgkmcnt(6)
	v_cmp_gt_u32_e64 s[14:15], v46, v30
	s_waitcnt lgkmcnt(5)
	v_cmp_gt_u32_e64 s[16:17], v50, v31
	v_cndmask_b32_e64 v40, 0, 1, vcc
	v_cmp_gt_u32_e32 vcc, v42, v29
	s_waitcnt lgkmcnt(4)
	v_cmp_gt_u32_e64 s[18:19], v54, v33
	s_waitcnt lgkmcnt(3)
	v_cmp_gt_u32_e64 s[20:21], v58, v34
	v_cndmask_b32_e64 v42, 0, 1, vcc
	v_cmp_gt_u32_e32 vcc, v44, v30
	s_waitcnt lgkmcnt(2)
	v_cmp_gt_u32_e64 s[22:23], v62, v36
	s_waitcnt lgkmcnt(1)
	v_cmp_gt_u32_e64 s[24:25], v66, v37
	v_cndmask_b32_e64 v44, 0, 1, vcc
	v_cmp_gt_u32_e32 vcc, v45, v30
	v_cndmask_b32_e64 v45, 0, 1, s[14:15]
	v_cmp_gt_u32_e64 s[14:15], v48, v31
	v_cndmask_b32_e64 v48, 0, 1, s[16:17]
	v_cmp_gt_u32_e64 s[16:17], v52, v33
	v_cndmask_b32_e64 v46, 0, 1, s[14:15]
	v_cmp_gt_u32_e64 s[14:15], v49, v31
	v_cndmask_b32_e64 v49, 0, 1, s[16:17]
	v_cmp_gt_u32_e64 s[16:17], v53, v33
	v_cndmask_b32_e64 v50, 0, 1, s[18:19]
	v_cmp_gt_u32_e64 s[18:19], v56, v34
	v_cndmask_b32_e64 v53, 0, 1, s[20:21]
	v_cmp_gt_u32_e64 s[20:21], v60, v36
	v_cndmask_b32_e64 v56, 0, 1, s[22:23]
	v_cmp_gt_u32_e64 s[22:23], v64, v37
	v_cndmask_b32_e64 v58, 0, 1, s[24:25]
	s_waitcnt lgkmcnt(0)
	v_cmp_gt_u32_e64 s[24:25], v68, v39
	v_cmp_gt_u32_e64 s[26:27], v70, v39
	v_cndmask_b32_e64 v52, 0, 1, s[18:19]
	v_cmp_gt_u32_e64 s[18:19], v57, v34
	v_cndmask_b32_e64 v54, 0, 1, s[20:21]
	v_cmp_gt_u32_e64 s[20:21], v61, v36
	v_cndmask_b32_e64 v57, 0, 1, s[22:23]
	v_cmp_gt_u32_e64 s[22:23], v65, v37
	v_cndmask_b32_e64 v60, 0, 1, s[24:25]
	v_cmp_gt_u32_e64 s[24:25], v69, v39
	v_cndmask_b32_e64 v61, 0, 1, s[26:27]
	v_cmp_gt_u32_e64 s[26:27], v41, v29
	v_addc_co_u32_e32 v35, vcc, v35, v44, vcc
	s_nop 0
	v_addc_co_u32_e64 v38, s[26:27], v38, v40, s[26:27]
	v_addc_co_u32_e64 v32, s[14:15], v32, v46, s[14:15]
	v_addc_co_u32_e64 v28, s[16:17], v28, v49, s[16:17]
	v_addc_co_u32_e64 v24, s[18:19], v24, v52, s[18:19]
	v_addc_co_u32_e64 v19, s[20:21], v19, v54, s[20:21]
	v_addc_co_u32_e64 v12, s[22:23], v12, v57, s[22:23]
	v_addc_co_u32_e64 v5, s[24:25], v5, v60, s[24:25]
	s_add_i32 s28, s28, 16
	v_cmp_gt_u32_e32 vcc, v47, v30
	v_cmp_gt_u32_e64 s[14:15], v51, v31
	v_cmp_gt_u32_e64 s[16:17], v55, v33
	v_cmp_gt_u32_e64 s[18:19], v59, v34
	v_cmp_gt_u32_e64 s[20:21], v63, v36
	v_cmp_gt_u32_e64 s[22:23], v67, v37
	v_cmp_gt_u32_e64 s[24:25], v71, v39
	v_cmp_gt_u32_e64 s[26:27], v43, v29
	s_cmpk_eq_i32 s28, 0xd0
	v_addc_co_u32_e32 v35, vcc, v35, v45, vcc
	v_addc_co_u32_e64 v38, s[26:27], v38, v42, s[26:27]
	v_addc_co_u32_e64 v32, vcc, v32, v48, s[14:15]
	v_addc_co_u32_e64 v28, vcc, v28, v50, s[16:17]
	v_addc_co_u32_e64 v24, vcc, v24, v53, s[18:19]
	v_addc_co_u32_e64 v19, vcc, v19, v56, s[20:21]
	v_addc_co_u32_e64 v12, vcc, v12, v58, s[22:23]
	v_addc_co_u32_e64 v5, vcc, v5, v61, s[24:25]
	s_cbranch_scc0 .LBB0_995
	s_mov_b32 s77, 0
	s_movk_i32 s78, 0x7f
	v_readfirstlane_b32 s14, v27
	v_cmp_gt_i32_e32 vcc, 16, v38
	v_mov_b32_e32 v143, 0
	v_subrev_f32_e32 v27, s14, v27
	v_mul_f32_e32 v27, 0x3fb8aa3b, v27
	v_exp_f32_e32 v27, v27
	s_and_b64 s[14:15], s[4:5], vcc
	v_lshl_add_u32 v142, v38, 2, v127
	v_xor_b32_e32 v184, v25, v26
	v_and_b32_e32 v184, 64, v184
	v_cmp_eq_u32_e32 vcc, 0, v184
	s_and_b64 s[72:73], vcc, s[14:15]
	s_andn2_b64 s[74:75], s[14:15], vcc
	v_mbcnt_lo_u32_b32 v184, s72, 0
	v_mbcnt_hi_u32_b32 v184, s73, v184
	v_mbcnt_lo_u32_b32 v185, s74, 0
	v_mbcnt_hi_u32_b32 v185, s75, v185
	v_add_u32_e32 v184, s77, v184
	v_sub_u32_e32 v185, s78, v185
	v_cndmask_b32_e32 v184, v185, v184, vcc
	v_lshl_add_u32 v142, v184, 2, v127
	s_bcnt1_i32_b64 s76, s[72:73]
	s_add_u32 s77, s77, s76
	s_bcnt1_i32_b64 s76, s[74:75]
	s_sub_u32 s78, s78, s76
	v_mov_b32_e32 v144, 0
	v_cndmask_b32_e64 v29, 0, v27, s[14:15]
	v_mov_b32_e32 v30, v29
	s_nop 1
	v_permlane32_swap_b32_e32 v29, v30
	v_add_f32_e32 v29, v29, v30
	v_mov_b32_e32 v30, v29
	s_nop 1
	v_permlane16_swap_b32_e32 v29, v30
	v_add_f32_e32 v29, v29, v30
	v_mov_b32_e32 v145, 0
	s_nop 0
	v_add_f32_dpp v29, v29, v29 row_ror:8 row_mask:0xf bank_mask:0xf bound_ctrl:1
	s_nop 1
	v_add_f32_dpp v29, v29, v29 row_ror:4 row_mask:0xf bank_mask:0xf bound_ctrl:1
	s_nop 1
	v_add_f32_dpp v29, v29, v29 quad_perm:[2,3,0,1] row_mask:0xf bank_mask:0xf bound_ctrl:1
	s_nop 1
	v_mov_b32_dpp v30, v29 quad_perm:[1,0,3,2] row_mask:0xf bank_mask:0xf bound_ctrl:1
	s_and_saveexec_b64 s[16:17], s[14:15]
	s_cbranch_execz .LBB0_998
	v_lshlrev_b32_e32 v25, 7, v25
	v_and_b32_e32 v26, 0x7f, v26
	v_and_or_b32 v25, v25, s49, v26
	v_lshlrev_b32_e32 v26, 2, v25
	global_load_dword v145, v26, s[36:37]
	global_load_dword v144, v26, s[38:39]
	v_add_f32_e32 v26, v29, v30
	v_div_scale_f32 v29, s[18:19], v26, v26, v27
	v_rcp_f32_e32 v30, v29
	s_nop 0
	v_fma_f32 v31, -v29, v30, 1.0
	v_fmac_f32_e32 v30, v31, v30
	v_div_scale_f32 v31, vcc, v27, v26, v27
	v_mul_f32_e32 v33, v31, v30
	v_fma_f32 v34, -v29, v33, v31
	v_fmac_f32_e32 v33, v34, v30
	v_fma_f32 v29, -v29, v33, v31
	v_div_fmas_f32 v29, v29, v30, v33
	v_div_fixup_f32 v26, v29, v26, v27
	ds_write2st64_b32 v142, v25, v26 offset0:12 offset1:14
.LBB0_998:
	s_or_b64 exec, exec, s[16:17]
	v_readfirstlane_b32 s16, v23
	v_cmp_gt_i32_e32 vcc, 16, v35
	v_lshl_add_u32 v27, v35, 2, v127
	v_subrev_f32_e32 v23, s16, v23
	v_mul_f32_e32 v23, 0x3fb8aa3b, v23
	v_exp_f32_e32 v23, v23
	s_and_b64 s[16:17], s[4:5], vcc
	v_add_u32_e32 v146, 64, v27
	v_xor_b32_e32 v184, v20, v21
	v_and_b32_e32 v184, 64, v184
	v_cmp_eq_u32_e32 vcc, 0, v184
	s_and_b64 s[72:73], vcc, s[16:17]
	s_andn2_b64 s[74:75], s[16:17], vcc
	v_mbcnt_lo_u32_b32 v184, s72, 0
	v_mbcnt_hi_u32_b32 v184, s73, v184
	v_mbcnt_lo_u32_b32 v185, s74, 0
	v_mbcnt_hi_u32_b32 v185, s75, v185
	v_add_u32_e32 v184, s77, v184
	v_sub_u32_e32 v185, s78, v185
	v_cndmask_b32_e32 v184, v185, v184, vcc
	v_lshl_add_u32 v146, v184, 2, v127
	s_bcnt1_i32_b64 s76, s[72:73]
	s_add_u32 s77, s77, s76
	s_bcnt1_i32_b64 s76, s[74:75]
	s_sub_u32 s78, s78, s76
	v_mov_b32_e32 v147, 0
	v_cndmask_b32_e64 v25, 0, v23, s[16:17]
	v_mov_b32_e32 v26, v25
	s_nop 1
	v_permlane32_swap_b32_e32 v25, v26
	v_add_f32_e32 v25, v25, v26
	v_mov_b32_e32 v26, v25
	s_nop 1
	v_permlane16_swap_b32_e32 v25, v26
	v_add_f32_e32 v25, v25, v26
	s_nop 1
	v_add_f32_dpp v25, v25, v25 row_ror:8 row_mask:0xf bank_mask:0xf bound_ctrl:1
	s_nop 1
	v_add_f32_dpp v25, v25, v25 row_ror:4 row_mask:0xf bank_mask:0xf bound_ctrl:1
	s_nop 1
	v_add_f32_dpp v25, v25, v25 quad_perm:[2,3,0,1] row_mask:0xf bank_mask:0xf bound_ctrl:1
	s_nop 1
	v_mov_b32_dpp v26, v25 quad_perm:[1,0,3,2] row_mask:0xf bank_mask:0xf bound_ctrl:1
	s_and_saveexec_b64 s[18:19], s[16:17]
	s_cbranch_execz .LBB0_1000
	v_lshlrev_b32_e32 v20, 7, v20
	v_and_b32_e32 v21, 0x7f, v21
	v_and_or_b32 v20, v20, s49, v21
	v_lshlrev_b32_e32 v21, 2, v20
	global_load_dword v147, v21, s[36:37]
	global_load_dword v143, v21, s[38:39]
	v_add_f32_e32 v21, v25, v26
	v_div_scale_f32 v25, s[20:21], v21, v21, v23
	v_rcp_f32_e32 v26, v25
	s_nop 0
	v_fma_f32 v27, -v25, v26, 1.0
	v_fmac_f32_e32 v26, v27, v26
	v_div_scale_f32 v27, vcc, v23, v21, v23
	v_mul_f32_e32 v29, v27, v26
	v_fma_f32 v30, -v25, v29, v27
	v_fmac_f32_e32 v29, v30, v26
	v_fma_f32 v25, -v25, v29, v27
	v_div_fmas_f32 v25, v25, v26, v29
	v_div_fixup_f32 v21, v25, v21, v23
	ds_write2st64_b32 v146, v20, v21 offset0:12 offset1:14
.LBB0_1000:
	s_or_b64 exec, exec, s[18:19]
	v_readfirstlane_b32 s18, v22
	v_cmp_gt_i32_e32 vcc, 16, v32
	v_lshl_add_u32 v23, v32, 2, v127
	v_subrev_f32_e32 v20, s18, v22
	v_mul_f32_e32 v20, 0x3fb8aa3b, v20
	v_exp_f32_e32 v20, v20
	s_and_b64 s[18:19], s[4:5], vcc
	v_mov_b32_e32 v149, 0
	v_add_u32_e32 v148, 0x80, v23
	v_xor_b32_e32 v184, v17, v18
	v_and_b32_e32 v184, 64, v184
	v_cmp_eq_u32_e32 vcc, 0, v184
	s_and_b64 s[72:73], vcc, s[18:19]
	s_andn2_b64 s[74:75], s[18:19], vcc
	v_mbcnt_lo_u32_b32 v184, s72, 0
	v_mbcnt_hi_u32_b32 v184, s73, v184
	v_mbcnt_lo_u32_b32 v185, s74, 0
	v_mbcnt_hi_u32_b32 v185, s75, v185
	v_add_u32_e32 v184, s77, v184
	v_sub_u32_e32 v185, s78, v185
	v_cndmask_b32_e32 v184, v185, v184, vcc
	v_lshl_add_u32 v148, v184, 2, v127
	s_bcnt1_i32_b64 s76, s[72:73]
	s_add_u32 s77, s77, s76
	s_bcnt1_i32_b64 s76, s[74:75]
	s_sub_u32 s78, s78, s76
	v_cndmask_b32_e64 v21, 0, v20, s[18:19]
	v_mov_b32_e32 v22, v21
	s_nop 1
	v_permlane32_swap_b32_e32 v21, v22
	v_add_f32_e32 v21, v21, v22
	v_mov_b32_e32 v22, v21
	s_nop 1
	v_permlane16_swap_b32_e32 v21, v22
	v_add_f32_e32 v21, v21, v22
	v_mov_b32_e32 v150, 0
	v_mov_b32_e32 v151, 0
	v_add_f32_dpp v21, v21, v21 row_ror:8 row_mask:0xf bank_mask:0xf bound_ctrl:1
	s_nop 1
	v_add_f32_dpp v21, v21, v21 row_ror:4 row_mask:0xf bank_mask:0xf bound_ctrl:1
	s_nop 1
	v_add_f32_dpp v21, v21, v21 quad_perm:[2,3,0,1] row_mask:0xf bank_mask:0xf bound_ctrl:1
	s_nop 1
	v_mov_b32_dpp v22, v21 quad_perm:[1,0,3,2] row_mask:0xf bank_mask:0xf bound_ctrl:1
	s_and_saveexec_b64 s[20:21], s[18:19]
	s_cbranch_execz .LBB0_1002
	v_lshlrev_b32_e32 v17, 7, v17
	v_and_b32_e32 v18, 0x7f, v18
	v_and_or_b32 v17, v17, s49, v18
	v_lshlrev_b32_e32 v18, 2, v17
	global_load_dword v151, v18, s[36:37]
	global_load_dword v150, v18, s[38:39]
	v_add_f32_e32 v18, v21, v22
	v_div_scale_f32 v21, s[22:23], v18, v18, v20
	v_rcp_f32_e32 v22, v21
	s_nop 0
	v_fma_f32 v23, -v21, v22, 1.0
	v_fmac_f32_e32 v22, v23, v22
	v_div_scale_f32 v23, vcc, v20, v18, v20
	v_mul_f32_e32 v25, v23, v22
	v_fma_f32 v26, -v21, v25, v23
	v_fmac_f32_e32 v25, v26, v22
	v_fma_f32 v21, -v21, v25, v23
	v_div_fmas_f32 v21, v21, v22, v25
	v_div_fixup_f32 v18, v21, v18, v20
	ds_write2st64_b32 v148, v17, v18 offset0:12 offset1:14
.LBB0_1002:
	s_or_b64 exec, exec, s[20:21]
	v_readfirstlane_b32 s20, v16
	v_cmp_gt_i32_e32 vcc, 16, v28
	v_lshl_add_u32 v20, v28, 2, v127
	v_subrev_f32_e32 v16, s20, v16
	v_mul_f32_e32 v16, 0x3fb8aa3b, v16
	v_exp_f32_e32 v16, v16
	s_and_b64 s[20:21], s[4:5], vcc
	v_add_u32_e32 v152, 0xc0, v20
	v_xor_b32_e32 v184, v13, v14
	v_and_b32_e32 v184, 64, v184
	v_cmp_eq_u32_e32 vcc, 0, v184
	s_and_b64 s[72:73], vcc, s[20:21]
	s_andn2_b64 s[74:75], s[20:21], vcc
	v_mbcnt_lo_u32_b32 v184, s72, 0
	v_mbcnt_hi_u32_b32 v184, s73, v184
	v_mbcnt_lo_u32_b32 v185, s74, 0
	v_mbcnt_hi_u32_b32 v185, s75, v185
	v_add_u32_e32 v184, s77, v184
	v_sub_u32_e32 v185, s78, v185
	v_cndmask_b32_e32 v184, v185, v184, vcc
	v_lshl_add_u32 v152, v184, 2, v127
	s_bcnt1_i32_b64 s76, s[72:73]
	s_add_u32 s77, s77, s76
	s_bcnt1_i32_b64 s76, s[74:75]
	s_sub_u32 s78, s78, s76
	v_mov_b32_e32 v153, 0
	v_cndmask_b32_e64 v17, 0, v16, s[20:21]
	v_mov_b32_e32 v18, v17
	s_nop 1
	v_permlane32_swap_b32_e32 v17, v18
	v_add_f32_e32 v17, v17, v18
	v_mov_b32_e32 v18, v17
	s_nop 1
	v_permlane16_swap_b32_e32 v17, v18
	v_add_f32_e32 v17, v17, v18
	s_nop 1
	v_add_f32_dpp v17, v17, v17 row_ror:8 row_mask:0xf bank_mask:0xf bound_ctrl:1
	s_nop 1
	v_add_f32_dpp v17, v17, v17 row_ror:4 row_mask:0xf bank_mask:0xf bound_ctrl:1
	s_nop 1
	v_add_f32_dpp v17, v17, v17 quad_perm:[2,3,0,1] row_mask:0xf bank_mask:0xf bound_ctrl:1
	s_nop 1
	v_mov_b32_dpp v18, v17 quad_perm:[1,0,3,2] row_mask:0xf bank_mask:0xf bound_ctrl:1
	s_and_saveexec_b64 s[22:23], s[20:21]
	s_cbranch_execz .LBB0_1004
	v_lshlrev_b32_e32 v13, 7, v13
	v_and_b32_e32 v14, 0x7f, v14
	v_and_or_b32 v13, v13, s49, v14
	v_lshlrev_b32_e32 v14, 2, v13
	global_load_dword v153, v14, s[36:37]
	global_load_dword v149, v14, s[38:39]
	v_add_f32_e32 v14, v17, v18
	v_div_scale_f32 v17, s[24:25], v14, v14, v16
	v_rcp_f32_e32 v18, v17
	s_nop 0
	v_fma_f32 v20, -v17, v18, 1.0
	v_fmac_f32_e32 v18, v20, v18
	v_div_scale_f32 v20, vcc, v16, v14, v16
	v_mul_f32_e32 v21, v20, v18
	v_fma_f32 v22, -v17, v21, v20
	v_fmac_f32_e32 v21, v22, v18
	v_fma_f32 v17, -v17, v21, v20
	v_div_fmas_f32 v17, v17, v18, v21
	v_div_fixup_f32 v14, v17, v14, v16
	ds_write2st64_b32 v152, v13, v14 offset0:12 offset1:14
.LBB0_1004:
	s_or_b64 exec, exec, s[22:23]
	v_readfirstlane_b32 s22, v15
	v_cmp_gt_i32_e32 vcc, 16, v24
	v_mov_b32_e32 v155, 0
	v_subrev_f32_e32 v13, s22, v15
	v_mul_f32_e32 v13, 0x3fb8aa3b, v13
	v_exp_f32_e32 v13, v13
	s_and_b64 s[22:23], s[4:5], vcc
	v_lshl_add_u32 v154, v24, 2, v127
	v_xor_b32_e32 v184, v10, v11
	v_and_b32_e32 v184, 64, v184
	v_cmp_eq_u32_e32 vcc, 0, v184
	s_and_b64 s[72:73], vcc, s[22:23]
	s_andn2_b64 s[74:75], s[22:23], vcc
	v_mbcnt_lo_u32_b32 v184, s72, 0
	v_mbcnt_hi_u32_b32 v184, s73, v184
	v_mbcnt_lo_u32_b32 v185, s74, 0
	v_mbcnt_hi_u32_b32 v185, s75, v185
	v_add_u32_e32 v184, s77, v184
	v_sub_u32_e32 v185, s78, v185
	v_cndmask_b32_e32 v184, v185, v184, vcc
	v_lshl_add_u32 v154, v184, 2, v127
	s_bcnt1_i32_b64 s76, s[72:73]
	s_add_u32 s77, s77, s76
	s_bcnt1_i32_b64 s76, s[74:75]
	s_sub_u32 s78, s78, s76
	v_mov_b32_e32 v156, 0
	v_cndmask_b32_e64 v14, 0, v13, s[22:23]
	v_mov_b32_e32 v15, v14
	s_nop 1
	v_permlane32_swap_b32_e32 v14, v15
	v_add_f32_e32 v14, v14, v15
	v_mov_b32_e32 v15, v14
	s_nop 1
	v_permlane16_swap_b32_e32 v14, v15
	v_add_f32_e32 v14, v14, v15
	v_mov_b32_e32 v157, 0
	s_nop 0
	v_add_f32_dpp v14, v14, v14 row_ror:8 row_mask:0xf bank_mask:0xf bound_ctrl:1
	s_nop 1
	v_add_f32_dpp v14, v14, v14 row_ror:4 row_mask:0xf bank_mask:0xf bound_ctrl:1
	s_nop 1
	v_add_f32_dpp v14, v14, v14 quad_perm:[2,3,0,1] row_mask:0xf bank_mask:0xf bound_ctrl:1
	s_nop 1
	v_mov_b32_dpp v15, v14 quad_perm:[1,0,3,2] row_mask:0xf bank_mask:0xf bound_ctrl:1
	s_and_saveexec_b64 s[24:25], s[22:23]
	s_cbranch_execz .LBB0_1006
	v_lshlrev_b32_e32 v10, 7, v10
	v_and_b32_e32 v11, 0x7f, v11
	v_and_or_b32 v10, v10, s49, v11
	v_lshlrev_b32_e32 v11, 2, v10
	global_load_dword v157, v11, s[36:37]
	global_load_dword v156, v11, s[38:39]
	v_add_f32_e32 v11, v14, v15
	v_div_scale_f32 v14, s[26:27], v11, v11, v13
	v_rcp_f32_e32 v15, v14
	s_nop 0
	v_fma_f32 v16, -v14, v15, 1.0
	v_fmac_f32_e32 v15, v16, v15
	v_div_scale_f32 v16, vcc, v13, v11, v13
	v_mul_f32_e32 v17, v16, v15
	v_fma_f32 v18, -v14, v17, v16
	v_fmac_f32_e32 v17, v18, v15
	v_fma_f32 v14, -v14, v17, v16
	v_div_fmas_f32 v14, v14, v15, v17
	v_div_fixup_f32 v11, v14, v11, v13
	ds_write2st64_b32 v154, v10, v11 offset0:12 offset1:14
.LBB0_1006:
	s_or_b64 exec, exec, s[24:25]
	v_readfirstlane_b32 s24, v9
	v_cmp_gt_i32_e32 vcc, 16, v19
	v_lshl_add_u32 v13, v19, 2, v127
	v_subrev_f32_e32 v9, s24, v9
	v_mul_f32_e32 v9, 0x3fb8aa3b, v9
	v_exp_f32_e32 v9, v9
	s_and_b64 s[24:25], s[4:5], vcc
	v_add_u32_e32 v158, 64, v13
	v_xor_b32_e32 v184, v6, v7
	v_and_b32_e32 v184, 64, v184
	v_cmp_eq_u32_e32 vcc, 0, v184
	s_and_b64 s[72:73], vcc, s[24:25]
	s_andn2_b64 s[74:75], s[24:25], vcc
	v_mbcnt_lo_u32_b32 v184, s72, 0
	v_mbcnt_hi_u32_b32 v184, s73, v184
	v_mbcnt_lo_u32_b32 v185, s74, 0
	v_mbcnt_hi_u32_b32 v185, s75, v185
	v_add_u32_e32 v184, s77, v184
	v_sub_u32_e32 v185, s78, v185
	v_cndmask_b32_e32 v184, v185, v184, vcc
	v_lshl_add_u32 v158, v184, 2, v127
	s_bcnt1_i32_b64 s76, s[72:73]
	s_add_u32 s77, s77, s76
	s_bcnt1_i32_b64 s76, s[74:75]
	s_sub_u32 s78, s78, s76
	v_mov_b32_e32 v159, 0
	v_cndmask_b32_e64 v10, 0, v9, s[24:25]
	v_mov_b32_e32 v11, v10
	s_nop 1
	v_permlane32_swap_b32_e32 v10, v11
	v_add_f32_e32 v10, v10, v11
	v_mov_b32_e32 v11, v10
	s_nop 1
	v_permlane16_swap_b32_e32 v10, v11
	v_add_f32_e32 v10, v10, v11
	s_nop 1
	v_add_f32_dpp v10, v10, v10 row_ror:8 row_mask:0xf bank_mask:0xf bound_ctrl:1
	s_nop 1
	v_add_f32_dpp v10, v10, v10 row_ror:4 row_mask:0xf bank_mask:0xf bound_ctrl:1
	s_nop 1
	v_add_f32_dpp v10, v10, v10 quad_perm:[2,3,0,1] row_mask:0xf bank_mask:0xf bound_ctrl:1
	s_nop 1
	v_mov_b32_dpp v11, v10 quad_perm:[1,0,3,2] row_mask:0xf bank_mask:0xf bound_ctrl:1
	s_and_saveexec_b64 s[26:27], s[24:25]
	s_cbranch_execz .LBB0_1008
	v_lshlrev_b32_e32 v6, 7, v6
	v_and_b32_e32 v7, 0x7f, v7
	v_and_or_b32 v6, v6, s49, v7
	v_lshlrev_b32_e32 v7, 2, v6
	global_load_dword v159, v7, s[36:37]
	global_load_dword v155, v7, s[38:39]
	v_add_f32_e32 v7, v10, v11
	v_div_scale_f32 v10, s[28:29], v7, v7, v9
	v_rcp_f32_e32 v11, v10
	s_nop 0
	v_fma_f32 v13, -v10, v11, 1.0
	v_fmac_f32_e32 v11, v13, v11
	v_div_scale_f32 v13, vcc, v9, v7, v9
	v_mul_f32_e32 v14, v13, v11
	v_fma_f32 v15, -v10, v14, v13
	v_fmac_f32_e32 v14, v15, v11
	v_fma_f32 v10, -v10, v14, v13
	v_div_fmas_f32 v10, v10, v11, v14
	v_div_fixup_f32 v7, v10, v7, v9
	ds_write2st64_b32 v158, v6, v7 offset0:12 offset1:14
.LBB0_1008:
	s_or_b64 exec, exec, s[26:27]
	v_readfirstlane_b32 s26, v8
	v_cmp_gt_i32_e32 vcc, 16, v12
	v_lshl_add_u32 v9, v12, 2, v127
	v_subrev_f32_e32 v6, s26, v8
	v_mul_f32_e32 v6, 0x3fb8aa3b, v6
	v_exp_f32_e32 v6, v6
	s_and_b64 s[26:27], s[4:5], vcc
	v_mov_b32_e32 v161, 0
	v_add_u32_e32 v160, 0x80, v9
	v_xor_b32_e32 v184, v3, v4
	v_and_b32_e32 v184, 64, v184
	v_cmp_eq_u32_e32 vcc, 0, v184
	s_and_b64 s[72:73], vcc, s[26:27]
	s_andn2_b64 s[74:75], s[26:27], vcc
	v_mbcnt_lo_u32_b32 v184, s72, 0
	v_mbcnt_hi_u32_b32 v184, s73, v184
	v_mbcnt_lo_u32_b32 v185, s74, 0
	v_mbcnt_hi_u32_b32 v185, s75, v185
	v_add_u32_e32 v184, s77, v184
	v_sub_u32_e32 v185, s78, v185
	v_cndmask_b32_e32 v184, v185, v184, vcc
	v_lshl_add_u32 v160, v184, 2, v127
	s_bcnt1_i32_b64 s76, s[72:73]
	s_add_u32 s77, s77, s76
	s_bcnt1_i32_b64 s76, s[74:75]
	s_sub_u32 s78, s78, s76
	v_cndmask_b32_e64 v7, 0, v6, s[26:27]
	v_mov_b32_e32 v8, v7
	s_nop 1
	v_permlane32_swap_b32_e32 v7, v8
	v_add_f32_e32 v7, v7, v8
	v_mov_b32_e32 v8, v7
	s_nop 1
	v_permlane16_swap_b32_e32 v7, v8
	v_add_f32_e32 v7, v7, v8
	v_mov_b32_e32 v162, 0
	v_mov_b32_e32 v163, 0
	v_add_f32_dpp v7, v7, v7 row_ror:8 row_mask:0xf bank_mask:0xf bound_ctrl:1
	s_nop 1
	v_add_f32_dpp v7, v7, v7 row_ror:4 row_mask:0xf bank_mask:0xf bound_ctrl:1
	s_nop 1
	v_add_f32_dpp v7, v7, v7 quad_perm:[2,3,0,1] row_mask:0xf bank_mask:0xf bound_ctrl:1
	s_nop 1
	v_mov_b32_dpp v8, v7 quad_perm:[1,0,3,2] row_mask:0xf bank_mask:0xf bound_ctrl:1
	s_and_saveexec_b64 s[28:29], s[26:27]
	s_cbranch_execz .LBB0_1010
	v_lshlrev_b32_e32 v3, 7, v3
	v_and_b32_e32 v4, 0x7f, v4
	v_and_or_b32 v3, v3, s49, v4
	v_lshlrev_b32_e32 v4, 2, v3
	global_load_dword v163, v4, s[36:37]
	global_load_dword v162, v4, s[38:39]
	v_add_f32_e32 v4, v7, v8
	v_div_scale_f32 v7, s[42:43], v4, v4, v6
	v_rcp_f32_e32 v8, v7
	s_nop 0
	v_fma_f32 v9, -v7, v8, 1.0
	v_fmac_f32_e32 v8, v9, v8
	v_div_scale_f32 v9, vcc, v6, v4, v6
	v_mul_f32_e32 v10, v9, v8
	v_fma_f32 v11, -v7, v10, v9
	v_fmac_f32_e32 v10, v11, v8
	v_fma_f32 v7, -v7, v10, v9
	v_div_fmas_f32 v7, v7, v8, v10
	v_div_fixup_f32 v4, v7, v4, v6
	ds_write2st64_b32 v160, v3, v4 offset0:12 offset1:14
.LBB0_1010:
	s_or_b64 exec, exec, s[28:29]
	v_readfirstlane_b32 s28, v2
	v_cmp_gt_i32_e32 vcc, 16, v5
	v_lshl_add_u32 v5, v5, 2, v127
	v_subrev_f32_e32 v2, s28, v2
	v_mul_f32_e32 v2, 0x3fb8aa3b, v2
	v_exp_f32_e32 v2, v2
	s_and_b64 s[28:29], s[4:5], vcc
	v_add_u32_e32 v164, 0xc0, v5
	v_xor_b32_e32 v184, v0, v1
	v_and_b32_e32 v184, 64, v184
	v_cmp_eq_u32_e32 vcc, 0, v184
	s_and_b64 s[72:73], vcc, s[28:29]
	s_andn2_b64 s[74:75], s[28:29], vcc
	v_mbcnt_lo_u32_b32 v184, s72, 0
	v_mbcnt_hi_u32_b32 v184, s73, v184
	v_mbcnt_lo_u32_b32 v185, s74, 0
	v_mbcnt_hi_u32_b32 v185, s75, v185
	v_add_u32_e32 v184, s77, v184
	v_sub_u32_e32 v185, s78, v185
	v_cndmask_b32_e32 v184, v185, v184, vcc
	v_lshl_add_u32 v164, v184, 2, v127
	s_bcnt1_i32_b64 s76, s[72:73]
	s_add_u32 s77, s77, s76
	s_bcnt1_i32_b64 s76, s[74:75]
	s_sub_u32 s78, s78, s76
	v_mov_b32_e32 v165, 0
	v_cndmask_b32_e64 v3, 0, v2, s[28:29]
	v_mov_b32_e32 v4, v3
	s_nop 1
	v_permlane32_swap_b32_e32 v3, v4
	v_add_f32_e32 v3, v3, v4
	v_mov_b32_e32 v4, v3
	s_nop 1
	v_permlane16_swap_b32_e32 v3, v4
	v_add_f32_e32 v3, v3, v4
	s_nop 1
	v_add_f32_dpp v3, v3, v3 row_ror:8 row_mask:0xf bank_mask:0xf bound_ctrl:1
	s_nop 1
	v_add_f32_dpp v3, v3, v3 row_ror:4 row_mask:0xf bank_mask:0xf bound_ctrl:1
	s_nop 1
	v_add_f32_dpp v3, v3, v3 quad_perm:[2,3,0,1] row_mask:0xf bank_mask:0xf bound_ctrl:1
	s_nop 1
	v_mov_b32_dpp v4, v3 quad_perm:[1,0,3,2] row_mask:0xf bank_mask:0xf bound_ctrl:1
	s_and_saveexec_b64 s[42:43], s[28:29]
	s_cbranch_execz .LBB0_1012
	v_lshlrev_b32_e32 v0, 7, v0
	v_and_b32_e32 v1, 0x7f, v1
	v_and_or_b32 v0, v0, s49, v1
	v_lshlrev_b32_e32 v1, 2, v0
	global_load_dword v165, v1, s[36:37]
	global_load_dword v161, v1, s[38:39]
	v_add_f32_e32 v1, v3, v4
	v_div_scale_f32 v3, s[44:45], v1, v1, v2
	v_rcp_f32_e32 v4, v3
	s_nop 0
	v_fma_f32 v5, -v3, v4, 1.0
	v_fmac_f32_e32 v4, v5, v4
	v_div_scale_f32 v5, vcc, v2, v1, v2
	v_mul_f32_e32 v6, v5, v4
	v_fma_f32 v7, -v3, v6, v5
	v_fmac_f32_e32 v6, v7, v4
	v_fma_f32 v3, -v3, v6, v5
	v_div_fmas_f32 v3, v3, v4, v6
	v_div_fixup_f32 v1, v3, v1, v2
	ds_write2st64_b32 v164, v0, v1 offset0:12 offset1:14
